# E24 + s_nop 0 between consecutive ds_read_b128 in the K-loop load segments (pace the loader's reads into the partner's MFMA gaps)
# baseline (speedup 1.0000x reference)
;     __device__ __forceinline__ int nt(const Unit& u) const { return (u.pn >> 1) < 2 ? 22 : 20; }
; #define PG8_STAGE(bufoff, gbase, voff) do { _Pragma("unroll") for (int _i = 0; _i < 2; ++_i) \
;         __builtin_amdgcn_global_load_lds((const unsigned*)((const char*)(gbase) + (voff)[_i]), (LAS unsigned*)(lds + (bufoff) + ldsw + _i * 8192), 16, 0, 0); } while (0)
; #define PG8_LDA(dst, b, h) do { _Pragma("unroll") for (int m = 0; m < 4; ++m) _Pragma("unroll") for (int k = 0; k < 2; ++k) dst[m][k] = *(const LAS bf16x8*)(pA + PG8_SA(b, h) + m * 2048 + k * 1024); } while (0)
; #define PG8_LDB(dst, b, h) do { _Pragma("unroll") for (int n = 0; n < 2; ++n) _Pragma("unroll") for (int k = 0; k < 2; ++k) dst[n][k] = *(const LAS bf16x8*)(pB + (PG8_SB(b, h) - 4 * HTB) + n * 2048 + k * 1024); } while (0)
; #define PG8_MMA(ai, bj, At, Bt) do { __builtin_amdgcn_s_setprio(1); _Pragma("unroll") for (int m = 0; m < 4; ++m) _Pragma("unroll") for (int n = 0; n < 2; ++n) _Pragma("unroll") for (int k = 0; k < 2; ++k) \
;         acc[ai][bj][m][n] = __builtin_amdgcn_mfma_f32_16x16x32_bf16(Bt[n][k], At[m][k], acc[ai][bj][m][n], 0, 0, 0); __builtin_amdgcn_s_setprio(0); } while (0)
; #define PG8_WAIT_V(n) asm volatile("s_waitcnt vmcnt(" #n ")" ::: "memory")
; #define PG8_BAR __builtin_amdgcn_s_barrier()
; template <class Desc, class Epi, bool ALIGN_EPI>
; __device__ __forceinline__ void gemm_phase(LAS unsigned char* lds, const Desc& D, const Epi& E, int G, int c) {
;     ...
;         for (int t = 0; t < nt; t += 2) {
;             const bool last = (t == nt - 2);
;             if (last && has_next) PG8_AWAIT(nxt);
;             const char* a1 = cA + (size_t)(t + 1) * kstep;
;             const char* a2 = last ? nA : cA + (size_t)(t + 2) * kstep; const char* b2 = last ? nB : cB + (size_t)(t + 2) * kstep;
;             const char* a3 = a2 + kstep; const char* b3 = b2 + kstep;
;             PG8_LDB(B0, 0, 0); PG8_LDB(B1, 0, 1); PG8_SCHED; PG8_LDA(At, 0, 0); PG8_STAGE(PG8_SA(1, 1), a1 + hstepA, voffA);
;             PG8_WAIT_V(8); PG8_WAIT_L(0); PG8_BAR; PG8_MMA(0, 0, At, B0); PG8_MMA(0, 1, At, B1); PG8_BAR; PG8_SCHED;
;             PG8_LDA(At, 0, 1); PG8_STAGE(PG8_SB(0, 0), b2, voffB); PG8_STAGE(PG8_SB(0, 1), b2 + hstepB, voffB); PG8_STAGE(PG8_SA(0, 0), a2, voffA);
;             PG8_WAIT_V(8); PG8_WAIT_L(0); PG8_BAR; PG8_MMA(1, 0, At, B0); PG8_MMA(1, 1, At, B1); PG8_BAR; PG8_SCHED;
.LBB0_172:
	s_or_b32 s14, s17, 1
	s_lshl_b64 s[26:27], s[14:15], 7
	s_add_i32 s14, s17, 2
	s_lshl_b64 s[40:41], s[14:15], 7
	s_add_u32 s17, s12, s40
	ds_read_b128 v[134:137], v169
	s_nop 0
	ds_read_b128 v[138:141], v169 offset:1024
	s_nop 0
	ds_read_b128 v[142:145], v169 offset:2048
	s_nop 0
	ds_read_b128 v[146:149], v169 offset:3072
	s_nop 0
	ds_read_b128 v[160:163], v169 offset:16384
	s_nop 0
	ds_read_b128 v[164:167], v169 offset:17408
	s_nop 0
	ds_read_b128 v[174:177], v169 offset:18432
	s_nop 0
	ds_read_b128 v[178:181], v169 offset:19456
	s_addc_u32 s21, s13, s41
	s_and_b64 s[38:39], s[30:31], exec
	s_cselect_b32 s39, s61, s21
	s_cselect_b32 s38, s60, s17
	s_add_u32 s17, s18, s40
	s_addc_u32 s21, s19, s41
	s_and_b64 s[30:31], s[30:31], exec
	s_cselect_b32 s31, s63, s21
	s_cselect_b32 s30, s62, s17
	s_add_u32 s17, s12, s26
	s_addc_u32 s21, s13, s27
	s_add_u32 s26, s17, 0x100000
	s_addc_u32 s27, s21, 0
	s_mov_b32 m0, s50
	v_lshl_add_u64 v[150:151], s[26:27], 0, v[152:153]
	ds_read_b128 v[182:185], v168
	s_nop 0
	ds_read_b128 v[186:189], v168 offset:1024
	s_nop 0
	ds_read_b128 v[190:193], v168 offset:2048
	s_nop 0
	ds_read_b128 v[194:197], v168 offset:3072
	s_nop 0
	ds_read_b128 v[198:201], v168 offset:4096
	s_nop 0
	ds_read_b128 v[202:205], v168 offset:5120
	s_nop 0
	ds_read_b128 v[206:209], v168 offset:6144
	s_nop 0
	ds_read_b128 v[210:213], v168 offset:7168
	global_load_lds_dwordx4 v[150:151], off
	v_lshl_add_u64 v[150:151], s[26:27], 0, v[156:157]
	s_mov_b32 m0, s51
	s_nop 0
	global_load_lds_dwordx4 v[150:151], off
	s_waitcnt vmcnt(8)
	s_waitcnt lgkmcnt(0)
	s_barrier
	v_mfma_f32_16x16x32_bf16 v[128:131], v[134:137], v[182:185], v[128:131]
	v_mfma_f32_16x16x32_bf16 v[128:131], v[138:141], v[186:189], v[128:131]
	v_mfma_f32_16x16x32_bf16 v[124:127], v[142:145], v[182:185], v[124:127]
	v_mfma_f32_16x16x32_bf16 v[124:127], v[146:149], v[186:189], v[124:127]
	v_mfma_f32_16x16x32_bf16 v[96:99], v[160:163], v[182:185], v[96:99]
	v_mfma_f32_16x16x32_bf16 v[96:99], v[164:167], v[186:189], v[96:99]
	v_mfma_f32_16x16x32_bf16 v[92:95], v[174:177], v[182:185], v[92:95]
	v_mfma_f32_16x16x32_bf16 v[92:95], v[178:181], v[186:189], v[92:95]
	v_mfma_f32_16x16x32_bf16 v[84:87], v[174:177], v[190:193], v[84:87]
	v_mfma_f32_16x16x32_bf16 v[84:87], v[178:181], v[194:197], v[84:87]
	v_mfma_f32_16x16x32_bf16 v[88:91], v[160:163], v[190:193], v[88:91]
	v_mfma_f32_16x16x32_bf16 v[88:91], v[164:167], v[194:197], v[88:91]
	v_mfma_f32_16x16x32_bf16 v[116:119], v[142:145], v[190:193], v[116:119]
	v_mfma_f32_16x16x32_bf16 v[116:119], v[146:149], v[194:197], v[116:119]
	v_mfma_f32_16x16x32_bf16 v[120:123], v[134:137], v[190:193], v[120:123]
	v_mfma_f32_16x16x32_bf16 v[120:123], v[138:141], v[194:197], v[120:123]
	v_mfma_f32_16x16x32_bf16 v[112:115], v[134:137], v[198:201], v[112:115]
	v_mfma_f32_16x16x32_bf16 v[112:115], v[138:141], v[202:205], v[112:115]
	v_mfma_f32_16x16x32_bf16 v[108:111], v[142:145], v[198:201], v[108:111]
	v_mfma_f32_16x16x32_bf16 v[108:111], v[146:149], v[202:205], v[108:111]
	v_mfma_f32_16x16x32_bf16 v[80:83], v[160:163], v[198:201], v[80:83]
	v_mfma_f32_16x16x32_bf16 v[80:83], v[164:167], v[202:205], v[80:83]
	v_mfma_f32_16x16x32_bf16 v[76:79], v[174:177], v[198:201], v[76:79]
	v_mfma_f32_16x16x32_bf16 v[76:79], v[178:181], v[202:205], v[76:79]
	v_mfma_f32_16x16x32_bf16 v[68:71], v[174:177], v[206:209], v[68:71]
	v_mfma_f32_16x16x32_bf16 v[68:71], v[178:181], v[210:213], v[68:71]
	v_mfma_f32_16x16x32_bf16 v[72:75], v[160:163], v[206:209], v[72:75]
	v_mfma_f32_16x16x32_bf16 v[72:75], v[164:167], v[210:213], v[72:75]
	v_mfma_f32_16x16x32_bf16 v[100:103], v[142:145], v[206:209], v[100:103]
	v_mfma_f32_16x16x32_bf16 v[100:103], v[146:149], v[210:213], v[100:103]
	v_mfma_f32_16x16x32_bf16 v[104:107], v[134:137], v[206:209], v[104:107]
	v_mfma_f32_16x16x32_bf16 v[104:107], v[138:141], v[210:213], v[104:107]
	s_barrier
	s_mov_b32 m0, s84
	v_lshl_add_u64 v[150:151], s[30:31], 0, v[154:155]
	s_add_u32 s26, s30, 0x100000
	ds_read_b128 v[182:185], v168 offset:16384
	s_nop 0
	ds_read_b128 v[186:189], v168 offset:17408
	s_nop 0
	ds_read_b128 v[190:193], v168 offset:18432
	s_nop 0
	ds_read_b128 v[194:197], v168 offset:19456
	s_nop 0
	ds_read_b128 v[198:201], v168 offset:20480
	s_nop 0
	ds_read_b128 v[202:205], v168 offset:21504
	s_nop 0
	ds_read_b128 v[206:209], v168 offset:22528
	s_nop 0
	ds_read_b128 v[210:213], v168 offset:23552
	global_load_lds_dwordx4 v[150:151], off
	v_lshl_add_u64 v[214:215], s[30:31], 0, v[158:159]
	s_mov_b32 m0, s85
	s_addc_u32 s27, s31, 0
	global_load_lds_dwordx4 v[214:215], off
	v_lshl_add_u64 v[216:217], s[26:27], 0, v[154:155]
	s_mov_b32 m0, s86
	v_lshl_add_u64 v[218:219], s[38:39], 0, v[156:157]
	global_load_lds_dwordx4 v[216:217], off
	v_lshl_add_u64 v[216:217], s[26:27], 0, v[158:159]
	s_mov_b32 m0, s87
	s_nop 0
	global_load_lds_dwordx4 v[216:217], off
	v_lshl_add_u64 v[216:217], s[38:39], 0, v[152:153]
	s_mov_b32 m0, s83
	s_nop 0
	global_load_lds_dwordx4 v[216:217], off
	s_mov_b32 m0, s88
	s_nop 0
	global_load_lds_dwordx4 v[218:219], off
	s_waitcnt vmcnt(8)
	s_waitcnt lgkmcnt(0)
	s_barrier
; #define PG8_STAGE(bufoff, gbase, voff) do { _Pragma("unroll") for (int _i = 0; _i < 2; ++_i) \
;         __builtin_amdgcn_global_load_lds((const unsigned*)((const char*)(gbase) + (voff)[_i]), (LAS unsigned*)(lds + (bufoff) + ldsw + _i * 8192), 16, 0, 0); } while (0)
; #define PG8_LDA(dst, b, h) do { _Pragma("unroll") for (int m = 0; m < 4; ++m) _Pragma("unroll") for (int k = 0; k < 2; ++k) dst[m][k] = *(const LAS bf16x8*)(pA + PG8_SA(b, h) + m * 2048 + k * 1024); } while (0)
; #define PG8_LDB(dst, b, h) do { _Pragma("unroll") for (int n = 0; n < 2; ++n) _Pragma("unroll") for (int k = 0; k < 2; ++k) dst[n][k] = *(const LAS bf16x8*)(pB + (PG8_SB(b, h) - 4 * HTB) + n * 2048 + k * 1024); } while (0)
; #define PG8_MMA(ai, bj, At, Bt) do { __builtin_amdgcn_s_setprio(1); _Pragma("unroll") for (int m = 0; m < 4; ++m) _Pragma("unroll") for (int n = 0; n < 2; ++n) _Pragma("unroll") for (int k = 0; k < 2; ++k) \
;         acc[ai][bj][m][n] = __builtin_amdgcn_mfma_f32_16x16x32_bf16(Bt[n][k], At[m][k], acc[ai][bj][m][n], 0, 0, 0); __builtin_amdgcn_s_setprio(0); } while (0)
; #define PG8_WAIT_V(n) asm volatile("s_waitcnt vmcnt(" #n ")" ::: "memory")
; #define PG8_WAIT_L(n) asm volatile("s_waitcnt lgkmcnt(" #n ")" ::: "memory")
; #define PG8_BAR __builtin_amdgcn_s_barrier()
; #define PG8_SCHED __builtin_amdgcn_sched_barrier(0)
; template <class Desc, class Epi, bool ALIGN_EPI>
; __device__ __forceinline__ void gemm_phase(LAS unsigned char* lds, const Desc& D, const Epi& E, int G, int c) {
;     ...
;             PG8_WAIT_V(8); PG8_WAIT_L(0); PG8_BAR; PG8_MMA(1, 0, At, B0); PG8_MMA(1, 1, At, B1); PG8_BAR; PG8_SCHED;
;             PG8_LDB(B0, 1, 0); PG8_LDB(B1, 1, 1); PG8_SCHED; PG8_LDA(At, 1, 0); PG8_STAGE(PG8_SA(0, 1), a2 + hstepA, voffA);
;             PG8_WAIT_V(8); PG8_WAIT_L(0); PG8_BAR; PG8_MMA(0, 0, At, B0); PG8_MMA(0, 1, At, B1); PG8_BAR; PG8_SCHED;
	v_mfma_f32_16x16x32_bf16 v[64:67], v[134:137], v[182:185], v[64:67]
	v_mfma_f32_16x16x32_bf16 v[64:67], v[138:141], v[186:189], v[64:67]
	v_mfma_f32_16x16x32_bf16 v[52:55], v[142:145], v[182:185], v[52:55]
	v_mfma_f32_16x16x32_bf16 v[52:55], v[146:149], v[186:189], v[52:55]
	v_mfma_f32_16x16x32_bf16 v[60:63], v[160:163], v[182:185], v[60:63]
	v_mfma_f32_16x16x32_bf16 v[60:63], v[164:167], v[186:189], v[60:63]
	v_mfma_f32_16x16x32_bf16 v[56:59], v[174:177], v[182:185], v[56:59]
	v_mfma_f32_16x16x32_bf16 v[56:59], v[178:181], v[186:189], v[56:59]
	v_mfma_f32_16x16x32_bf16 v[44:47], v[174:177], v[190:193], v[44:47]
	v_mfma_f32_16x16x32_bf16 v[44:47], v[178:181], v[194:197], v[44:47]
	v_mfma_f32_16x16x32_bf16 v[48:51], v[160:163], v[190:193], v[48:51]
	v_mfma_f32_16x16x32_bf16 v[48:51], v[164:167], v[194:197], v[48:51]
	v_mfma_f32_16x16x32_bf16 v[20:23], v[142:145], v[190:193], v[20:23]
	v_mfma_f32_16x16x32_bf16 v[20:23], v[146:149], v[194:197], v[20:23]
	v_mfma_f32_16x16x32_bf16 v[32:35], v[134:137], v[190:193], v[32:35]
	v_mfma_f32_16x16x32_bf16 v[32:35], v[138:141], v[194:197], v[32:35]
	v_mfma_f32_16x16x32_bf16 v[16:19], v[134:137], v[198:201], v[16:19]
	v_mfma_f32_16x16x32_bf16 v[16:19], v[138:141], v[202:205], v[16:19]
	v_mfma_f32_16x16x32_bf16 v[12:15], v[142:145], v[198:201], v[12:15]
	v_mfma_f32_16x16x32_bf16 v[12:15], v[146:149], v[202:205], v[12:15]
	v_mfma_f32_16x16x32_bf16 v[40:43], v[160:163], v[198:201], v[40:43]
	v_mfma_f32_16x16x32_bf16 v[40:43], v[164:167], v[202:205], v[40:43]
	v_mfma_f32_16x16x32_bf16 v[36:39], v[174:177], v[198:201], v[36:39]
	v_mfma_f32_16x16x32_bf16 v[36:39], v[178:181], v[202:205], v[36:39]
	v_mfma_f32_16x16x32_bf16 v[24:27], v[174:177], v[206:209], v[24:27]
	v_mfma_f32_16x16x32_bf16 v[24:27], v[178:181], v[210:213], v[24:27]
	v_mfma_f32_16x16x32_bf16 v[28:31], v[160:163], v[206:209], v[28:31]
	v_mfma_f32_16x16x32_bf16 v[28:31], v[164:167], v[210:213], v[28:31]
	v_mfma_f32_16x16x32_bf16 v[4:7], v[142:145], v[206:209], v[4:7]
	v_mfma_f32_16x16x32_bf16 v[4:7], v[146:149], v[210:213], v[4:7]
	v_mfma_f32_16x16x32_bf16 v[8:11], v[134:137], v[206:209], v[8:11]
	v_mfma_f32_16x16x32_bf16 v[8:11], v[138:141], v[210:213], v[8:11]
	s_barrier
	ds_read_b128 v[134:137], v169 offset:32768
	s_nop 0
	ds_read_b128 v[138:141], v169 offset:33792
	s_nop 0
	ds_read_b128 v[142:145], v169 offset:34816
	s_nop 0
	ds_read_b128 v[146:149], v169 offset:35840
	s_nop 0
	ds_read_b128 v[160:163], v169 offset:49152
	s_nop 0
	ds_read_b128 v[164:167], v169 offset:50176
	s_nop 0
	ds_read_b128 v[174:177], v169 offset:51200
	s_nop 0
	ds_read_b128 v[178:181], v169 offset:52224
	s_add_u32 s26, s38, 0x100000
	s_addc_u32 s27, s39, 0
	s_mov_b32 m0, s89
	v_lshl_add_u64 v[220:221], s[26:27], 0, v[152:153]
	ds_read_b128 v[182:185], v168 offset:32768
	s_nop 0
	ds_read_b128 v[186:189], v168 offset:33792
	s_nop 0
	ds_read_b128 v[190:193], v168 offset:34816
	s_nop 0
	ds_read_b128 v[194:197], v168 offset:35840
	s_nop 0
	ds_read_b128 v[198:201], v168 offset:36864
	s_nop 0
	ds_read_b128 v[202:205], v168 offset:37888
	s_nop 0
	ds_read_b128 v[206:209], v168 offset:38912
	s_nop 0
	ds_read_b128 v[210:213], v168 offset:39936
	global_load_lds_dwordx4 v[220:221], off
	v_lshl_add_u64 v[220:221], s[26:27], 0, v[156:157]
	s_mov_b32 m0, s90
	s_nop 0
	global_load_lds_dwordx4 v[220:221], off
	s_waitcnt vmcnt(8)
	s_waitcnt lgkmcnt(0)
	s_barrier
	v_mfma_f32_16x16x32_bf16 v[128:131], v[134:137], v[182:185], v[128:131]
	v_mfma_f32_16x16x32_bf16 v[128:131], v[138:141], v[186:189], v[128:131]
	v_mfma_f32_16x16x32_bf16 v[124:127], v[142:145], v[182:185], v[124:127]
	v_mfma_f32_16x16x32_bf16 v[124:127], v[146:149], v[186:189], v[124:127]
	v_mfma_f32_16x16x32_bf16 v[96:99], v[160:163], v[182:185], v[96:99]
	v_mfma_f32_16x16x32_bf16 v[96:99], v[164:167], v[186:189], v[96:99]
	v_mfma_f32_16x16x32_bf16 v[92:95], v[174:177], v[182:185], v[92:95]
	v_mfma_f32_16x16x32_bf16 v[92:95], v[178:181], v[186:189], v[92:95]
	v_mfma_f32_16x16x32_bf16 v[84:87], v[174:177], v[190:193], v[84:87]
	v_mfma_f32_16x16x32_bf16 v[84:87], v[178:181], v[194:197], v[84:87]
	v_mfma_f32_16x16x32_bf16 v[88:91], v[160:163], v[190:193], v[88:91]
	v_mfma_f32_16x16x32_bf16 v[88:91], v[164:167], v[194:197], v[88:91]
	v_mfma_f32_16x16x32_bf16 v[116:119], v[142:145], v[190:193], v[116:119]
	v_mfma_f32_16x16x32_bf16 v[116:119], v[146:149], v[194:197], v[116:119]
	v_mfma_f32_16x16x32_bf16 v[120:123], v[134:137], v[190:193], v[120:123]
	v_mfma_f32_16x16x32_bf16 v[120:123], v[138:141], v[194:197], v[120:123]
	v_mfma_f32_16x16x32_bf16 v[112:115], v[134:137], v[198:201], v[112:115]
	v_mfma_f32_16x16x32_bf16 v[112:115], v[138:141], v[202:205], v[112:115]
	v_mfma_f32_16x16x32_bf16 v[108:111], v[142:145], v[198:201], v[108:111]
	v_mfma_f32_16x16x32_bf16 v[108:111], v[146:149], v[202:205], v[108:111]
	v_mfma_f32_16x16x32_bf16 v[80:83], v[160:163], v[198:201], v[80:83]
	v_mfma_f32_16x16x32_bf16 v[80:83], v[164:167], v[202:205], v[80:83]
	v_mfma_f32_16x16x32_bf16 v[76:79], v[174:177], v[198:201], v[76:79]
	v_mfma_f32_16x16x32_bf16 v[76:79], v[178:181], v[202:205], v[76:79]
	v_mfma_f32_16x16x32_bf16 v[68:71], v[174:177], v[206:209], v[68:71]
	v_mfma_f32_16x16x32_bf16 v[68:71], v[178:181], v[210:213], v[68:71]
	v_mfma_f32_16x16x32_bf16 v[72:75], v[160:163], v[206:209], v[72:75]
	v_mfma_f32_16x16x32_bf16 v[72:75], v[164:167], v[210:213], v[72:75]
	v_mfma_f32_16x16x32_bf16 v[100:103], v[142:145], v[206:209], v[100:103]
	v_mfma_f32_16x16x32_bf16 v[100:103], v[146:149], v[210:213], v[100:103]
	v_mfma_f32_16x16x32_bf16 v[104:107], v[134:137], v[206:209], v[104:107]
	v_mfma_f32_16x16x32_bf16 v[104:107], v[138:141], v[210:213], v[104:107]
	s_barrier
; #define PG8_STAGE(bufoff, gbase, voff) do { _Pragma("unroll") for (int _i = 0; _i < 2; ++_i) \
;         __builtin_amdgcn_global_load_lds((const unsigned*)((const char*)(gbase) + (voff)[_i]), (LAS unsigned*)(lds + (bufoff) + ldsw + _i * 8192), 16, 0, 0); } while (0)
; #define PG8_LDA(dst, b, h) do { _Pragma("unroll") for (int m = 0; m < 4; ++m) _Pragma("unroll") for (int k = 0; k < 2; ++k) dst[m][k] = *(const LAS bf16x8*)(pA + PG8_SA(b, h) + m * 2048 + k * 1024); } while (0)
; #define PG8_MMA(ai, bj, At, Bt) do { __builtin_amdgcn_s_setprio(1); _Pragma("unroll") for (int m = 0; m < 4; ++m) _Pragma("unroll") for (int n = 0; n < 2; ++n) _Pragma("unroll") for (int k = 0; k < 2; ++k) \
;         acc[ai][bj][m][n] = __builtin_amdgcn_mfma_f32_16x16x32_bf16(Bt[n][k], At[m][k], acc[ai][bj][m][n], 0, 0, 0); __builtin_amdgcn_s_setprio(0); } while (0)
; #define PG8_WAIT_V(n) asm volatile("s_waitcnt vmcnt(" #n ")" ::: "memory")
; #define PG8_WAIT_L(n) asm volatile("s_waitcnt lgkmcnt(" #n ")" ::: "memory")
; #define PG8_BAR __builtin_amdgcn_s_barrier()
; #define PG8_SCHED __builtin_amdgcn_sched_barrier(0)
; template <class Desc, class Epi, bool ALIGN_EPI>
; __device__ __forceinline__ void gemm_phase(LAS unsigned char* lds, const Desc& D, const Epi& E, int G, int c) {
;     ...
;             PG8_LDA(At, 1, 1); PG8_STAGE(PG8_SB(1, 0), b3, voffB); PG8_STAGE(PG8_SB(1, 1), b3 + hstepB, voffB); PG8_STAGE(PG8_SA(1, 0), a3, voffA);
;             PG8_WAIT_V(8); PG8_WAIT_L(0); PG8_BAR; PG8_MMA(1, 0, At, B0); PG8_MMA(1, 1, At, B1); PG8_BAR; PG8_SCHED;
;         }
	s_mov_b32 m0, s92
	v_lshl_add_u64 v[150:151], v[150:151], 0, s[76:77]
	s_add_u32 s26, s30, 0x100080
	ds_read_b128 v[182:185], v168 offset:49152
	s_nop 0
	ds_read_b128 v[186:189], v168 offset:50176
	s_nop 0
	ds_read_b128 v[190:193], v168 offset:51200
	s_nop 0
	ds_read_b128 v[194:197], v168 offset:52224
	s_nop 0
	ds_read_b128 v[198:201], v168 offset:53248
	s_nop 0
	ds_read_b128 v[202:205], v168 offset:54272
	s_nop 0
	ds_read_b128 v[206:209], v168 offset:55296
	s_nop 0
	ds_read_b128 v[210:213], v168 offset:56320
	global_load_lds_dwordx4 v[150:151], off
	v_lshl_add_u64 v[150:151], v[214:215], 0, s[76:77]
	s_mov_b32 m0, s93
	s_addc_u32 s27, s31, 0
	global_load_lds_dwordx4 v[150:151], off
	v_lshl_add_u64 v[150:151], s[26:27], 0, v[154:155]
	s_mov_b32 m0, s97
	s_nop 0
	global_load_lds_dwordx4 v[150:151], off
	v_lshl_add_u64 v[150:151], s[26:27], 0, v[158:159]
	s_mov_b32 m0, s82
	s_nop 0
	global_load_lds_dwordx4 v[150:151], off
	v_lshl_add_u64 v[150:151], v[216:217], 0, s[76:77]
	s_mov_b32 m0, s94
	s_nop 0
	global_load_lds_dwordx4 v[150:151], off
	v_lshl_add_u64 v[150:151], v[218:219], 0, s[76:77]
	s_mov_b32 m0, s95
	s_nop 0
	global_load_lds_dwordx4 v[150:151], off
	s_waitcnt vmcnt(8)
	s_waitcnt lgkmcnt(0)
	s_barrier
	v_mfma_f32_16x16x32_bf16 v[64:67], v[134:137], v[182:185], v[64:67]
	v_mfma_f32_16x16x32_bf16 v[64:67], v[138:141], v[186:189], v[64:67]
	v_mfma_f32_16x16x32_bf16 v[52:55], v[142:145], v[182:185], v[52:55]
	v_mfma_f32_16x16x32_bf16 v[52:55], v[146:149], v[186:189], v[52:55]
	v_mfma_f32_16x16x32_bf16 v[60:63], v[160:163], v[182:185], v[60:63]
	v_mfma_f32_16x16x32_bf16 v[60:63], v[164:167], v[186:189], v[60:63]
	v_mfma_f32_16x16x32_bf16 v[56:59], v[174:177], v[182:185], v[56:59]
	v_mfma_f32_16x16x32_bf16 v[56:59], v[178:181], v[186:189], v[56:59]
	v_mfma_f32_16x16x32_bf16 v[44:47], v[174:177], v[190:193], v[44:47]
	v_mfma_f32_16x16x32_bf16 v[44:47], v[178:181], v[194:197], v[44:47]
	v_mfma_f32_16x16x32_bf16 v[48:51], v[160:163], v[190:193], v[48:51]
	v_mfma_f32_16x16x32_bf16 v[48:51], v[164:167], v[194:197], v[48:51]
	v_mfma_f32_16x16x32_bf16 v[20:23], v[142:145], v[190:193], v[20:23]
	v_mfma_f32_16x16x32_bf16 v[20:23], v[146:149], v[194:197], v[20:23]
	v_mfma_f32_16x16x32_bf16 v[32:35], v[134:137], v[190:193], v[32:35]
	v_mfma_f32_16x16x32_bf16 v[32:35], v[138:141], v[194:197], v[32:35]
	v_mfma_f32_16x16x32_bf16 v[16:19], v[134:137], v[198:201], v[16:19]
	v_mfma_f32_16x16x32_bf16 v[16:19], v[138:141], v[202:205], v[16:19]
	v_mfma_f32_16x16x32_bf16 v[12:15], v[142:145], v[198:201], v[12:15]
	v_mfma_f32_16x16x32_bf16 v[12:15], v[146:149], v[202:205], v[12:15]
	v_mfma_f32_16x16x32_bf16 v[40:43], v[160:163], v[198:201], v[40:43]
	v_mfma_f32_16x16x32_bf16 v[40:43], v[164:167], v[202:205], v[40:43]
	v_mfma_f32_16x16x32_bf16 v[36:39], v[174:177], v[198:201], v[36:39]
	v_mfma_f32_16x16x32_bf16 v[36:39], v[178:181], v[202:205], v[36:39]
	v_mfma_f32_16x16x32_bf16 v[24:27], v[174:177], v[206:209], v[24:27]
	v_mfma_f32_16x16x32_bf16 v[24:27], v[178:181], v[210:213], v[24:27]
	v_mfma_f32_16x16x32_bf16 v[28:31], v[160:163], v[206:209], v[28:31]
	v_mfma_f32_16x16x32_bf16 v[28:31], v[164:167], v[210:213], v[28:31]
	v_mfma_f32_16x16x32_bf16 v[4:7], v[142:145], v[206:209], v[4:7]
	v_mfma_f32_16x16x32_bf16 v[4:7], v[146:149], v[210:213], v[4:7]
	v_mfma_f32_16x16x32_bf16 v[8:11], v[134:137], v[206:209], v[8:11]
	v_mfma_f32_16x16x32_bf16 v[8:11], v[138:141], v[210:213], v[8:11]
	s_barrier
	s_cmp_ge_u32 s14, s3
	s_mov_b32 s17, s14
	s_cbranch_scc1 .LBB0_183

;     __device__ __forceinline__ int nt(const Unit& u) const { return (u.pn >> 1) < 2 ? 22 : 20; }
; #define PG8_STAGE(bufoff, gbase, voff) do { _Pragma("unroll") for (int _i = 0; _i < 2; ++_i) \
;         __builtin_amdgcn_global_load_lds((const unsigned*)((const char*)(gbase) + (voff)[_i]), (LAS unsigned*)(lds + (bufoff) + ldsw + _i * 8192), 16, 0, 0); } while (0)
; #define PG8_LDA(dst, b, h) do { _Pragma("unroll") for (int m = 0; m < 4; ++m) _Pragma("unroll") for (int k = 0; k < 2; ++k) dst[m][k] = *(const LAS bf16x8*)(pA + PG8_SA(b, h) + m * 2048 + k * 1024); } while (0)
; #define PG8_LDB(dst, b, h) do { _Pragma("unroll") for (int n = 0; n < 2; ++n) _Pragma("unroll") for (int k = 0; k < 2; ++k) dst[n][k] = *(const LAS bf16x8*)(pB + (PG8_SB(b, h) - 4 * HTB) + n * 2048 + k * 1024); } while (0)
; #define PG8_MMA(ai, bj, At, Bt) do { __builtin_amdgcn_s_setprio(1); _Pragma("unroll") for (int m = 0; m < 4; ++m) _Pragma("unroll") for (int n = 0; n < 2; ++n) _Pragma("unroll") for (int k = 0; k < 2; ++k) \
;         acc[ai][bj][m][n] = __builtin_amdgcn_mfma_f32_16x16x32_bf16(Bt[n][k], At[m][k], acc[ai][bj][m][n], 0, 0, 0); __builtin_amdgcn_s_setprio(0); } while (0)
; #define PG8_WAIT_V(n) asm volatile("s_waitcnt vmcnt(" #n ")" ::: "memory")
; #define PG8_BAR __builtin_amdgcn_s_barrier()
; template <class Desc, class Epi, bool ALIGN_EPI>
; __device__ __forceinline__ void gemm_phase(LAS unsigned char* lds, const Desc& D, const Epi& E, int G, int c) {
;     ...
;         for (int t = 0; t < nt; t += 2) {
;             const bool last = (t == nt - 2);
;             if (last && has_next) PG8_AWAIT(nxt);
;             const char* a1 = cA + (size_t)(t + 1) * kstep;
;             const char* a2 = last ? nA : cA + (size_t)(t + 2) * kstep; const char* b2 = last ? nB : cB + (size_t)(t + 2) * kstep;
;             const char* a3 = a2 + kstep; const char* b3 = b2 + kstep;
;             PG8_LDB(B0, 0, 0); PG8_LDB(B1, 0, 1); PG8_SCHED; PG8_LDA(At, 0, 0); PG8_STAGE(PG8_SA(1, 1), a1 + hstepA, voffA);
;             PG8_WAIT_V(8); PG8_WAIT_L(0); PG8_BAR; PG8_MMA(0, 0, At, B0); PG8_MMA(0, 1, At, B1); PG8_BAR; PG8_SCHED;
;             PG8_LDA(At, 0, 1); PG8_STAGE(PG8_SB(0, 0), b2, voffB); PG8_STAGE(PG8_SB(0, 1), b2 + hstepB, voffB); PG8_STAGE(PG8_SA(0, 0), a2, voffA);
;             PG8_WAIT_V(8); PG8_WAIT_L(0); PG8_BAR; PG8_MMA(1, 0, At, B0); PG8_MMA(1, 1, At, B1); PG8_BAR; PG8_SCHED;
.LBB0_603:
	ds_read_b128 v[144:147], v149
	s_nop 0
	ds_read_b128 v[152:155], v149 offset:1024
	s_nop 0
	ds_read_b128 v[156:159], v149 offset:2048
	s_nop 0
	ds_read_b128 v[160:163], v149 offset:3072
	s_nop 0
	ds_read_b128 v[164:167], v149 offset:16384
	s_nop 0
	ds_read_b128 v[168:171], v149 offset:17408
	s_nop 0
	ds_read_b128 v[172:175], v149 offset:18432
	s_nop 0
	ds_read_b128 v[176:179], v149 offset:19456
	s_add_u32 s16, s12, 0xfff80080
	s_addc_u32 s17, s13, -1
	s_cmp_eq_u32 s46, 4
	s_cselect_b32 s19, s9, s17
	s_cselect_b32 s18, s8, s16
	s_cselect_b32 s17, s11, s45
	s_cselect_b32 s16, s10, s7
	v_lshl_add_u64 v[212:213], s[12:13], 0, v[140:141]
	s_add_i32 m0, s20, 0xc000
	ds_read_b128 v[180:183], v148
	s_nop 0
	ds_read_b128 v[184:187], v148 offset:1024
	s_nop 0
	ds_read_b128 v[188:191], v148 offset:2048
	s_nop 0
	ds_read_b128 v[192:195], v148 offset:3072
	s_nop 0
	ds_read_b128 v[196:199], v148 offset:4096
	s_nop 0
	ds_read_b128 v[200:203], v148 offset:5120
	s_nop 0
	ds_read_b128 v[204:207], v148 offset:6144
	s_nop 0
	ds_read_b128 v[208:211], v148 offset:7168
	global_load_lds_dwordx4 v[212:213], off
	v_lshl_add_u64 v[212:213], s[12:13], 0, v[142:143]
	s_add_i32 m0, s20, 0xe000
	s_nop 0
	global_load_lds_dwordx4 v[212:213], off
	s_waitcnt vmcnt(8)
	s_waitcnt lgkmcnt(0)
	s_barrier
	v_mfma_f32_16x16x32_bf16 v[128:131], v[144:147], v[180:183], v[128:131]
	v_mfma_f32_16x16x32_bf16 v[128:131], v[152:155], v[184:187], v[128:131]
	v_mfma_f32_16x16x32_bf16 v[124:127], v[156:159], v[180:183], v[124:127]
	v_mfma_f32_16x16x32_bf16 v[124:127], v[160:163], v[184:187], v[124:127]
	v_mfma_f32_16x16x32_bf16 v[120:123], v[164:167], v[180:183], v[120:123]
	v_mfma_f32_16x16x32_bf16 v[120:123], v[168:171], v[184:187], v[120:123]
	v_mfma_f32_16x16x32_bf16 v[112:115], v[172:175], v[180:183], v[112:115]
	v_mfma_f32_16x16x32_bf16 v[112:115], v[176:179], v[184:187], v[112:115]
	v_mfma_f32_16x16x32_bf16 v[96:99], v[172:175], v[188:191], v[96:99]
	v_mfma_f32_16x16x32_bf16 v[96:99], v[176:179], v[192:195], v[96:99]
	v_mfma_f32_16x16x32_bf16 v[104:107], v[164:167], v[188:191], v[104:107]
	v_mfma_f32_16x16x32_bf16 v[104:107], v[168:171], v[192:195], v[104:107]
	v_mfma_f32_16x16x32_bf16 v[108:111], v[156:159], v[188:191], v[108:111]
	v_mfma_f32_16x16x32_bf16 v[108:111], v[160:163], v[192:195], v[108:111]
	v_mfma_f32_16x16x32_bf16 v[116:119], v[144:147], v[188:191], v[116:119]
	v_mfma_f32_16x16x32_bf16 v[116:119], v[152:155], v[192:195], v[116:119]
	v_mfma_f32_16x16x32_bf16 v[100:103], v[144:147], v[196:199], v[100:103]
	v_mfma_f32_16x16x32_bf16 v[100:103], v[152:155], v[200:203], v[100:103]
	v_mfma_f32_16x16x32_bf16 v[92:95], v[156:159], v[196:199], v[92:95]
	v_mfma_f32_16x16x32_bf16 v[92:95], v[160:163], v[200:203], v[92:95]
	v_mfma_f32_16x16x32_bf16 v[88:91], v[164:167], v[196:199], v[88:91]
	v_mfma_f32_16x16x32_bf16 v[88:91], v[168:171], v[200:203], v[88:91]
	v_mfma_f32_16x16x32_bf16 v[80:83], v[172:175], v[196:199], v[80:83]
	v_mfma_f32_16x16x32_bf16 v[80:83], v[176:179], v[200:203], v[80:83]
	v_mfma_f32_16x16x32_bf16 v[68:71], v[172:175], v[204:207], v[68:71]
	v_mfma_f32_16x16x32_bf16 v[68:71], v[176:179], v[208:211], v[68:71]
	v_mfma_f32_16x16x32_bf16 v[72:75], v[164:167], v[204:207], v[72:75]
	v_mfma_f32_16x16x32_bf16 v[72:75], v[168:171], v[208:211], v[72:75]
	v_mfma_f32_16x16x32_bf16 v[76:79], v[156:159], v[204:207], v[76:79]
	v_mfma_f32_16x16x32_bf16 v[76:79], v[160:163], v[208:211], v[76:79]
	v_mfma_f32_16x16x32_bf16 v[84:87], v[144:147], v[204:207], v[84:87]
	v_mfma_f32_16x16x32_bf16 v[84:87], v[152:155], v[208:211], v[84:87]
	s_barrier
	s_mov_b32 m0, s21
	v_lshl_add_u64 v[212:213], s[16:17], 0, v[136:137]
	s_add_u32 s48, s16, 0x20000
	ds_read_b128 v[180:183], v148 offset:16384
	s_nop 0
	ds_read_b128 v[184:187], v148 offset:17408
	s_nop 0
	ds_read_b128 v[188:191], v148 offset:18432
	s_nop 0
	ds_read_b128 v[192:195], v148 offset:19456
	s_nop 0
	ds_read_b128 v[196:199], v148 offset:20480
	s_nop 0
	ds_read_b128 v[200:203], v148 offset:21504
	s_nop 0
	ds_read_b128 v[204:207], v148 offset:22528
	s_nop 0
	ds_read_b128 v[208:211], v148 offset:23552
	global_load_lds_dwordx4 v[212:213], off
	v_lshl_add_u64 v[214:215], s[16:17], 0, v[132:133]
	s_mov_b32 m0, s23
	s_addc_u32 s49, s17, 0
	global_load_lds_dwordx4 v[214:215], off
	v_lshl_add_u64 v[216:217], s[48:49], 0, v[136:137]
	s_mov_b32 m0, s24
	v_lshl_add_u64 v[218:219], s[18:19], 0, v[134:135]
	global_load_lds_dwordx4 v[216:217], off
	v_lshl_add_u64 v[216:217], s[48:49], 0, v[132:133]
	s_mov_b32 m0, s25
	s_nop 0
	global_load_lds_dwordx4 v[216:217], off
	v_lshl_add_u64 v[216:217], s[18:19], 0, v[138:139]
	s_mov_b32 m0, s20
	s_nop 0
	global_load_lds_dwordx4 v[216:217], off
	s_mov_b32 m0, s26
	s_nop 0
	global_load_lds_dwordx4 v[218:219], off
	s_waitcnt vmcnt(8)
	s_waitcnt lgkmcnt(0)
	s_barrier
; #define PG8_STAGE(bufoff, gbase, voff) do { _Pragma("unroll") for (int _i = 0; _i < 2; ++_i) \
;         __builtin_amdgcn_global_load_lds((const unsigned*)((const char*)(gbase) + (voff)[_i]), (LAS unsigned*)(lds + (bufoff) + ldsw + _i * 8192), 16, 0, 0); } while (0)
; #define PG8_LDA(dst, b, h) do { _Pragma("unroll") for (int m = 0; m < 4; ++m) _Pragma("unroll") for (int k = 0; k < 2; ++k) dst[m][k] = *(const LAS bf16x8*)(pA + PG8_SA(b, h) + m * 2048 + k * 1024); } while (0)
; #define PG8_LDB(dst, b, h) do { _Pragma("unroll") for (int n = 0; n < 2; ++n) _Pragma("unroll") for (int k = 0; k < 2; ++k) dst[n][k] = *(const LAS bf16x8*)(pB + (PG8_SB(b, h) - 4 * HTB) + n * 2048 + k * 1024); } while (0)
; #define PG8_MMA(ai, bj, At, Bt) do { __builtin_amdgcn_s_setprio(1); _Pragma("unroll") for (int m = 0; m < 4; ++m) _Pragma("unroll") for (int n = 0; n < 2; ++n) _Pragma("unroll") for (int k = 0; k < 2; ++k) \
;         acc[ai][bj][m][n] = __builtin_amdgcn_mfma_f32_16x16x32_bf16(Bt[n][k], At[m][k], acc[ai][bj][m][n], 0, 0, 0); __builtin_amdgcn_s_setprio(0); } while (0)
; #define PG8_WAIT_V(n) asm volatile("s_waitcnt vmcnt(" #n ")" ::: "memory")
; #define PG8_WAIT_L(n) asm volatile("s_waitcnt lgkmcnt(" #n ")" ::: "memory")
; #define PG8_BAR __builtin_amdgcn_s_barrier()
; #define PG8_SCHED __builtin_amdgcn_sched_barrier(0)
; template <class Desc, class Epi, bool ALIGN_EPI>
; __device__ __forceinline__ void gemm_phase(LAS unsigned char* lds, const Desc& D, const Epi& E, int G, int c) {
;     ...
;             PG8_WAIT_V(8); PG8_WAIT_L(0); PG8_BAR; PG8_MMA(1, 0, At, B0); PG8_MMA(1, 1, At, B1); PG8_BAR; PG8_SCHED;
;             PG8_LDB(B0, 1, 0); PG8_LDB(B1, 1, 1); PG8_SCHED; PG8_LDA(At, 1, 0); PG8_STAGE(PG8_SA(0, 1), a2 + hstepA, voffA);
;             PG8_WAIT_V(8); PG8_WAIT_L(0); PG8_BAR; PG8_MMA(0, 0, At, B0); PG8_MMA(0, 1, At, B1); PG8_BAR; PG8_SCHED;
	v_mfma_f32_16x16x32_bf16 v[64:67], v[144:147], v[180:183], v[64:67]
	v_mfma_f32_16x16x32_bf16 v[64:67], v[152:155], v[184:187], v[64:67]
	v_mfma_f32_16x16x32_bf16 v[60:63], v[156:159], v[180:183], v[60:63]
	v_mfma_f32_16x16x32_bf16 v[60:63], v[160:163], v[184:187], v[60:63]
	v_mfma_f32_16x16x32_bf16 v[56:59], v[164:167], v[180:183], v[56:59]
	v_mfma_f32_16x16x32_bf16 v[56:59], v[168:171], v[184:187], v[56:59]
	v_mfma_f32_16x16x32_bf16 v[48:51], v[172:175], v[180:183], v[48:51]
	v_mfma_f32_16x16x32_bf16 v[48:51], v[176:179], v[184:187], v[48:51]
	v_mfma_f32_16x16x32_bf16 v[32:35], v[172:175], v[188:191], v[32:35]
	v_mfma_f32_16x16x32_bf16 v[32:35], v[176:179], v[192:195], v[32:35]
	v_mfma_f32_16x16x32_bf16 v[40:43], v[164:167], v[188:191], v[40:43]
	v_mfma_f32_16x16x32_bf16 v[40:43], v[168:171], v[192:195], v[40:43]
	v_mfma_f32_16x16x32_bf16 v[44:47], v[156:159], v[188:191], v[44:47]
	v_mfma_f32_16x16x32_bf16 v[44:47], v[160:163], v[192:195], v[44:47]
	v_mfma_f32_16x16x32_bf16 v[52:55], v[144:147], v[188:191], v[52:55]
	v_mfma_f32_16x16x32_bf16 v[52:55], v[152:155], v[192:195], v[52:55]
	v_mfma_f32_16x16x32_bf16 v[36:39], v[144:147], v[196:199], v[36:39]
	v_mfma_f32_16x16x32_bf16 v[36:39], v[152:155], v[200:203], v[36:39]
	v_mfma_f32_16x16x32_bf16 v[28:31], v[156:159], v[196:199], v[28:31]
	v_mfma_f32_16x16x32_bf16 v[28:31], v[160:163], v[200:203], v[28:31]
	v_mfma_f32_16x16x32_bf16 v[24:27], v[164:167], v[196:199], v[24:27]
	v_mfma_f32_16x16x32_bf16 v[24:27], v[168:171], v[200:203], v[24:27]
	v_mfma_f32_16x16x32_bf16 v[16:19], v[172:175], v[196:199], v[16:19]
	v_mfma_f32_16x16x32_bf16 v[16:19], v[176:179], v[200:203], v[16:19]
	v_mfma_f32_16x16x32_bf16 v[4:7], v[172:175], v[204:207], v[4:7]
	v_mfma_f32_16x16x32_bf16 v[4:7], v[176:179], v[208:211], v[4:7]
	v_mfma_f32_16x16x32_bf16 v[8:11], v[164:167], v[204:207], v[8:11]
	v_mfma_f32_16x16x32_bf16 v[8:11], v[168:171], v[208:211], v[8:11]
	v_mfma_f32_16x16x32_bf16 v[12:15], v[156:159], v[204:207], v[12:15]
	v_mfma_f32_16x16x32_bf16 v[12:15], v[160:163], v[208:211], v[12:15]
	v_mfma_f32_16x16x32_bf16 v[20:23], v[144:147], v[204:207], v[20:23]
	v_mfma_f32_16x16x32_bf16 v[20:23], v[152:155], v[208:211], v[20:23]
	s_barrier
	ds_read_b128 v[144:147], v149 offset:32768
	s_nop 0
	ds_read_b128 v[152:155], v149 offset:33792
	s_nop 0
	ds_read_b128 v[156:159], v149 offset:34816
	s_nop 0
	ds_read_b128 v[160:163], v149 offset:35840
	s_nop 0
	ds_read_b128 v[164:167], v149 offset:49152
	s_nop 0
	ds_read_b128 v[168:171], v149 offset:50176
	s_nop 0
	ds_read_b128 v[172:175], v149 offset:51200
	s_nop 0
	ds_read_b128 v[176:179], v149 offset:52224
	s_add_u32 s18, s18, 0x80000
	s_addc_u32 s19, s19, 0
	s_mov_b32 m0, s27
	v_lshl_add_u64 v[220:221], s[18:19], 0, v[138:139]
	ds_read_b128 v[180:183], v148 offset:32768
	s_nop 0
	ds_read_b128 v[184:187], v148 offset:33792
	s_nop 0
	ds_read_b128 v[188:191], v148 offset:34816
	s_nop 0
	ds_read_b128 v[192:195], v148 offset:35840
	s_nop 0
	ds_read_b128 v[196:199], v148 offset:36864
	s_nop 0
	ds_read_b128 v[200:203], v148 offset:37888
	s_nop 0
	ds_read_b128 v[204:207], v148 offset:38912
	s_nop 0
	ds_read_b128 v[208:211], v148 offset:39936
	global_load_lds_dwordx4 v[220:221], off
	v_lshl_add_u64 v[220:221], s[18:19], 0, v[134:135]
	s_mov_b32 m0, s30
	s_nop 0
	global_load_lds_dwordx4 v[220:221], off
	s_waitcnt vmcnt(8)
	s_waitcnt lgkmcnt(0)
	s_barrier
	v_mfma_f32_16x16x32_bf16 v[128:131], v[144:147], v[180:183], v[128:131]
	v_mfma_f32_16x16x32_bf16 v[128:131], v[152:155], v[184:187], v[128:131]
	v_mfma_f32_16x16x32_bf16 v[124:127], v[156:159], v[180:183], v[124:127]
	v_mfma_f32_16x16x32_bf16 v[124:127], v[160:163], v[184:187], v[124:127]
	v_mfma_f32_16x16x32_bf16 v[120:123], v[164:167], v[180:183], v[120:123]
	v_mfma_f32_16x16x32_bf16 v[120:123], v[168:171], v[184:187], v[120:123]
	v_mfma_f32_16x16x32_bf16 v[112:115], v[172:175], v[180:183], v[112:115]
	v_mfma_f32_16x16x32_bf16 v[112:115], v[176:179], v[184:187], v[112:115]
	v_mfma_f32_16x16x32_bf16 v[96:99], v[172:175], v[188:191], v[96:99]
	v_mfma_f32_16x16x32_bf16 v[96:99], v[176:179], v[192:195], v[96:99]
	v_mfma_f32_16x16x32_bf16 v[104:107], v[164:167], v[188:191], v[104:107]
	v_mfma_f32_16x16x32_bf16 v[104:107], v[168:171], v[192:195], v[104:107]
	v_mfma_f32_16x16x32_bf16 v[108:111], v[156:159], v[188:191], v[108:111]
	v_mfma_f32_16x16x32_bf16 v[108:111], v[160:163], v[192:195], v[108:111]
	v_mfma_f32_16x16x32_bf16 v[116:119], v[144:147], v[188:191], v[116:119]
	v_mfma_f32_16x16x32_bf16 v[116:119], v[152:155], v[192:195], v[116:119]
	v_mfma_f32_16x16x32_bf16 v[100:103], v[144:147], v[196:199], v[100:103]
	v_mfma_f32_16x16x32_bf16 v[100:103], v[152:155], v[200:203], v[100:103]
	v_mfma_f32_16x16x32_bf16 v[92:95], v[156:159], v[196:199], v[92:95]
	v_mfma_f32_16x16x32_bf16 v[92:95], v[160:163], v[200:203], v[92:95]
	v_mfma_f32_16x16x32_bf16 v[88:91], v[164:167], v[196:199], v[88:91]
	v_mfma_f32_16x16x32_bf16 v[88:91], v[168:171], v[200:203], v[88:91]
	v_mfma_f32_16x16x32_bf16 v[80:83], v[172:175], v[196:199], v[80:83]
	v_mfma_f32_16x16x32_bf16 v[80:83], v[176:179], v[200:203], v[80:83]
	v_mfma_f32_16x16x32_bf16 v[68:71], v[172:175], v[204:207], v[68:71]
	v_mfma_f32_16x16x32_bf16 v[68:71], v[176:179], v[208:211], v[68:71]
	v_mfma_f32_16x16x32_bf16 v[72:75], v[164:167], v[204:207], v[72:75]
	v_mfma_f32_16x16x32_bf16 v[72:75], v[168:171], v[208:211], v[72:75]
	v_mfma_f32_16x16x32_bf16 v[76:79], v[156:159], v[204:207], v[76:79]
	v_mfma_f32_16x16x32_bf16 v[76:79], v[160:163], v[208:211], v[76:79]
	v_mfma_f32_16x16x32_bf16 v[84:87], v[144:147], v[204:207], v[84:87]
	v_mfma_f32_16x16x32_bf16 v[84:87], v[152:155], v[208:211], v[84:87]
	s_barrier
; #define PG8_STAGE(bufoff, gbase, voff) do { _Pragma("unroll") for (int _i = 0; _i < 2; ++_i) \
;         __builtin_amdgcn_global_load_lds((const unsigned*)((const char*)(gbase) + (voff)[_i]), (LAS unsigned*)(lds + (bufoff) + ldsw + _i * 8192), 16, 0, 0); } while (0)
; #define PG8_LDA(dst, b, h) do { _Pragma("unroll") for (int m = 0; m < 4; ++m) _Pragma("unroll") for (int k = 0; k < 2; ++k) dst[m][k] = *(const LAS bf16x8*)(pA + PG8_SA(b, h) + m * 2048 + k * 1024); } while (0)
; #define PG8_MMA(ai, bj, At, Bt) do { __builtin_amdgcn_s_setprio(1); _Pragma("unroll") for (int m = 0; m < 4; ++m) _Pragma("unroll") for (int n = 0; n < 2; ++n) _Pragma("unroll") for (int k = 0; k < 2; ++k) \
;         acc[ai][bj][m][n] = __builtin_amdgcn_mfma_f32_16x16x32_bf16(Bt[n][k], At[m][k], acc[ai][bj][m][n], 0, 0, 0); __builtin_amdgcn_s_setprio(0); } while (0)
; #define PG8_WAIT_V(n) asm volatile("s_waitcnt vmcnt(" #n ")" ::: "memory")
; #define PG8_WAIT_L(n) asm volatile("s_waitcnt lgkmcnt(" #n ")" ::: "memory")
; #define PG8_BAR __builtin_amdgcn_s_barrier()
; #define PG8_SCHED __builtin_amdgcn_sched_barrier(0)
; template <class Desc, class Epi, bool ALIGN_EPI>
; __device__ __forceinline__ void gemm_phase(LAS unsigned char* lds, const Desc& D, const Epi& E, int G, int c) {
;     ...
;             PG8_LDA(At, 1, 1); PG8_STAGE(PG8_SB(1, 0), b3, voffB); PG8_STAGE(PG8_SB(1, 1), b3 + hstepB, voffB); PG8_STAGE(PG8_SA(1, 0), a3, voffA);
;             PG8_WAIT_V(8); PG8_WAIT_L(0); PG8_BAR; PG8_MMA(1, 0, At, B0); PG8_MMA(1, 1, At, B1); PG8_BAR; PG8_SCHED;
;         }
;         if constexpr (ALIGN_EPI) { if (wr == 0) PG8_BAR; }
	s_mov_b32 m0, s31
	v_lshl_add_u64 v[212:213], v[212:213], 0, s[76:77]
	s_add_u32 s16, s16, 0x20080
	ds_read_b128 v[180:183], v148 offset:49152
	s_nop 0
	ds_read_b128 v[184:187], v148 offset:50176
	s_nop 0
	ds_read_b128 v[188:191], v148 offset:51200
	s_nop 0
	ds_read_b128 v[192:195], v148 offset:52224
	s_nop 0
	ds_read_b128 v[196:199], v148 offset:53248
	s_nop 0
	ds_read_b128 v[200:203], v148 offset:54272
	s_nop 0
	ds_read_b128 v[204:207], v148 offset:55296
	s_nop 0
	ds_read_b128 v[208:211], v148 offset:56320
	global_load_lds_dwordx4 v[212:213], off
	v_lshl_add_u64 v[212:213], v[214:215], 0, s[76:77]
	s_mov_b32 m0, s33
	s_addc_u32 s17, s17, 0
	global_load_lds_dwordx4 v[212:213], off
	v_lshl_add_u64 v[212:213], s[16:17], 0, v[136:137]
	s_mov_b32 m0, s38
	s_nop 0
	global_load_lds_dwordx4 v[212:213], off
	v_lshl_add_u64 v[212:213], s[16:17], 0, v[132:133]
	s_mov_b32 m0, s39
	s_nop 0
	global_load_lds_dwordx4 v[212:213], off
	v_lshl_add_u64 v[212:213], v[216:217], 0, s[76:77]
	s_mov_b32 m0, s34
	s_nop 0
	global_load_lds_dwordx4 v[212:213], off
	v_lshl_add_u64 v[212:213], v[218:219], 0, s[76:77]
	s_mov_b32 m0, s35
	s_nop 0
	global_load_lds_dwordx4 v[212:213], off
	s_waitcnt vmcnt(8)
	s_waitcnt lgkmcnt(0)
	s_barrier
	v_mfma_f32_16x16x32_bf16 v[64:67], v[144:147], v[180:183], v[64:67]
	v_mfma_f32_16x16x32_bf16 v[64:67], v[152:155], v[184:187], v[64:67]
	v_mfma_f32_16x16x32_bf16 v[60:63], v[156:159], v[180:183], v[60:63]
	v_mfma_f32_16x16x32_bf16 v[60:63], v[160:163], v[184:187], v[60:63]
	v_mfma_f32_16x16x32_bf16 v[56:59], v[164:167], v[180:183], v[56:59]
	v_mfma_f32_16x16x32_bf16 v[56:59], v[168:171], v[184:187], v[56:59]
	v_mfma_f32_16x16x32_bf16 v[48:51], v[172:175], v[180:183], v[48:51]
	v_mfma_f32_16x16x32_bf16 v[48:51], v[176:179], v[184:187], v[48:51]
	v_mfma_f32_16x16x32_bf16 v[32:35], v[172:175], v[188:191], v[32:35]
	v_mfma_f32_16x16x32_bf16 v[32:35], v[176:179], v[192:195], v[32:35]
	v_mfma_f32_16x16x32_bf16 v[40:43], v[164:167], v[188:191], v[40:43]
	v_mfma_f32_16x16x32_bf16 v[40:43], v[168:171], v[192:195], v[40:43]
	v_mfma_f32_16x16x32_bf16 v[44:47], v[156:159], v[188:191], v[44:47]
	v_mfma_f32_16x16x32_bf16 v[44:47], v[160:163], v[192:195], v[44:47]
	v_mfma_f32_16x16x32_bf16 v[52:55], v[144:147], v[188:191], v[52:55]
	v_mfma_f32_16x16x32_bf16 v[52:55], v[152:155], v[192:195], v[52:55]
	v_mfma_f32_16x16x32_bf16 v[36:39], v[144:147], v[196:199], v[36:39]
	v_mfma_f32_16x16x32_bf16 v[36:39], v[152:155], v[200:203], v[36:39]
	v_mfma_f32_16x16x32_bf16 v[28:31], v[156:159], v[196:199], v[28:31]
	v_mfma_f32_16x16x32_bf16 v[28:31], v[160:163], v[200:203], v[28:31]
	v_mfma_f32_16x16x32_bf16 v[24:27], v[164:167], v[196:199], v[24:27]
	v_mfma_f32_16x16x32_bf16 v[24:27], v[168:171], v[200:203], v[24:27]
	v_mfma_f32_16x16x32_bf16 v[16:19], v[172:175], v[196:199], v[16:19]
	v_mfma_f32_16x16x32_bf16 v[16:19], v[176:179], v[200:203], v[16:19]
	v_mfma_f32_16x16x32_bf16 v[4:7], v[172:175], v[204:207], v[4:7]
	v_mfma_f32_16x16x32_bf16 v[4:7], v[176:179], v[208:211], v[4:7]
	v_mfma_f32_16x16x32_bf16 v[8:11], v[164:167], v[204:207], v[8:11]
	v_mfma_f32_16x16x32_bf16 v[8:11], v[168:171], v[208:211], v[8:11]
	v_mfma_f32_16x16x32_bf16 v[12:15], v[156:159], v[204:207], v[12:15]
	v_mfma_f32_16x16x32_bf16 v[12:15], v[160:163], v[208:211], v[12:15]
	v_mfma_f32_16x16x32_bf16 v[20:23], v[144:147], v[204:207], v[20:23]
	v_mfma_f32_16x16x32_bf16 v[20:23], v[152:155], v[208:211], v[20:23]
	s_barrier
	s_add_i32 s46, s46, 2
	s_add_u32 s12, s12, 0x100
	s_addc_u32 s13, s13, 0
	s_add_u32 s7, s7, 0x100
	s_addc_u32 s45, s45, 0
	s_cmp_gt_u32 s46, 5
	s_cbranch_scc0 .LBB0_603
	v_readlane_b32 s46, v255, 36
	s_and_b64 vcc, exec, s[4:5]
	v_readlane_b32 s47, v255, 37
	s_cbranch_vccz .LBB0_606
	s_barrier

;     __device__ __forceinline__ int nt(const Unit& u) const { return (u.pn >> 1) < 2 ? 22 : 20; }
; #define PG8_STAGE(bufoff, gbase, voff) do { _Pragma("unroll") for (int _i = 0; _i < 2; ++_i) \
;         __builtin_amdgcn_global_load_lds((const unsigned*)((const char*)(gbase) + (voff)[_i]), (LAS unsigned*)(lds + (bufoff) + ldsw + _i * 8192), 16, 0, 0); } while (0)
; #define PG8_LDA(dst, b, h) do { _Pragma("unroll") for (int m = 0; m < 4; ++m) _Pragma("unroll") for (int k = 0; k < 2; ++k) dst[m][k] = *(const LAS bf16x8*)(pA + PG8_SA(b, h) + m * 2048 + k * 1024); } while (0)
; #define PG8_LDB(dst, b, h) do { _Pragma("unroll") for (int n = 0; n < 2; ++n) _Pragma("unroll") for (int k = 0; k < 2; ++k) dst[n][k] = *(const LAS bf16x8*)(pB + (PG8_SB(b, h) - 4 * HTB) + n * 2048 + k * 1024); } while (0)
; #define PG8_MMA(ai, bj, At, Bt) do { __builtin_amdgcn_s_setprio(1); _Pragma("unroll") for (int m = 0; m < 4; ++m) _Pragma("unroll") for (int n = 0; n < 2; ++n) _Pragma("unroll") for (int k = 0; k < 2; ++k) \
;         acc[ai][bj][m][n] = __builtin_amdgcn_mfma_f32_16x16x32_bf16(Bt[n][k], At[m][k], acc[ai][bj][m][n], 0, 0, 0); __builtin_amdgcn_s_setprio(0); } while (0)
; #define PG8_WAIT_V(n) asm volatile("s_waitcnt vmcnt(" #n ")" ::: "memory")
; #define PG8_BAR __builtin_amdgcn_s_barrier()
; template <class Desc, class Epi, bool ALIGN_EPI>
; __device__ __forceinline__ void gemm_phase(LAS unsigned char* lds, const Desc& D, const Epi& E, int G, int c) {
;     ...
;         for (int t = 0; t < nt; t += 2) {
;             const bool last = (t == nt - 2);
;             if (last && has_next) PG8_AWAIT(nxt);
;             const char* a1 = cA + (size_t)(t + 1) * kstep;
;             const char* a2 = last ? nA : cA + (size_t)(t + 2) * kstep; const char* b2 = last ? nB : cB + (size_t)(t + 2) * kstep;
;             const char* a3 = a2 + kstep; const char* b3 = b2 + kstep;
;             PG8_LDB(B0, 0, 0); PG8_LDB(B1, 0, 1); PG8_SCHED; PG8_LDA(At, 0, 0); PG8_STAGE(PG8_SA(1, 1), a1 + hstepA, voffA);
;             PG8_WAIT_V(8); PG8_WAIT_L(0); PG8_BAR; PG8_MMA(0, 0, At, B0); PG8_MMA(0, 1, At, B1); PG8_BAR; PG8_SCHED;
;             PG8_LDA(At, 0, 1); PG8_STAGE(PG8_SB(0, 0), b2, voffB); PG8_STAGE(PG8_SB(0, 1), b2 + hstepB, voffB); PG8_STAGE(PG8_SA(0, 0), a2, voffA);
;             PG8_WAIT_V(8); PG8_WAIT_L(0); PG8_BAR; PG8_MMA(1, 0, At, B0); PG8_MMA(1, 1, At, B1); PG8_BAR; PG8_SCHED;
.LBB0_1164:
	s_waitcnt lgkmcnt(0)
	ds_read_b128 v[132:135], v229
	s_nop 0
	ds_read_b128 v[136:139], v229 offset:1024
	s_nop 0
	ds_read_b128 v[140:143], v229 offset:2048
	s_nop 0
	ds_read_b128 v[144:147], v229 offset:3072
	s_nop 0
	ds_read_b128 v[148:151], v229 offset:16384
	s_nop 0
	ds_read_b128 v[152:155], v229 offset:17408
	s_nop 0
	ds_read_b128 v[156:159], v229 offset:18432
	s_nop 0
	ds_read_b128 v[160:163], v229 offset:19456
	s_add_i32 s20, s14, 2
	s_add_u32 s16, s12, 0xfff00080
	s_addc_u32 s17, s13, -1
	s_cmp_eq_u32 s1, s14
	s_cselect_b32 s19, s39, s17
	s_cselect_b32 s18, s38, s16
	s_cselect_b32 s17, s41, s11
	s_cselect_b32 s16, s40, s3
	v_lshl_add_u64 v[208:209], s[12:13], 0, v[204:205]
	s_add_i32 m0, s35, 0xc000
	ds_read_b128 v[164:167], v228
	s_nop 0
	ds_read_b128 v[168:171], v228 offset:1024
	s_nop 0
	ds_read_b128 v[172:175], v228 offset:2048
	s_nop 0
	ds_read_b128 v[176:179], v228 offset:3072
	s_nop 0
	ds_read_b128 v[180:183], v228 offset:4096
	s_nop 0
	ds_read_b128 v[184:187], v228 offset:5120
	s_nop 0
	ds_read_b128 v[188:191], v228 offset:6144
	s_nop 0
	ds_read_b128 v[192:195], v228 offset:7168
	global_load_lds_dwordx4 v[208:209], off
	v_lshl_add_u64 v[208:209], s[12:13], 0, v[206:207]
	s_add_i32 m0, s35, 0xe000
	s_nop 0
	global_load_lds_dwordx4 v[208:209], off
	s_waitcnt vmcnt(8)
	s_waitcnt lgkmcnt(0)
	s_barrier
	v_mfma_f32_16x16x32_bf16 v[128:131], v[132:135], v[164:167], v[128:131]
	v_mfma_f32_16x16x32_bf16 v[128:131], v[136:139], v[168:171], v[128:131]
	v_mfma_f32_16x16x32_bf16 v[124:127], v[140:143], v[164:167], v[124:127]
	v_mfma_f32_16x16x32_bf16 v[124:127], v[144:147], v[168:171], v[124:127]
	v_mfma_f32_16x16x32_bf16 v[96:99], v[148:151], v[164:167], v[96:99]
	v_mfma_f32_16x16x32_bf16 v[96:99], v[152:155], v[168:171], v[96:99]
	v_mfma_f32_16x16x32_bf16 v[92:95], v[156:159], v[164:167], v[92:95]
	v_mfma_f32_16x16x32_bf16 v[92:95], v[160:163], v[168:171], v[92:95]
	v_mfma_f32_16x16x32_bf16 v[80:83], v[156:159], v[172:175], v[80:83]
	v_mfma_f32_16x16x32_bf16 v[80:83], v[160:163], v[176:179], v[80:83]
	v_mfma_f32_16x16x32_bf16 v[88:91], v[148:151], v[172:175], v[88:91]
	v_mfma_f32_16x16x32_bf16 v[88:91], v[152:155], v[176:179], v[88:91]
	v_mfma_f32_16x16x32_bf16 v[116:119], v[140:143], v[172:175], v[116:119]
	v_mfma_f32_16x16x32_bf16 v[116:119], v[144:147], v[176:179], v[116:119]
	v_mfma_f32_16x16x32_bf16 v[120:123], v[132:135], v[172:175], v[120:123]
	v_mfma_f32_16x16x32_bf16 v[120:123], v[136:139], v[176:179], v[120:123]
	v_mfma_f32_16x16x32_bf16 v[112:115], v[132:135], v[180:183], v[112:115]
	v_mfma_f32_16x16x32_bf16 v[112:115], v[136:139], v[184:187], v[112:115]
	v_mfma_f32_16x16x32_bf16 v[108:111], v[140:143], v[180:183], v[108:111]
	v_mfma_f32_16x16x32_bf16 v[108:111], v[144:147], v[184:187], v[108:111]
	v_mfma_f32_16x16x32_bf16 v[64:67], v[148:151], v[180:183], v[64:67]
	v_mfma_f32_16x16x32_bf16 v[64:67], v[152:155], v[184:187], v[64:67]
	v_mfma_f32_16x16x32_bf16 v[52:55], v[156:159], v[180:183], v[52:55]
	v_mfma_f32_16x16x32_bf16 v[52:55], v[160:163], v[184:187], v[52:55]
	v_mfma_f32_16x16x32_bf16 v[20:23], v[156:159], v[188:191], v[20:23]
	v_mfma_f32_16x16x32_bf16 v[20:23], v[160:163], v[192:195], v[20:23]
	v_mfma_f32_16x16x32_bf16 v[32:35], v[148:151], v[188:191], v[32:35]
	v_mfma_f32_16x16x32_bf16 v[32:35], v[152:155], v[192:195], v[32:35]
	v_mfma_f32_16x16x32_bf16 v[100:103], v[140:143], v[188:191], v[100:103]
	v_mfma_f32_16x16x32_bf16 v[100:103], v[144:147], v[192:195], v[100:103]
	v_mfma_f32_16x16x32_bf16 v[104:107], v[132:135], v[188:191], v[104:107]
	v_mfma_f32_16x16x32_bf16 v[104:107], v[136:139], v[192:195], v[104:107]
	s_barrier
	s_mov_b32 m0, s44
	v_lshl_add_u64 v[208:209], s[16:17], 0, v[198:199]
	s_add_u32 s62, s16, 0x100000
	ds_read_b128 v[164:167], v228 offset:16384
	s_nop 0
	ds_read_b128 v[168:171], v228 offset:17408
	s_nop 0
	ds_read_b128 v[172:175], v228 offset:18432
	s_nop 0
	ds_read_b128 v[176:179], v228 offset:19456
	s_nop 0
	ds_read_b128 v[180:183], v228 offset:20480
	s_nop 0
	ds_read_b128 v[184:187], v228 offset:21504
	s_nop 0
	ds_read_b128 v[188:191], v228 offset:22528
	s_nop 0
	ds_read_b128 v[192:195], v228 offset:23552
	global_load_lds_dwordx4 v[208:209], off
	v_lshl_add_u64 v[210:211], s[16:17], 0, v[202:203]
	s_mov_b32 m0, s45
	s_addc_u32 s63, s17, 0
	global_load_lds_dwordx4 v[210:211], off
	v_lshl_add_u64 v[212:213], s[62:63], 0, v[198:199]
	s_mov_b32 m0, s46
	v_lshl_add_u64 v[214:215], s[18:19], 0, v[200:201]
	global_load_lds_dwordx4 v[212:213], off
	v_lshl_add_u64 v[212:213], s[62:63], 0, v[202:203]
	s_mov_b32 m0, s47
	s_nop 0
	global_load_lds_dwordx4 v[212:213], off
	v_lshl_add_u64 v[212:213], s[18:19], 0, v[196:197]
	s_mov_b32 m0, s35
	s_nop 0
	global_load_lds_dwordx4 v[212:213], off
	s_mov_b32 m0, s48
	s_nop 0
	global_load_lds_dwordx4 v[214:215], off
	s_waitcnt vmcnt(8)
	s_waitcnt lgkmcnt(0)
	s_barrier
; #define PG8_STAGE(bufoff, gbase, voff) do { _Pragma("unroll") for (int _i = 0; _i < 2; ++_i) \
;         __builtin_amdgcn_global_load_lds((const unsigned*)((const char*)(gbase) + (voff)[_i]), (LAS unsigned*)(lds + (bufoff) + ldsw + _i * 8192), 16, 0, 0); } while (0)
; #define PG8_LDA(dst, b, h) do { _Pragma("unroll") for (int m = 0; m < 4; ++m) _Pragma("unroll") for (int k = 0; k < 2; ++k) dst[m][k] = *(const LAS bf16x8*)(pA + PG8_SA(b, h) + m * 2048 + k * 1024); } while (0)
; #define PG8_LDB(dst, b, h) do { _Pragma("unroll") for (int n = 0; n < 2; ++n) _Pragma("unroll") for (int k = 0; k < 2; ++k) dst[n][k] = *(const LAS bf16x8*)(pB + (PG8_SB(b, h) - 4 * HTB) + n * 2048 + k * 1024); } while (0)
; #define PG8_MMA(ai, bj, At, Bt) do { __builtin_amdgcn_s_setprio(1); _Pragma("unroll") for (int m = 0; m < 4; ++m) _Pragma("unroll") for (int n = 0; n < 2; ++n) _Pragma("unroll") for (int k = 0; k < 2; ++k) \
;         acc[ai][bj][m][n] = __builtin_amdgcn_mfma_f32_16x16x32_bf16(Bt[n][k], At[m][k], acc[ai][bj][m][n], 0, 0, 0); __builtin_amdgcn_s_setprio(0); } while (0)
; #define PG8_WAIT_V(n) asm volatile("s_waitcnt vmcnt(" #n ")" ::: "memory")
; #define PG8_WAIT_L(n) asm volatile("s_waitcnt lgkmcnt(" #n ")" ::: "memory")
; #define PG8_BAR __builtin_amdgcn_s_barrier()
; #define PG8_SCHED __builtin_amdgcn_sched_barrier(0)
; template <class Desc, class Epi, bool ALIGN_EPI>
; __device__ __forceinline__ void gemm_phase(LAS unsigned char* lds, const Desc& D, const Epi& E, int G, int c) {
;     ...
;             PG8_WAIT_V(8); PG8_WAIT_L(0); PG8_BAR; PG8_MMA(1, 0, At, B0); PG8_MMA(1, 1, At, B1); PG8_BAR; PG8_SCHED;
;             PG8_LDB(B0, 1, 0); PG8_LDB(B1, 1, 1); PG8_SCHED; PG8_LDA(At, 1, 0); PG8_STAGE(PG8_SA(0, 1), a2 + hstepA, voffA);
;             PG8_WAIT_V(8); PG8_WAIT_L(0); PG8_BAR; PG8_MMA(0, 0, At, B0); PG8_MMA(0, 1, At, B1); PG8_BAR; PG8_SCHED;
	v_mfma_f32_16x16x32_bf16 v[84:87], v[132:135], v[164:167], v[84:87]
	v_mfma_f32_16x16x32_bf16 v[84:87], v[136:139], v[168:171], v[84:87]
	v_mfma_f32_16x16x32_bf16 v[76:79], v[140:143], v[164:167], v[76:79]
	v_mfma_f32_16x16x32_bf16 v[76:79], v[144:147], v[168:171], v[76:79]
	v_mfma_f32_16x16x32_bf16 v[40:43], v[148:151], v[164:167], v[40:43]
	v_mfma_f32_16x16x32_bf16 v[40:43], v[152:155], v[168:171], v[40:43]
	v_mfma_f32_16x16x32_bf16 v[36:39], v[156:159], v[164:167], v[36:39]
	v_mfma_f32_16x16x32_bf16 v[36:39], v[160:163], v[168:171], v[36:39]
	v_mfma_f32_16x16x32_bf16 v[24:27], v[156:159], v[172:175], v[24:27]
	v_mfma_f32_16x16x32_bf16 v[24:27], v[160:163], v[176:179], v[24:27]
	v_mfma_f32_16x16x32_bf16 v[28:31], v[148:151], v[172:175], v[28:31]
	v_mfma_f32_16x16x32_bf16 v[28:31], v[152:155], v[176:179], v[28:31]
	v_mfma_f32_16x16x32_bf16 v[68:71], v[140:143], v[172:175], v[68:71]
	v_mfma_f32_16x16x32_bf16 v[68:71], v[144:147], v[176:179], v[68:71]
	v_mfma_f32_16x16x32_bf16 v[72:75], v[132:135], v[172:175], v[72:75]
	v_mfma_f32_16x16x32_bf16 v[72:75], v[136:139], v[176:179], v[72:75]
	v_mfma_f32_16x16x32_bf16 v[60:63], v[132:135], v[180:183], v[60:63]
	v_mfma_f32_16x16x32_bf16 v[60:63], v[136:139], v[184:187], v[60:63]
	v_mfma_f32_16x16x32_bf16 v[56:59], v[140:143], v[180:183], v[56:59]
	v_mfma_f32_16x16x32_bf16 v[56:59], v[144:147], v[184:187], v[56:59]
	v_mfma_f32_16x16x32_bf16 v[16:19], v[148:151], v[180:183], v[16:19]
	v_mfma_f32_16x16x32_bf16 v[16:19], v[152:155], v[184:187], v[16:19]
	v_mfma_f32_16x16x32_bf16 v[12:15], v[156:159], v[180:183], v[12:15]
	v_mfma_f32_16x16x32_bf16 v[12:15], v[160:163], v[184:187], v[12:15]
	v_mfma_f32_16x16x32_bf16 v[4:7], v[156:159], v[188:191], v[4:7]
	v_mfma_f32_16x16x32_bf16 v[4:7], v[160:163], v[192:195], v[4:7]
	v_mfma_f32_16x16x32_bf16 v[8:11], v[148:151], v[188:191], v[8:11]
	v_mfma_f32_16x16x32_bf16 v[8:11], v[152:155], v[192:195], v[8:11]
	v_mfma_f32_16x16x32_bf16 v[44:47], v[140:143], v[188:191], v[44:47]
	v_mfma_f32_16x16x32_bf16 v[44:47], v[144:147], v[192:195], v[44:47]
	v_mfma_f32_16x16x32_bf16 v[48:51], v[132:135], v[188:191], v[48:51]
	v_mfma_f32_16x16x32_bf16 v[48:51], v[136:139], v[192:195], v[48:51]
	s_barrier
	ds_read_b128 v[132:135], v229 offset:32768
	s_nop 0
	ds_read_b128 v[136:139], v229 offset:33792
	s_nop 0
	ds_read_b128 v[140:143], v229 offset:34816
	s_nop 0
	ds_read_b128 v[144:147], v229 offset:35840
	s_nop 0
	ds_read_b128 v[148:151], v229 offset:49152
	s_nop 0
	ds_read_b128 v[152:155], v229 offset:50176
	s_nop 0
	ds_read_b128 v[156:159], v229 offset:51200
	s_nop 0
	ds_read_b128 v[160:163], v229 offset:52224
	s_add_u32 s18, s18, 0x100000
	s_addc_u32 s19, s19, 0
	s_mov_b32 m0, s49
	v_lshl_add_u64 v[216:217], s[18:19], 0, v[196:197]
	ds_read_b128 v[164:167], v228 offset:32768
	s_nop 0
	ds_read_b128 v[168:171], v228 offset:33792
	s_nop 0
	ds_read_b128 v[172:175], v228 offset:34816
	s_nop 0
	ds_read_b128 v[176:179], v228 offset:35840
	s_nop 0
	ds_read_b128 v[180:183], v228 offset:36864
	s_nop 0
	ds_read_b128 v[184:187], v228 offset:37888
	s_nop 0
	ds_read_b128 v[188:191], v228 offset:38912
	s_nop 0
	ds_read_b128 v[192:195], v228 offset:39936
	global_load_lds_dwordx4 v[216:217], off
	v_lshl_add_u64 v[216:217], s[18:19], 0, v[200:201]
	s_mov_b32 m0, s50
	s_nop 0
	global_load_lds_dwordx4 v[216:217], off
	s_waitcnt vmcnt(8)
	s_waitcnt lgkmcnt(0)
	s_barrier
	v_mfma_f32_16x16x32_bf16 v[128:131], v[132:135], v[164:167], v[128:131]
	v_mfma_f32_16x16x32_bf16 v[128:131], v[136:139], v[168:171], v[128:131]
	v_mfma_f32_16x16x32_bf16 v[124:127], v[140:143], v[164:167], v[124:127]
	v_mfma_f32_16x16x32_bf16 v[124:127], v[144:147], v[168:171], v[124:127]
	v_mfma_f32_16x16x32_bf16 v[96:99], v[148:151], v[164:167], v[96:99]
	v_mfma_f32_16x16x32_bf16 v[96:99], v[152:155], v[168:171], v[96:99]
	v_mfma_f32_16x16x32_bf16 v[92:95], v[156:159], v[164:167], v[92:95]
	v_mfma_f32_16x16x32_bf16 v[92:95], v[160:163], v[168:171], v[92:95]
	v_mfma_f32_16x16x32_bf16 v[80:83], v[156:159], v[172:175], v[80:83]
	v_mfma_f32_16x16x32_bf16 v[80:83], v[160:163], v[176:179], v[80:83]
	v_mfma_f32_16x16x32_bf16 v[88:91], v[148:151], v[172:175], v[88:91]
	v_mfma_f32_16x16x32_bf16 v[88:91], v[152:155], v[176:179], v[88:91]
	v_mfma_f32_16x16x32_bf16 v[116:119], v[140:143], v[172:175], v[116:119]
	v_mfma_f32_16x16x32_bf16 v[116:119], v[144:147], v[176:179], v[116:119]
	v_mfma_f32_16x16x32_bf16 v[120:123], v[132:135], v[172:175], v[120:123]
	v_mfma_f32_16x16x32_bf16 v[120:123], v[136:139], v[176:179], v[120:123]
	v_mfma_f32_16x16x32_bf16 v[112:115], v[132:135], v[180:183], v[112:115]
	v_mfma_f32_16x16x32_bf16 v[112:115], v[136:139], v[184:187], v[112:115]
	v_mfma_f32_16x16x32_bf16 v[108:111], v[140:143], v[180:183], v[108:111]
	v_mfma_f32_16x16x32_bf16 v[108:111], v[144:147], v[184:187], v[108:111]
	v_mfma_f32_16x16x32_bf16 v[64:67], v[148:151], v[180:183], v[64:67]
	v_mfma_f32_16x16x32_bf16 v[64:67], v[152:155], v[184:187], v[64:67]
	v_mfma_f32_16x16x32_bf16 v[52:55], v[156:159], v[180:183], v[52:55]
	v_mfma_f32_16x16x32_bf16 v[52:55], v[160:163], v[184:187], v[52:55]
	v_mfma_f32_16x16x32_bf16 v[20:23], v[156:159], v[188:191], v[20:23]
	v_mfma_f32_16x16x32_bf16 v[20:23], v[160:163], v[192:195], v[20:23]
	v_mfma_f32_16x16x32_bf16 v[32:35], v[148:151], v[188:191], v[32:35]
	v_mfma_f32_16x16x32_bf16 v[32:35], v[152:155], v[192:195], v[32:35]
	v_mfma_f32_16x16x32_bf16 v[100:103], v[140:143], v[188:191], v[100:103]
	v_mfma_f32_16x16x32_bf16 v[100:103], v[144:147], v[192:195], v[100:103]
	v_mfma_f32_16x16x32_bf16 v[104:107], v[132:135], v[188:191], v[104:107]
	v_mfma_f32_16x16x32_bf16 v[104:107], v[136:139], v[192:195], v[104:107]
	s_barrier
; #define PG8_STAGE(bufoff, gbase, voff) do { _Pragma("unroll") for (int _i = 0; _i < 2; ++_i) \
;         __builtin_amdgcn_global_load_lds((const unsigned*)((const char*)(gbase) + (voff)[_i]), (LAS unsigned*)(lds + (bufoff) + ldsw + _i * 8192), 16, 0, 0); } while (0)
; #define PG8_LDA(dst, b, h) do { _Pragma("unroll") for (int m = 0; m < 4; ++m) _Pragma("unroll") for (int k = 0; k < 2; ++k) dst[m][k] = *(const LAS bf16x8*)(pA + PG8_SA(b, h) + m * 2048 + k * 1024); } while (0)
; #define PG8_MMA(ai, bj, At, Bt) do { __builtin_amdgcn_s_setprio(1); _Pragma("unroll") for (int m = 0; m < 4; ++m) _Pragma("unroll") for (int n = 0; n < 2; ++n) _Pragma("unroll") for (int k = 0; k < 2; ++k) \
;         acc[ai][bj][m][n] = __builtin_amdgcn_mfma_f32_16x16x32_bf16(Bt[n][k], At[m][k], acc[ai][bj][m][n], 0, 0, 0); __builtin_amdgcn_s_setprio(0); } while (0)
; #define PG8_WAIT_V(n) asm volatile("s_waitcnt vmcnt(" #n ")" ::: "memory")
; #define PG8_WAIT_L(n) asm volatile("s_waitcnt lgkmcnt(" #n ")" ::: "memory")
; #define PG8_BAR __builtin_amdgcn_s_barrier()
; #define PG8_SCHED __builtin_amdgcn_sched_barrier(0)
; template <class Desc, class Epi, bool ALIGN_EPI>
; __device__ __forceinline__ void gemm_phase(LAS unsigned char* lds, const Desc& D, const Epi& E, int G, int c) {
;     ...
;             PG8_LDA(At, 1, 1); PG8_STAGE(PG8_SB(1, 0), b3, voffB); PG8_STAGE(PG8_SB(1, 1), b3 + hstepB, voffB); PG8_STAGE(PG8_SA(1, 0), a3, voffA);
;             PG8_WAIT_V(8); PG8_WAIT_L(0); PG8_BAR; PG8_MMA(1, 0, At, B0); PG8_MMA(1, 1, At, B1); PG8_BAR; PG8_SCHED;
;         }
;         if constexpr (ALIGN_EPI) { if (wr == 0) PG8_BAR; }
	s_mov_b32 m0, s52
	v_lshl_add_u64 v[208:209], v[208:209], 0, s[76:77]
	s_add_u32 s16, s16, 0x100080
	ds_read_b128 v[164:167], v228 offset:49152
	s_nop 0
	ds_read_b128 v[168:171], v228 offset:50176
	s_nop 0
	ds_read_b128 v[172:175], v228 offset:51200
	s_nop 0
	ds_read_b128 v[176:179], v228 offset:52224
	s_nop 0
	ds_read_b128 v[180:183], v228 offset:53248
	s_nop 0
	ds_read_b128 v[184:187], v228 offset:54272
	s_nop 0
	ds_read_b128 v[188:191], v228 offset:55296
	s_nop 0
	ds_read_b128 v[192:195], v228 offset:56320
	global_load_lds_dwordx4 v[208:209], off
	v_lshl_add_u64 v[208:209], v[210:211], 0, s[76:77]
	s_mov_b32 m0, s53
	s_addc_u32 s17, s17, 0
	global_load_lds_dwordx4 v[208:209], off
	v_lshl_add_u64 v[208:209], s[16:17], 0, v[198:199]
	s_mov_b32 m0, s56
	s_nop 0
	global_load_lds_dwordx4 v[208:209], off
	v_lshl_add_u64 v[208:209], s[16:17], 0, v[202:203]
	s_mov_b32 m0, s57
	s_nop 0
	global_load_lds_dwordx4 v[208:209], off
	v_lshl_add_u64 v[208:209], v[212:213], 0, s[76:77]
	s_mov_b32 m0, s54
	s_nop 0
	global_load_lds_dwordx4 v[208:209], off
	v_lshl_add_u64 v[208:209], v[214:215], 0, s[76:77]
	s_mov_b32 m0, s55
	s_nop 0
	global_load_lds_dwordx4 v[208:209], off
	s_waitcnt vmcnt(8)
	s_waitcnt lgkmcnt(0)
	s_barrier
	v_mfma_f32_16x16x32_bf16 v[84:87], v[132:135], v[164:167], v[84:87]
	v_mfma_f32_16x16x32_bf16 v[84:87], v[136:139], v[168:171], v[84:87]
	v_mfma_f32_16x16x32_bf16 v[76:79], v[140:143], v[164:167], v[76:79]
	v_mfma_f32_16x16x32_bf16 v[76:79], v[144:147], v[168:171], v[76:79]
	v_mfma_f32_16x16x32_bf16 v[40:43], v[148:151], v[164:167], v[40:43]
	v_mfma_f32_16x16x32_bf16 v[40:43], v[152:155], v[168:171], v[40:43]
	v_mfma_f32_16x16x32_bf16 v[36:39], v[156:159], v[164:167], v[36:39]
	v_mfma_f32_16x16x32_bf16 v[36:39], v[160:163], v[168:171], v[36:39]
	v_mfma_f32_16x16x32_bf16 v[24:27], v[156:159], v[172:175], v[24:27]
	v_mfma_f32_16x16x32_bf16 v[24:27], v[160:163], v[176:179], v[24:27]
	v_mfma_f32_16x16x32_bf16 v[28:31], v[148:151], v[172:175], v[28:31]
	v_mfma_f32_16x16x32_bf16 v[28:31], v[152:155], v[176:179], v[28:31]
	v_mfma_f32_16x16x32_bf16 v[68:71], v[140:143], v[172:175], v[68:71]
	v_mfma_f32_16x16x32_bf16 v[68:71], v[144:147], v[176:179], v[68:71]
	v_mfma_f32_16x16x32_bf16 v[72:75], v[132:135], v[172:175], v[72:75]
	v_mfma_f32_16x16x32_bf16 v[72:75], v[136:139], v[176:179], v[72:75]
	v_mfma_f32_16x16x32_bf16 v[60:63], v[132:135], v[180:183], v[60:63]
	v_mfma_f32_16x16x32_bf16 v[60:63], v[136:139], v[184:187], v[60:63]
	v_mfma_f32_16x16x32_bf16 v[56:59], v[140:143], v[180:183], v[56:59]
	v_mfma_f32_16x16x32_bf16 v[56:59], v[144:147], v[184:187], v[56:59]
	v_mfma_f32_16x16x32_bf16 v[16:19], v[148:151], v[180:183], v[16:19]
	v_mfma_f32_16x16x32_bf16 v[16:19], v[152:155], v[184:187], v[16:19]
	v_mfma_f32_16x16x32_bf16 v[12:15], v[156:159], v[180:183], v[12:15]
	v_mfma_f32_16x16x32_bf16 v[12:15], v[160:163], v[184:187], v[12:15]
	v_mfma_f32_16x16x32_bf16 v[4:7], v[156:159], v[188:191], v[4:7]
	v_mfma_f32_16x16x32_bf16 v[4:7], v[160:163], v[192:195], v[4:7]
	v_mfma_f32_16x16x32_bf16 v[8:11], v[148:151], v[188:191], v[8:11]
	v_mfma_f32_16x16x32_bf16 v[8:11], v[152:155], v[192:195], v[8:11]
	v_mfma_f32_16x16x32_bf16 v[44:47], v[140:143], v[188:191], v[44:47]
	v_mfma_f32_16x16x32_bf16 v[44:47], v[144:147], v[192:195], v[44:47]
	v_mfma_f32_16x16x32_bf16 v[48:51], v[132:135], v[188:191], v[48:51]
	v_mfma_f32_16x16x32_bf16 v[48:51], v[136:139], v[192:195], v[48:51]
	s_barrier
	s_add_u32 s12, s12, 0x100
	s_addc_u32 s13, s13, 0
	s_add_u32 s3, s3, 0x100
	s_addc_u32 s11, s11, 0
	s_cmp_ge_u32 s20, s2
	s_mov_b32 s14, s20
	s_cbranch_scc0 .LBB0_1164
	s_and_b64 vcc, exec, s[8:9]
	s_cbranch_vccz .LBB0_1167
	s_barrier

;     __device__ __forceinline__ int nt(const Unit& u) const { return (u.pn >> 1) < 2 ? 22 : 20; }
; #define PG8_STAGE(bufoff, gbase, voff) do { _Pragma("unroll") for (int _i = 0; _i < 2; ++_i) \
;         __builtin_amdgcn_global_load_lds((const unsigned*)((const char*)(gbase) + (voff)[_i]), (LAS unsigned*)(lds + (bufoff) + ldsw + _i * 8192), 16, 0, 0); } while (0)
; #define PG8_LDA(dst, b, h) do { _Pragma("unroll") for (int m = 0; m < 4; ++m) _Pragma("unroll") for (int k = 0; k < 2; ++k) dst[m][k] = *(const LAS bf16x8*)(pA + PG8_SA(b, h) + m * 2048 + k * 1024); } while (0)
; #define PG8_LDB(dst, b, h) do { _Pragma("unroll") for (int n = 0; n < 2; ++n) _Pragma("unroll") for (int k = 0; k < 2; ++k) dst[n][k] = *(const LAS bf16x8*)(pB + (PG8_SB(b, h) - 4 * HTB) + n * 2048 + k * 1024); } while (0)
; #define PG8_MMA(ai, bj, At, Bt) do { __builtin_amdgcn_s_setprio(1); _Pragma("unroll") for (int m = 0; m < 4; ++m) _Pragma("unroll") for (int n = 0; n < 2; ++n) _Pragma("unroll") for (int k = 0; k < 2; ++k) \
;         acc[ai][bj][m][n] = __builtin_amdgcn_mfma_f32_16x16x32_bf16(Bt[n][k], At[m][k], acc[ai][bj][m][n], 0, 0, 0); __builtin_amdgcn_s_setprio(0); } while (0)
; #define PG8_WAIT_V(n) asm volatile("s_waitcnt vmcnt(" #n ")" ::: "memory")
; #define PG8_BAR __builtin_amdgcn_s_barrier()
; template <class Desc, class Epi, bool ALIGN_EPI>
; __device__ __forceinline__ void gemm_phase(LAS unsigned char* lds, const Desc& D, const Epi& E, int G, int c) {
;     ...
;         for (int t = 0; t < nt; t += 2) {
;             const bool last = (t == nt - 2);
;             if (last && has_next) PG8_AWAIT(nxt);
;             const char* a1 = cA + (size_t)(t + 1) * kstep;
;             const char* a2 = last ? nA : cA + (size_t)(t + 2) * kstep; const char* b2 = last ? nB : cB + (size_t)(t + 2) * kstep;
;             const char* a3 = a2 + kstep; const char* b3 = b2 + kstep;
;             PG8_LDB(B0, 0, 0); PG8_LDB(B1, 0, 1); PG8_SCHED; PG8_LDA(At, 0, 0); PG8_STAGE(PG8_SA(1, 1), a1 + hstepA, voffA);
;             PG8_WAIT_V(8); PG8_WAIT_L(0); PG8_BAR; PG8_MMA(0, 0, At, B0); PG8_MMA(0, 1, At, B1); PG8_BAR; PG8_SCHED;
;             PG8_LDA(At, 0, 1); PG8_STAGE(PG8_SB(0, 0), b2, voffB); PG8_STAGE(PG8_SB(0, 1), b2 + hstepB, voffB); PG8_STAGE(PG8_SA(0, 0), a2, voffA);
;             PG8_WAIT_V(8); PG8_WAIT_L(0); PG8_BAR; PG8_MMA(1, 0, At, B0); PG8_MMA(1, 1, At, B1); PG8_BAR; PG8_SCHED;
.LBB0_1324:
	ds_read_b128 v[144:147], v149
	s_nop 0
	ds_read_b128 v[152:155], v149 offset:1024
	s_nop 0
	ds_read_b128 v[156:159], v149 offset:2048
	s_nop 0
	ds_read_b128 v[160:163], v149 offset:3072
	s_nop 0
	ds_read_b128 v[164:167], v149 offset:16384
	s_nop 0
	ds_read_b128 v[168:171], v149 offset:17408
	s_nop 0
	ds_read_b128 v[172:175], v149 offset:18432
	s_nop 0
	ds_read_b128 v[176:179], v149 offset:19456
	s_add_i32 s50, s18, 2
	s_add_u32 s19, s16, 0xfff00080
	s_addc_u32 s20, s17, -1
	s_cmp_eq_u32 s9, s18
	s_cselect_b32 s18, s12, s48
	s_cselect_b32 s21, s11, s20
	s_cselect_b32 s20, s10, s19
	s_cselect_b32 s19, s13, s49
	v_lshl_add_u64 v[212:213], s[16:17], 0, v[140:141]
	s_add_i32 m0, s24, 0xc000
	ds_read_b128 v[180:183], v148
	s_nop 0
	ds_read_b128 v[184:187], v148 offset:1024
	s_nop 0
	ds_read_b128 v[188:191], v148 offset:2048
	s_nop 0
	ds_read_b128 v[192:195], v148 offset:3072
	s_nop 0
	ds_read_b128 v[196:199], v148 offset:4096
	s_nop 0
	ds_read_b128 v[200:203], v148 offset:5120
	s_nop 0
	ds_read_b128 v[204:207], v148 offset:6144
	s_nop 0
	ds_read_b128 v[208:211], v148 offset:7168
	global_load_lds_dwordx4 v[212:213], off
	v_lshl_add_u64 v[212:213], s[16:17], 0, v[142:143]
	s_add_i32 m0, s24, 0xe000
	s_nop 0
	global_load_lds_dwordx4 v[212:213], off
	s_waitcnt vmcnt(8)
	s_waitcnt lgkmcnt(0)
	s_barrier
	v_mfma_f32_16x16x32_bf16 v[128:131], v[144:147], v[180:183], v[128:131]
	v_mfma_f32_16x16x32_bf16 v[128:131], v[152:155], v[184:187], v[128:131]
	v_mfma_f32_16x16x32_bf16 v[124:127], v[156:159], v[180:183], v[124:127]
	v_mfma_f32_16x16x32_bf16 v[124:127], v[160:163], v[184:187], v[124:127]
	v_mfma_f32_16x16x32_bf16 v[116:119], v[164:167], v[180:183], v[116:119]
	v_mfma_f32_16x16x32_bf16 v[116:119], v[168:171], v[184:187], v[116:119]
	v_mfma_f32_16x16x32_bf16 v[108:111], v[172:175], v[180:183], v[108:111]
	v_mfma_f32_16x16x32_bf16 v[108:111], v[176:179], v[184:187], v[108:111]
	v_mfma_f32_16x16x32_bf16 v[92:95], v[172:175], v[188:191], v[92:95]
	v_mfma_f32_16x16x32_bf16 v[92:95], v[176:179], v[192:195], v[92:95]
	v_mfma_f32_16x16x32_bf16 v[100:103], v[164:167], v[188:191], v[100:103]
	v_mfma_f32_16x16x32_bf16 v[100:103], v[168:171], v[192:195], v[100:103]
	v_mfma_f32_16x16x32_bf16 v[112:115], v[156:159], v[188:191], v[112:115]
	v_mfma_f32_16x16x32_bf16 v[112:115], v[160:163], v[192:195], v[112:115]
	v_mfma_f32_16x16x32_bf16 v[120:123], v[144:147], v[188:191], v[120:123]
	v_mfma_f32_16x16x32_bf16 v[120:123], v[152:155], v[192:195], v[120:123]
	v_mfma_f32_16x16x32_bf16 v[104:107], v[144:147], v[196:199], v[104:107]
	v_mfma_f32_16x16x32_bf16 v[104:107], v[152:155], v[200:203], v[104:107]
	v_mfma_f32_16x16x32_bf16 v[96:99], v[156:159], v[196:199], v[96:99]
	v_mfma_f32_16x16x32_bf16 v[96:99], v[160:163], v[200:203], v[96:99]
	v_mfma_f32_16x16x32_bf16 v[84:87], v[164:167], v[196:199], v[84:87]
	v_mfma_f32_16x16x32_bf16 v[84:87], v[168:171], v[200:203], v[84:87]
	v_mfma_f32_16x16x32_bf16 v[76:79], v[172:175], v[196:199], v[76:79]
	v_mfma_f32_16x16x32_bf16 v[76:79], v[176:179], v[200:203], v[76:79]
	v_mfma_f32_16x16x32_bf16 v[68:71], v[172:175], v[204:207], v[68:71]
	v_mfma_f32_16x16x32_bf16 v[68:71], v[176:179], v[208:211], v[68:71]
	v_mfma_f32_16x16x32_bf16 v[72:75], v[164:167], v[204:207], v[72:75]
	v_mfma_f32_16x16x32_bf16 v[72:75], v[168:171], v[208:211], v[72:75]
	v_mfma_f32_16x16x32_bf16 v[80:83], v[156:159], v[204:207], v[80:83]
	v_mfma_f32_16x16x32_bf16 v[80:83], v[160:163], v[208:211], v[80:83]
	v_mfma_f32_16x16x32_bf16 v[88:91], v[144:147], v[204:207], v[88:91]
	v_mfma_f32_16x16x32_bf16 v[88:91], v[152:155], v[208:211], v[88:91]
	s_barrier
	s_mov_b32 m0, s25
	v_lshl_add_u64 v[212:213], s[18:19], 0, v[136:137]
	s_add_u32 s52, s18, 0x100000
	ds_read_b128 v[180:183], v148 offset:16384
	s_nop 0
	ds_read_b128 v[184:187], v148 offset:17408
	s_nop 0
	ds_read_b128 v[188:191], v148 offset:18432
	s_nop 0
	ds_read_b128 v[192:195], v148 offset:19456
	s_nop 0
	ds_read_b128 v[196:199], v148 offset:20480
	s_nop 0
	ds_read_b128 v[200:203], v148 offset:21504
	s_nop 0
	ds_read_b128 v[204:207], v148 offset:22528
	s_nop 0
	ds_read_b128 v[208:211], v148 offset:23552
	global_load_lds_dwordx4 v[212:213], off
	v_lshl_add_u64 v[214:215], s[18:19], 0, v[132:133]
	s_mov_b32 m0, s26
	s_addc_u32 s53, s19, 0
	global_load_lds_dwordx4 v[214:215], off
	v_lshl_add_u64 v[216:217], s[52:53], 0, v[136:137]
	s_mov_b32 m0, s27
	v_lshl_add_u64 v[218:219], s[20:21], 0, v[134:135]
	global_load_lds_dwordx4 v[216:217], off
	v_lshl_add_u64 v[216:217], s[52:53], 0, v[132:133]
	s_mov_b32 m0, s30
	s_nop 0
	global_load_lds_dwordx4 v[216:217], off
	v_lshl_add_u64 v[216:217], s[20:21], 0, v[138:139]
	s_mov_b32 m0, s24
	s_nop 0
	global_load_lds_dwordx4 v[216:217], off
	s_mov_b32 m0, s31
	s_nop 0
	global_load_lds_dwordx4 v[218:219], off
	s_waitcnt vmcnt(8)
	s_waitcnt lgkmcnt(0)
	s_barrier
; #define PG8_STAGE(bufoff, gbase, voff) do { _Pragma("unroll") for (int _i = 0; _i < 2; ++_i) \
;         __builtin_amdgcn_global_load_lds((const unsigned*)((const char*)(gbase) + (voff)[_i]), (LAS unsigned*)(lds + (bufoff) + ldsw + _i * 8192), 16, 0, 0); } while (0)
; #define PG8_LDA(dst, b, h) do { _Pragma("unroll") for (int m = 0; m < 4; ++m) _Pragma("unroll") for (int k = 0; k < 2; ++k) dst[m][k] = *(const LAS bf16x8*)(pA + PG8_SA(b, h) + m * 2048 + k * 1024); } while (0)
; #define PG8_LDB(dst, b, h) do { _Pragma("unroll") for (int n = 0; n < 2; ++n) _Pragma("unroll") for (int k = 0; k < 2; ++k) dst[n][k] = *(const LAS bf16x8*)(pB + (PG8_SB(b, h) - 4 * HTB) + n * 2048 + k * 1024); } while (0)
; #define PG8_MMA(ai, bj, At, Bt) do { __builtin_amdgcn_s_setprio(1); _Pragma("unroll") for (int m = 0; m < 4; ++m) _Pragma("unroll") for (int n = 0; n < 2; ++n) _Pragma("unroll") for (int k = 0; k < 2; ++k) \
;         acc[ai][bj][m][n] = __builtin_amdgcn_mfma_f32_16x16x32_bf16(Bt[n][k], At[m][k], acc[ai][bj][m][n], 0, 0, 0); __builtin_amdgcn_s_setprio(0); } while (0)
; #define PG8_WAIT_V(n) asm volatile("s_waitcnt vmcnt(" #n ")" ::: "memory")
; #define PG8_WAIT_L(n) asm volatile("s_waitcnt lgkmcnt(" #n ")" ::: "memory")
; #define PG8_BAR __builtin_amdgcn_s_barrier()
; #define PG8_SCHED __builtin_amdgcn_sched_barrier(0)
; template <class Desc, class Epi, bool ALIGN_EPI>
; __device__ __forceinline__ void gemm_phase(LAS unsigned char* lds, const Desc& D, const Epi& E, int G, int c) {
;     ...
;             PG8_WAIT_V(8); PG8_WAIT_L(0); PG8_BAR; PG8_MMA(1, 0, At, B0); PG8_MMA(1, 1, At, B1); PG8_BAR; PG8_SCHED;
;             PG8_LDB(B0, 1, 0); PG8_LDB(B1, 1, 1); PG8_SCHED; PG8_LDA(At, 1, 0); PG8_STAGE(PG8_SA(0, 1), a2 + hstepA, voffA);
;             PG8_WAIT_V(8); PG8_WAIT_L(0); PG8_BAR; PG8_MMA(0, 0, At, B0); PG8_MMA(0, 1, At, B1); PG8_BAR; PG8_SCHED;
	v_mfma_f32_16x16x32_bf16 v[64:67], v[144:147], v[180:183], v[64:67]
	v_mfma_f32_16x16x32_bf16 v[64:67], v[152:155], v[184:187], v[64:67]
	v_mfma_f32_16x16x32_bf16 v[60:63], v[156:159], v[180:183], v[60:63]
	v_mfma_f32_16x16x32_bf16 v[60:63], v[160:163], v[184:187], v[60:63]
	v_mfma_f32_16x16x32_bf16 v[52:55], v[164:167], v[180:183], v[52:55]
	v_mfma_f32_16x16x32_bf16 v[52:55], v[168:171], v[184:187], v[52:55]
	v_mfma_f32_16x16x32_bf16 v[44:47], v[172:175], v[180:183], v[44:47]
	v_mfma_f32_16x16x32_bf16 v[44:47], v[176:179], v[184:187], v[44:47]
	v_mfma_f32_16x16x32_bf16 v[28:31], v[172:175], v[188:191], v[28:31]
	v_mfma_f32_16x16x32_bf16 v[28:31], v[176:179], v[192:195], v[28:31]
	v_mfma_f32_16x16x32_bf16 v[36:39], v[164:167], v[188:191], v[36:39]
	v_mfma_f32_16x16x32_bf16 v[36:39], v[168:171], v[192:195], v[36:39]
	v_mfma_f32_16x16x32_bf16 v[48:51], v[156:159], v[188:191], v[48:51]
	v_mfma_f32_16x16x32_bf16 v[48:51], v[160:163], v[192:195], v[48:51]
	v_mfma_f32_16x16x32_bf16 v[56:59], v[144:147], v[188:191], v[56:59]
	v_mfma_f32_16x16x32_bf16 v[56:59], v[152:155], v[192:195], v[56:59]
	v_mfma_f32_16x16x32_bf16 v[40:43], v[144:147], v[196:199], v[40:43]
	v_mfma_f32_16x16x32_bf16 v[40:43], v[152:155], v[200:203], v[40:43]
	v_mfma_f32_16x16x32_bf16 v[32:35], v[156:159], v[196:199], v[32:35]
	v_mfma_f32_16x16x32_bf16 v[32:35], v[160:163], v[200:203], v[32:35]
	v_mfma_f32_16x16x32_bf16 v[20:23], v[164:167], v[196:199], v[20:23]
	v_mfma_f32_16x16x32_bf16 v[20:23], v[168:171], v[200:203], v[20:23]
	v_mfma_f32_16x16x32_bf16 v[12:15], v[172:175], v[196:199], v[12:15]
	v_mfma_f32_16x16x32_bf16 v[12:15], v[176:179], v[200:203], v[12:15]
	v_mfma_f32_16x16x32_bf16 v[4:7], v[172:175], v[204:207], v[4:7]
	v_mfma_f32_16x16x32_bf16 v[4:7], v[176:179], v[208:211], v[4:7]
	v_mfma_f32_16x16x32_bf16 v[8:11], v[164:167], v[204:207], v[8:11]
	v_mfma_f32_16x16x32_bf16 v[8:11], v[168:171], v[208:211], v[8:11]
	v_mfma_f32_16x16x32_bf16 v[16:19], v[156:159], v[204:207], v[16:19]
	v_mfma_f32_16x16x32_bf16 v[16:19], v[160:163], v[208:211], v[16:19]
	v_mfma_f32_16x16x32_bf16 v[24:27], v[144:147], v[204:207], v[24:27]
	v_mfma_f32_16x16x32_bf16 v[24:27], v[152:155], v[208:211], v[24:27]
	s_barrier
	ds_read_b128 v[144:147], v149 offset:32768
	s_nop 0
	ds_read_b128 v[152:155], v149 offset:33792
	s_nop 0
	ds_read_b128 v[156:159], v149 offset:34816
	s_nop 0
	ds_read_b128 v[160:163], v149 offset:35840
	s_nop 0
	ds_read_b128 v[164:167], v149 offset:49152
	s_nop 0
	ds_read_b128 v[168:171], v149 offset:50176
	s_nop 0
	ds_read_b128 v[172:175], v149 offset:51200
	s_nop 0
	ds_read_b128 v[176:179], v149 offset:52224
	s_add_u32 s20, s20, 0x100000
	s_addc_u32 s21, s21, 0
	s_mov_b32 m0, s33
	v_lshl_add_u64 v[220:221], s[20:21], 0, v[138:139]
	ds_read_b128 v[180:183], v148 offset:32768
	s_nop 0
	ds_read_b128 v[184:187], v148 offset:33792
	s_nop 0
	ds_read_b128 v[188:191], v148 offset:34816
	s_nop 0
	ds_read_b128 v[192:195], v148 offset:35840
	s_nop 0
	ds_read_b128 v[196:199], v148 offset:36864
	s_nop 0
	ds_read_b128 v[200:203], v148 offset:37888
	s_nop 0
	ds_read_b128 v[204:207], v148 offset:38912
	s_nop 0
	ds_read_b128 v[208:211], v148 offset:39936
	global_load_lds_dwordx4 v[220:221], off
	v_lshl_add_u64 v[220:221], s[20:21], 0, v[134:135]
	s_mov_b32 m0, s34
	s_nop 0
	global_load_lds_dwordx4 v[220:221], off
	s_waitcnt vmcnt(8)
	s_waitcnt lgkmcnt(0)
	s_barrier
	v_mfma_f32_16x16x32_bf16 v[128:131], v[144:147], v[180:183], v[128:131]
	v_mfma_f32_16x16x32_bf16 v[128:131], v[152:155], v[184:187], v[128:131]
	v_mfma_f32_16x16x32_bf16 v[124:127], v[156:159], v[180:183], v[124:127]
	v_mfma_f32_16x16x32_bf16 v[124:127], v[160:163], v[184:187], v[124:127]
	v_mfma_f32_16x16x32_bf16 v[116:119], v[164:167], v[180:183], v[116:119]
	v_mfma_f32_16x16x32_bf16 v[116:119], v[168:171], v[184:187], v[116:119]
	v_mfma_f32_16x16x32_bf16 v[108:111], v[172:175], v[180:183], v[108:111]
	v_mfma_f32_16x16x32_bf16 v[108:111], v[176:179], v[184:187], v[108:111]
	v_mfma_f32_16x16x32_bf16 v[92:95], v[172:175], v[188:191], v[92:95]
	v_mfma_f32_16x16x32_bf16 v[92:95], v[176:179], v[192:195], v[92:95]
	v_mfma_f32_16x16x32_bf16 v[100:103], v[164:167], v[188:191], v[100:103]
	v_mfma_f32_16x16x32_bf16 v[100:103], v[168:171], v[192:195], v[100:103]
	v_mfma_f32_16x16x32_bf16 v[112:115], v[156:159], v[188:191], v[112:115]
	v_mfma_f32_16x16x32_bf16 v[112:115], v[160:163], v[192:195], v[112:115]
	v_mfma_f32_16x16x32_bf16 v[120:123], v[144:147], v[188:191], v[120:123]
	v_mfma_f32_16x16x32_bf16 v[120:123], v[152:155], v[192:195], v[120:123]
	v_mfma_f32_16x16x32_bf16 v[104:107], v[144:147], v[196:199], v[104:107]
	v_mfma_f32_16x16x32_bf16 v[104:107], v[152:155], v[200:203], v[104:107]
	v_mfma_f32_16x16x32_bf16 v[96:99], v[156:159], v[196:199], v[96:99]
	v_mfma_f32_16x16x32_bf16 v[96:99], v[160:163], v[200:203], v[96:99]
	v_mfma_f32_16x16x32_bf16 v[84:87], v[164:167], v[196:199], v[84:87]
	v_mfma_f32_16x16x32_bf16 v[84:87], v[168:171], v[200:203], v[84:87]
	v_mfma_f32_16x16x32_bf16 v[76:79], v[172:175], v[196:199], v[76:79]
	v_mfma_f32_16x16x32_bf16 v[76:79], v[176:179], v[200:203], v[76:79]
	v_mfma_f32_16x16x32_bf16 v[68:71], v[172:175], v[204:207], v[68:71]
	v_mfma_f32_16x16x32_bf16 v[68:71], v[176:179], v[208:211], v[68:71]
	v_mfma_f32_16x16x32_bf16 v[72:75], v[164:167], v[204:207], v[72:75]
	v_mfma_f32_16x16x32_bf16 v[72:75], v[168:171], v[208:211], v[72:75]
	v_mfma_f32_16x16x32_bf16 v[80:83], v[156:159], v[204:207], v[80:83]
	v_mfma_f32_16x16x32_bf16 v[80:83], v[160:163], v[208:211], v[80:83]
	v_mfma_f32_16x16x32_bf16 v[88:91], v[144:147], v[204:207], v[88:91]
	v_mfma_f32_16x16x32_bf16 v[88:91], v[152:155], v[208:211], v[88:91]
	s_barrier
; #define PG8_STAGE(bufoff, gbase, voff) do { _Pragma("unroll") for (int _i = 0; _i < 2; ++_i) \
;         __builtin_amdgcn_global_load_lds((const unsigned*)((const char*)(gbase) + (voff)[_i]), (LAS unsigned*)(lds + (bufoff) + ldsw + _i * 8192), 16, 0, 0); } while (0)
; #define PG8_LDA(dst, b, h) do { _Pragma("unroll") for (int m = 0; m < 4; ++m) _Pragma("unroll") for (int k = 0; k < 2; ++k) dst[m][k] = *(const LAS bf16x8*)(pA + PG8_SA(b, h) + m * 2048 + k * 1024); } while (0)
; #define PG8_MMA(ai, bj, At, Bt) do { __builtin_amdgcn_s_setprio(1); _Pragma("unroll") for (int m = 0; m < 4; ++m) _Pragma("unroll") for (int n = 0; n < 2; ++n) _Pragma("unroll") for (int k = 0; k < 2; ++k) \
;         acc[ai][bj][m][n] = __builtin_amdgcn_mfma_f32_16x16x32_bf16(Bt[n][k], At[m][k], acc[ai][bj][m][n], 0, 0, 0); __builtin_amdgcn_s_setprio(0); } while (0)
; #define PG8_WAIT_V(n) asm volatile("s_waitcnt vmcnt(" #n ")" ::: "memory")
; #define PG8_WAIT_L(n) asm volatile("s_waitcnt lgkmcnt(" #n ")" ::: "memory")
; #define PG8_BAR __builtin_amdgcn_s_barrier()
; #define PG8_SCHED __builtin_amdgcn_sched_barrier(0)
; template <class Desc, class Epi, bool ALIGN_EPI>
; __device__ __forceinline__ void gemm_phase(LAS unsigned char* lds, const Desc& D, const Epi& E, int G, int c) {
;     ...
;             PG8_LDA(At, 1, 1); PG8_STAGE(PG8_SB(1, 0), b3, voffB); PG8_STAGE(PG8_SB(1, 1), b3 + hstepB, voffB); PG8_STAGE(PG8_SA(1, 0), a3, voffA);
;             PG8_WAIT_V(8); PG8_WAIT_L(0); PG8_BAR; PG8_MMA(1, 0, At, B0); PG8_MMA(1, 1, At, B1); PG8_BAR; PG8_SCHED;
;         }
;         if constexpr (ALIGN_EPI) { if (wr == 0) PG8_BAR; }
	s_mov_b32 m0, s35
	v_lshl_add_u64 v[212:213], v[212:213], 0, s[76:77]
	s_add_u32 s18, s18, 0x100080
	ds_read_b128 v[180:183], v148 offset:49152
	s_nop 0
	ds_read_b128 v[184:187], v148 offset:50176
	s_nop 0
	ds_read_b128 v[188:191], v148 offset:51200
	s_nop 0
	ds_read_b128 v[192:195], v148 offset:52224
	s_nop 0
	ds_read_b128 v[196:199], v148 offset:53248
	s_nop 0
	ds_read_b128 v[200:203], v148 offset:54272
	s_nop 0
	ds_read_b128 v[204:207], v148 offset:55296
	s_nop 0
	ds_read_b128 v[208:211], v148 offset:56320
	global_load_lds_dwordx4 v[212:213], off
	v_lshl_add_u64 v[212:213], v[214:215], 0, s[76:77]
	s_mov_b32 m0, s38
	s_addc_u32 s19, s19, 0
	global_load_lds_dwordx4 v[212:213], off
	v_lshl_add_u64 v[212:213], s[18:19], 0, v[136:137]
	s_mov_b32 m0, s41
	s_nop 0
	global_load_lds_dwordx4 v[212:213], off
	v_lshl_add_u64 v[212:213], s[18:19], 0, v[132:133]
	s_mov_b32 m0, s42
	s_nop 0
	global_load_lds_dwordx4 v[212:213], off
	v_lshl_add_u64 v[212:213], v[216:217], 0, s[76:77]
	s_mov_b32 m0, s39
	s_nop 0
	global_load_lds_dwordx4 v[212:213], off
	v_lshl_add_u64 v[212:213], v[218:219], 0, s[76:77]
	s_mov_b32 m0, s40
	s_nop 0
	global_load_lds_dwordx4 v[212:213], off
	s_waitcnt vmcnt(8)
	s_waitcnt lgkmcnt(0)
	s_barrier
	v_mfma_f32_16x16x32_bf16 v[64:67], v[144:147], v[180:183], v[64:67]
	v_mfma_f32_16x16x32_bf16 v[64:67], v[152:155], v[184:187], v[64:67]
	v_mfma_f32_16x16x32_bf16 v[60:63], v[156:159], v[180:183], v[60:63]
	v_mfma_f32_16x16x32_bf16 v[60:63], v[160:163], v[184:187], v[60:63]
	v_mfma_f32_16x16x32_bf16 v[52:55], v[164:167], v[180:183], v[52:55]
	v_mfma_f32_16x16x32_bf16 v[52:55], v[168:171], v[184:187], v[52:55]
	v_mfma_f32_16x16x32_bf16 v[44:47], v[172:175], v[180:183], v[44:47]
	v_mfma_f32_16x16x32_bf16 v[44:47], v[176:179], v[184:187], v[44:47]
	v_mfma_f32_16x16x32_bf16 v[28:31], v[172:175], v[188:191], v[28:31]
	v_mfma_f32_16x16x32_bf16 v[28:31], v[176:179], v[192:195], v[28:31]
	v_mfma_f32_16x16x32_bf16 v[36:39], v[164:167], v[188:191], v[36:39]
	v_mfma_f32_16x16x32_bf16 v[36:39], v[168:171], v[192:195], v[36:39]
	v_mfma_f32_16x16x32_bf16 v[48:51], v[156:159], v[188:191], v[48:51]
	v_mfma_f32_16x16x32_bf16 v[48:51], v[160:163], v[192:195], v[48:51]
	v_mfma_f32_16x16x32_bf16 v[56:59], v[144:147], v[188:191], v[56:59]
	v_mfma_f32_16x16x32_bf16 v[56:59], v[152:155], v[192:195], v[56:59]
	v_mfma_f32_16x16x32_bf16 v[40:43], v[144:147], v[196:199], v[40:43]
	v_mfma_f32_16x16x32_bf16 v[40:43], v[152:155], v[200:203], v[40:43]
	v_mfma_f32_16x16x32_bf16 v[32:35], v[156:159], v[196:199], v[32:35]
	v_mfma_f32_16x16x32_bf16 v[32:35], v[160:163], v[200:203], v[32:35]
	v_mfma_f32_16x16x32_bf16 v[20:23], v[164:167], v[196:199], v[20:23]
	v_mfma_f32_16x16x32_bf16 v[20:23], v[168:171], v[200:203], v[20:23]
	v_mfma_f32_16x16x32_bf16 v[12:15], v[172:175], v[196:199], v[12:15]
	v_mfma_f32_16x16x32_bf16 v[12:15], v[176:179], v[200:203], v[12:15]
	v_mfma_f32_16x16x32_bf16 v[4:7], v[172:175], v[204:207], v[4:7]
	v_mfma_f32_16x16x32_bf16 v[4:7], v[176:179], v[208:211], v[4:7]
	v_mfma_f32_16x16x32_bf16 v[8:11], v[164:167], v[204:207], v[8:11]
	v_mfma_f32_16x16x32_bf16 v[8:11], v[168:171], v[208:211], v[8:11]
	v_mfma_f32_16x16x32_bf16 v[16:19], v[156:159], v[204:207], v[16:19]
	v_mfma_f32_16x16x32_bf16 v[16:19], v[160:163], v[208:211], v[16:19]
	v_mfma_f32_16x16x32_bf16 v[24:27], v[144:147], v[204:207], v[24:27]
	v_mfma_f32_16x16x32_bf16 v[24:27], v[152:155], v[208:211], v[24:27]
	s_barrier
	s_add_u32 s16, s16, 0x100
	s_addc_u32 s17, s17, 0
	s_add_u32 s48, s48, 0x100
	s_addc_u32 s49, s49, 0
	s_cmp_ge_u32 s50, s46
	s_mov_b32 s18, s50
	s_cbranch_scc0 .LBB0_1324
	s_and_b64 vcc, exec, s[6:7]
	s_cbranch_vccz .LBB0_1327
	s_barrier

;     __device__ __forceinline__ int nt(const Unit& u) const { return (u.pn >> 1) < 2 ? 22 : 20; }
; #define PG8_STAGE(bufoff, gbase, voff) do { _Pragma("unroll") for (int _i = 0; _i < 2; ++_i) \
;         __builtin_amdgcn_global_load_lds((const unsigned*)((const char*)(gbase) + (voff)[_i]), (LAS unsigned*)(lds + (bufoff) + ldsw + _i * 8192), 16, 0, 0); } while (0)
; #define PG8_LDA(dst, b, h) do { _Pragma("unroll") for (int m = 0; m < 4; ++m) _Pragma("unroll") for (int k = 0; k < 2; ++k) dst[m][k] = *(const LAS bf16x8*)(pA + PG8_SA(b, h) + m * 2048 + k * 1024); } while (0)
; #define PG8_LDB(dst, b, h) do { _Pragma("unroll") for (int n = 0; n < 2; ++n) _Pragma("unroll") for (int k = 0; k < 2; ++k) dst[n][k] = *(const LAS bf16x8*)(pB + (PG8_SB(b, h) - 4 * HTB) + n * 2048 + k * 1024); } while (0)
; #define PG8_MMA(ai, bj, At, Bt) do { __builtin_amdgcn_s_setprio(1); _Pragma("unroll") for (int m = 0; m < 4; ++m) _Pragma("unroll") for (int n = 0; n < 2; ++n) _Pragma("unroll") for (int k = 0; k < 2; ++k) \
;         acc[ai][bj][m][n] = __builtin_amdgcn_mfma_f32_16x16x32_bf16(Bt[n][k], At[m][k], acc[ai][bj][m][n], 0, 0, 0); __builtin_amdgcn_s_setprio(0); } while (0)
; #define PG8_WAIT_V(n) asm volatile("s_waitcnt vmcnt(" #n ")" ::: "memory")
; #define PG8_BAR __builtin_amdgcn_s_barrier()
; template <class Desc, class Epi, bool ALIGN_EPI>
; __device__ __forceinline__ void gemm_phase(LAS unsigned char* lds, const Desc& D, const Epi& E, int G, int c) {
;     ...
;         for (int t = 0; t < nt; t += 2) {
;             const bool last = (t == nt - 2);
;             if (last && has_next) PG8_AWAIT(nxt);
;             const char* a1 = cA + (size_t)(t + 1) * kstep;
;             const char* a2 = last ? nA : cA + (size_t)(t + 2) * kstep; const char* b2 = last ? nB : cB + (size_t)(t + 2) * kstep;
;             const char* a3 = a2 + kstep; const char* b3 = b2 + kstep;
;             PG8_LDB(B0, 0, 0); PG8_LDB(B1, 0, 1); PG8_SCHED; PG8_LDA(At, 0, 0); PG8_STAGE(PG8_SA(1, 1), a1 + hstepA, voffA);
;             PG8_WAIT_V(8); PG8_WAIT_L(0); PG8_BAR; PG8_MMA(0, 0, At, B0); PG8_MMA(0, 1, At, B1); PG8_BAR; PG8_SCHED;
;             PG8_LDA(At, 0, 1); PG8_STAGE(PG8_SB(0, 0), b2, voffB); PG8_STAGE(PG8_SB(0, 1), b2 + hstepB, voffB); PG8_STAGE(PG8_SA(0, 0), a2, voffA);
;             PG8_WAIT_V(8); PG8_WAIT_L(0); PG8_BAR; PG8_MMA(1, 0, At, B0); PG8_MMA(1, 1, At, B1); PG8_BAR; PG8_SCHED;
.LBB0_1479:
	ds_read_b128 v[116:119], v225
	s_nop 0
	ds_read_b128 v[128:131], v225 offset:1024
	s_nop 0
	ds_read_b128 v[132:135], v225 offset:2048
	s_nop 0
	ds_read_b128 v[136:139], v225 offset:3072
	s_nop 0
	ds_read_b128 v[140:143], v225 offset:16384
	s_nop 0
	ds_read_b128 v[144:147], v225 offset:17408
	s_nop 0
	ds_read_b128 v[148:151], v225 offset:18432
	s_nop 0
	ds_read_b128 v[152:155], v225 offset:19456
	s_add_u32 s12, s0, 0xfffe0080
	s_addc_u32 s13, s1, -1
	s_cmp_eq_u32 s52, 4
	s_cselect_b32 s17, s37, s13
	s_cselect_b32 s16, s36, s12
	s_cselect_b32 s13, s21, s33
	s_cselect_b32 s12, s24, s27
	v_lshl_add_u64 v[208:209], s[0:1], 0, v[200:201]
	s_add_i32 m0, s31, 0xc000
	ds_read_b128 v[164:167], v224
	s_nop 0
	ds_read_b128 v[168:171], v224 offset:1024
	s_nop 0
	ds_read_b128 v[172:175], v224 offset:2048
	s_nop 0
	ds_read_b128 v[176:179], v224 offset:3072
	s_nop 0
	ds_read_b128 v[180:183], v224 offset:4096
	s_nop 0
	ds_read_b128 v[184:187], v224 offset:5120
	s_nop 0
	ds_read_b128 v[188:191], v224 offset:6144
	s_nop 0
	ds_read_b128 v[204:207], v224 offset:7168
	global_load_lds_dwordx4 v[208:209], off
	v_lshl_add_u64 v[208:209], s[0:1], 0, v[202:203]
	s_add_i32 m0, s31, 0xe000
	s_nop 0
	global_load_lds_dwordx4 v[208:209], off
	s_waitcnt vmcnt(8)
	s_waitcnt lgkmcnt(0)
	s_barrier
	v_mfma_f32_16x16x32_bf16 v[160:163], v[116:119], v[164:167], v[160:163]
	v_mfma_f32_16x16x32_bf16 v[160:163], v[128:131], v[168:171], v[160:163]
	v_mfma_f32_16x16x32_bf16 v[156:159], v[132:135], v[164:167], v[156:159]
	v_mfma_f32_16x16x32_bf16 v[156:159], v[136:139], v[168:171], v[156:159]
	v_mfma_f32_16x16x32_bf16 v[124:127], v[140:143], v[164:167], v[124:127]
	v_mfma_f32_16x16x32_bf16 v[124:127], v[144:147], v[168:171], v[124:127]
	v_mfma_f32_16x16x32_bf16 v[120:123], v[148:151], v[164:167], v[120:123]
	v_mfma_f32_16x16x32_bf16 v[120:123], v[152:155], v[168:171], v[120:123]
	v_mfma_f32_16x16x32_bf16 v[100:103], v[148:151], v[172:175], v[100:103]
	v_mfma_f32_16x16x32_bf16 v[100:103], v[152:155], v[176:179], v[100:103]
	v_mfma_f32_16x16x32_bf16 v[104:107], v[140:143], v[172:175], v[104:107]
	v_mfma_f32_16x16x32_bf16 v[104:107], v[144:147], v[176:179], v[104:107]
	v_mfma_f32_16x16x32_bf16 v[108:111], v[132:135], v[172:175], v[108:111]
	v_mfma_f32_16x16x32_bf16 v[108:111], v[136:139], v[176:179], v[108:111]
	v_mfma_f32_16x16x32_bf16 v[112:115], v[116:119], v[172:175], v[112:115]
	v_mfma_f32_16x16x32_bf16 v[112:115], v[128:131], v[176:179], v[112:115]
	v_mfma_f32_16x16x32_bf16 v[96:99], v[116:119], v[180:183], v[96:99]
	v_mfma_f32_16x16x32_bf16 v[96:99], v[128:131], v[184:187], v[96:99]
	v_mfma_f32_16x16x32_bf16 v[92:95], v[132:135], v[180:183], v[92:95]
	v_mfma_f32_16x16x32_bf16 v[92:95], v[136:139], v[184:187], v[92:95]
	v_mfma_f32_16x16x32_bf16 v[88:91], v[140:143], v[180:183], v[88:91]
	v_mfma_f32_16x16x32_bf16 v[88:91], v[144:147], v[184:187], v[88:91]
	v_mfma_f32_16x16x32_bf16 v[84:87], v[148:151], v[180:183], v[84:87]
	v_mfma_f32_16x16x32_bf16 v[84:87], v[152:155], v[184:187], v[84:87]
	v_mfma_f32_16x16x32_bf16 v[68:71], v[148:151], v[188:191], v[68:71]
	v_mfma_f32_16x16x32_bf16 v[68:71], v[152:155], v[204:207], v[68:71]
	v_mfma_f32_16x16x32_bf16 v[72:75], v[140:143], v[188:191], v[72:75]
	v_mfma_f32_16x16x32_bf16 v[72:75], v[144:147], v[204:207], v[72:75]
	v_mfma_f32_16x16x32_bf16 v[76:79], v[132:135], v[188:191], v[76:79]
	v_mfma_f32_16x16x32_bf16 v[76:79], v[136:139], v[204:207], v[76:79]
	v_mfma_f32_16x16x32_bf16 v[80:83], v[116:119], v[188:191], v[80:83]
	v_mfma_f32_16x16x32_bf16 v[80:83], v[128:131], v[204:207], v[80:83]
	s_barrier
	s_mov_b32 m0, s34
	v_lshl_add_u64 v[208:209], s[12:13], 0, v[196:197]
	s_add_u32 s54, s12, 0x20000
	ds_read_b128 v[164:167], v224 offset:16384
	s_nop 0
	ds_read_b128 v[168:171], v224 offset:17408
	s_nop 0
	ds_read_b128 v[172:175], v224 offset:18432
	s_nop 0
	ds_read_b128 v[176:179], v224 offset:19456
	s_nop 0
	ds_read_b128 v[180:183], v224 offset:20480
	s_nop 0
	ds_read_b128 v[184:187], v224 offset:21504
	s_nop 0
	ds_read_b128 v[188:191], v224 offset:22528
	s_nop 0
	ds_read_b128 v[204:207], v224 offset:23552
	global_load_lds_dwordx4 v[208:209], off
	v_lshl_add_u64 v[210:211], s[12:13], 0, v[192:193]
	s_mov_b32 m0, s35
	s_addc_u32 s55, s13, 0
	global_load_lds_dwordx4 v[210:211], off
	v_lshl_add_u64 v[212:213], s[54:55], 0, v[196:197]
	s_mov_b32 m0, s40
	v_lshl_add_u64 v[214:215], s[16:17], 0, v[194:195]
	global_load_lds_dwordx4 v[212:213], off
	v_lshl_add_u64 v[212:213], s[54:55], 0, v[192:193]
	s_mov_b32 m0, s41
	s_nop 0
	global_load_lds_dwordx4 v[212:213], off
	v_lshl_add_u64 v[212:213], s[16:17], 0, v[198:199]
	s_mov_b32 m0, s31
	s_nop 0
	global_load_lds_dwordx4 v[212:213], off
	s_mov_b32 m0, s42
	s_nop 0
	global_load_lds_dwordx4 v[214:215], off
	s_waitcnt vmcnt(8)
	s_waitcnt lgkmcnt(0)
	s_barrier
; #define PG8_STAGE(bufoff, gbase, voff) do { _Pragma("unroll") for (int _i = 0; _i < 2; ++_i) \
;         __builtin_amdgcn_global_load_lds((const unsigned*)((const char*)(gbase) + (voff)[_i]), (LAS unsigned*)(lds + (bufoff) + ldsw + _i * 8192), 16, 0, 0); } while (0)
; #define PG8_LDA(dst, b, h) do { _Pragma("unroll") for (int m = 0; m < 4; ++m) _Pragma("unroll") for (int k = 0; k < 2; ++k) dst[m][k] = *(const LAS bf16x8*)(pA + PG8_SA(b, h) + m * 2048 + k * 1024); } while (0)
; #define PG8_LDB(dst, b, h) do { _Pragma("unroll") for (int n = 0; n < 2; ++n) _Pragma("unroll") for (int k = 0; k < 2; ++k) dst[n][k] = *(const LAS bf16x8*)(pB + (PG8_SB(b, h) - 4 * HTB) + n * 2048 + k * 1024); } while (0)
; #define PG8_MMA(ai, bj, At, Bt) do { __builtin_amdgcn_s_setprio(1); _Pragma("unroll") for (int m = 0; m < 4; ++m) _Pragma("unroll") for (int n = 0; n < 2; ++n) _Pragma("unroll") for (int k = 0; k < 2; ++k) \
;         acc[ai][bj][m][n] = __builtin_amdgcn_mfma_f32_16x16x32_bf16(Bt[n][k], At[m][k], acc[ai][bj][m][n], 0, 0, 0); __builtin_amdgcn_s_setprio(0); } while (0)
; #define PG8_WAIT_V(n) asm volatile("s_waitcnt vmcnt(" #n ")" ::: "memory")
; #define PG8_WAIT_L(n) asm volatile("s_waitcnt lgkmcnt(" #n ")" ::: "memory")
; #define PG8_BAR __builtin_amdgcn_s_barrier()
; #define PG8_SCHED __builtin_amdgcn_sched_barrier(0)
; template <class Desc, class Epi, bool ALIGN_EPI>
; __device__ __forceinline__ void gemm_phase(LAS unsigned char* lds, const Desc& D, const Epi& E, int G, int c) {
;     ...
;             PG8_WAIT_V(8); PG8_WAIT_L(0); PG8_BAR; PG8_MMA(1, 0, At, B0); PG8_MMA(1, 1, At, B1); PG8_BAR; PG8_SCHED;
;             PG8_LDB(B0, 1, 0); PG8_LDB(B1, 1, 1); PG8_SCHED; PG8_LDA(At, 1, 0); PG8_STAGE(PG8_SA(0, 1), a2 + hstepA, voffA);
;             PG8_WAIT_V(8); PG8_WAIT_L(0); PG8_BAR; PG8_MMA(0, 0, At, B0); PG8_MMA(0, 1, At, B1); PG8_BAR; PG8_SCHED;
	v_mfma_f32_16x16x32_bf16 v[64:67], v[116:119], v[164:167], v[64:67]
	v_mfma_f32_16x16x32_bf16 v[64:67], v[128:131], v[168:171], v[64:67]
	v_mfma_f32_16x16x32_bf16 v[60:63], v[132:135], v[164:167], v[60:63]
	v_mfma_f32_16x16x32_bf16 v[60:63], v[136:139], v[168:171], v[60:63]
	v_mfma_f32_16x16x32_bf16 v[56:59], v[140:143], v[164:167], v[56:59]
	v_mfma_f32_16x16x32_bf16 v[56:59], v[144:147], v[168:171], v[56:59]
	v_mfma_f32_16x16x32_bf16 v[52:55], v[148:151], v[164:167], v[52:55]
	v_mfma_f32_16x16x32_bf16 v[52:55], v[152:155], v[168:171], v[52:55]
	v_mfma_f32_16x16x32_bf16 v[36:39], v[148:151], v[172:175], v[36:39]
	v_mfma_f32_16x16x32_bf16 v[36:39], v[152:155], v[176:179], v[36:39]
	v_mfma_f32_16x16x32_bf16 v[40:43], v[140:143], v[172:175], v[40:43]
	v_mfma_f32_16x16x32_bf16 v[40:43], v[144:147], v[176:179], v[40:43]
	v_mfma_f32_16x16x32_bf16 v[44:47], v[132:135], v[172:175], v[44:47]
	v_mfma_f32_16x16x32_bf16 v[44:47], v[136:139], v[176:179], v[44:47]
	v_mfma_f32_16x16x32_bf16 v[48:51], v[116:119], v[172:175], v[48:51]
	v_mfma_f32_16x16x32_bf16 v[48:51], v[128:131], v[176:179], v[48:51]
	v_mfma_f32_16x16x32_bf16 v[32:35], v[116:119], v[180:183], v[32:35]
	v_mfma_f32_16x16x32_bf16 v[32:35], v[128:131], v[184:187], v[32:35]
	v_mfma_f32_16x16x32_bf16 v[28:31], v[132:135], v[180:183], v[28:31]
	v_mfma_f32_16x16x32_bf16 v[28:31], v[136:139], v[184:187], v[28:31]
	v_mfma_f32_16x16x32_bf16 v[24:27], v[140:143], v[180:183], v[24:27]
	v_mfma_f32_16x16x32_bf16 v[24:27], v[144:147], v[184:187], v[24:27]
	v_mfma_f32_16x16x32_bf16 v[20:23], v[148:151], v[180:183], v[20:23]
	v_mfma_f32_16x16x32_bf16 v[20:23], v[152:155], v[184:187], v[20:23]
	v_mfma_f32_16x16x32_bf16 v[4:7], v[148:151], v[188:191], v[4:7]
	v_mfma_f32_16x16x32_bf16 v[4:7], v[152:155], v[204:207], v[4:7]
	v_mfma_f32_16x16x32_bf16 v[8:11], v[140:143], v[188:191], v[8:11]
	v_mfma_f32_16x16x32_bf16 v[8:11], v[144:147], v[204:207], v[8:11]
	v_mfma_f32_16x16x32_bf16 v[12:15], v[132:135], v[188:191], v[12:15]
	v_mfma_f32_16x16x32_bf16 v[12:15], v[136:139], v[204:207], v[12:15]
	v_mfma_f32_16x16x32_bf16 v[16:19], v[116:119], v[188:191], v[16:19]
	v_mfma_f32_16x16x32_bf16 v[16:19], v[128:131], v[204:207], v[16:19]
	s_barrier
	ds_read_b128 v[116:119], v225 offset:32768
	s_nop 0
	ds_read_b128 v[128:131], v225 offset:33792
	s_nop 0
	ds_read_b128 v[132:135], v225 offset:34816
	s_nop 0
	ds_read_b128 v[136:139], v225 offset:35840
	s_nop 0
	ds_read_b128 v[140:143], v225 offset:49152
	s_nop 0
	ds_read_b128 v[144:147], v225 offset:50176
	s_nop 0
	ds_read_b128 v[148:151], v225 offset:51200
	s_nop 0
	ds_read_b128 v[152:155], v225 offset:52224
	s_add_u32 s16, s16, 0x20000
	s_addc_u32 s17, s17, 0
	s_mov_b32 m0, s43
	v_lshl_add_u64 v[216:217], s[16:17], 0, v[198:199]
	ds_read_b128 v[164:167], v224 offset:32768
	s_nop 0
	ds_read_b128 v[168:171], v224 offset:33792
	s_nop 0
	ds_read_b128 v[172:175], v224 offset:34816
	s_nop 0
	ds_read_b128 v[176:179], v224 offset:35840
	s_nop 0
	ds_read_b128 v[180:183], v224 offset:36864
	s_nop 0
	ds_read_b128 v[184:187], v224 offset:37888
	s_nop 0
	ds_read_b128 v[188:191], v224 offset:38912
	s_nop 0
	ds_read_b128 v[204:207], v224 offset:39936
	global_load_lds_dwordx4 v[216:217], off
	v_lshl_add_u64 v[216:217], s[16:17], 0, v[194:195]
	s_mov_b32 m0, s44
	s_nop 0
	global_load_lds_dwordx4 v[216:217], off
	s_waitcnt vmcnt(8)
	s_waitcnt lgkmcnt(0)
	s_barrier
	v_mfma_f32_16x16x32_bf16 v[160:163], v[116:119], v[164:167], v[160:163]
	v_mfma_f32_16x16x32_bf16 v[160:163], v[128:131], v[168:171], v[160:163]
	v_mfma_f32_16x16x32_bf16 v[156:159], v[132:135], v[164:167], v[156:159]
	v_mfma_f32_16x16x32_bf16 v[156:159], v[136:139], v[168:171], v[156:159]
	v_mfma_f32_16x16x32_bf16 v[124:127], v[140:143], v[164:167], v[124:127]
	v_mfma_f32_16x16x32_bf16 v[124:127], v[144:147], v[168:171], v[124:127]
	v_mfma_f32_16x16x32_bf16 v[120:123], v[148:151], v[164:167], v[120:123]
	v_mfma_f32_16x16x32_bf16 v[120:123], v[152:155], v[168:171], v[120:123]
	v_mfma_f32_16x16x32_bf16 v[100:103], v[148:151], v[172:175], v[100:103]
	v_mfma_f32_16x16x32_bf16 v[100:103], v[152:155], v[176:179], v[100:103]
	v_mfma_f32_16x16x32_bf16 v[104:107], v[140:143], v[172:175], v[104:107]
	v_mfma_f32_16x16x32_bf16 v[104:107], v[144:147], v[176:179], v[104:107]
	v_mfma_f32_16x16x32_bf16 v[108:111], v[132:135], v[172:175], v[108:111]
	v_mfma_f32_16x16x32_bf16 v[108:111], v[136:139], v[176:179], v[108:111]
	v_mfma_f32_16x16x32_bf16 v[112:115], v[116:119], v[172:175], v[112:115]
	v_mfma_f32_16x16x32_bf16 v[112:115], v[128:131], v[176:179], v[112:115]
	v_mfma_f32_16x16x32_bf16 v[96:99], v[116:119], v[180:183], v[96:99]
	v_mfma_f32_16x16x32_bf16 v[96:99], v[128:131], v[184:187], v[96:99]
	v_mfma_f32_16x16x32_bf16 v[92:95], v[132:135], v[180:183], v[92:95]
	v_mfma_f32_16x16x32_bf16 v[92:95], v[136:139], v[184:187], v[92:95]
	v_mfma_f32_16x16x32_bf16 v[88:91], v[140:143], v[180:183], v[88:91]
	v_mfma_f32_16x16x32_bf16 v[88:91], v[144:147], v[184:187], v[88:91]
	v_mfma_f32_16x16x32_bf16 v[84:87], v[148:151], v[180:183], v[84:87]
	v_mfma_f32_16x16x32_bf16 v[84:87], v[152:155], v[184:187], v[84:87]
	v_mfma_f32_16x16x32_bf16 v[68:71], v[148:151], v[188:191], v[68:71]
	v_mfma_f32_16x16x32_bf16 v[68:71], v[152:155], v[204:207], v[68:71]
	v_mfma_f32_16x16x32_bf16 v[72:75], v[140:143], v[188:191], v[72:75]
	v_mfma_f32_16x16x32_bf16 v[72:75], v[144:147], v[204:207], v[72:75]
	v_mfma_f32_16x16x32_bf16 v[76:79], v[132:135], v[188:191], v[76:79]
	v_mfma_f32_16x16x32_bf16 v[76:79], v[136:139], v[204:207], v[76:79]
	v_mfma_f32_16x16x32_bf16 v[80:83], v[116:119], v[188:191], v[80:83]
	v_mfma_f32_16x16x32_bf16 v[80:83], v[128:131], v[204:207], v[80:83]
	s_barrier
; #define PG8_STAGE(bufoff, gbase, voff) do { _Pragma("unroll") for (int _i = 0; _i < 2; ++_i) \
;         __builtin_amdgcn_global_load_lds((const unsigned*)((const char*)(gbase) + (voff)[_i]), (LAS unsigned*)(lds + (bufoff) + ldsw + _i * 8192), 16, 0, 0); } while (0)
; #define PG8_LDA(dst, b, h) do { _Pragma("unroll") for (int m = 0; m < 4; ++m) _Pragma("unroll") for (int k = 0; k < 2; ++k) dst[m][k] = *(const LAS bf16x8*)(pA + PG8_SA(b, h) + m * 2048 + k * 1024); } while (0)
; #define PG8_MMA(ai, bj, At, Bt) do { __builtin_amdgcn_s_setprio(1); _Pragma("unroll") for (int m = 0; m < 4; ++m) _Pragma("unroll") for (int n = 0; n < 2; ++n) _Pragma("unroll") for (int k = 0; k < 2; ++k) \
;         acc[ai][bj][m][n] = __builtin_amdgcn_mfma_f32_16x16x32_bf16(Bt[n][k], At[m][k], acc[ai][bj][m][n], 0, 0, 0); __builtin_amdgcn_s_setprio(0); } while (0)
; #define PG8_WAIT_V(n) asm volatile("s_waitcnt vmcnt(" #n ")" ::: "memory")
; #define PG8_WAIT_L(n) asm volatile("s_waitcnt lgkmcnt(" #n ")" ::: "memory")
; #define PG8_BAR __builtin_amdgcn_s_barrier()
; #define PG8_SCHED __builtin_amdgcn_sched_barrier(0)
; template <class Desc, class Epi, bool ALIGN_EPI>
; __device__ __forceinline__ void gemm_phase(LAS unsigned char* lds, const Desc& D, const Epi& E, int G, int c) {
;     ...
;             PG8_LDA(At, 1, 1); PG8_STAGE(PG8_SB(1, 0), b3, voffB); PG8_STAGE(PG8_SB(1, 1), b3 + hstepB, voffB); PG8_STAGE(PG8_SA(1, 0), a3, voffA);
;             PG8_WAIT_V(8); PG8_WAIT_L(0); PG8_BAR; PG8_MMA(1, 0, At, B0); PG8_MMA(1, 1, At, B1); PG8_BAR; PG8_SCHED;
;         }
;         if constexpr (ALIGN_EPI) { if (wr == 0) PG8_BAR; }
	s_mov_b32 m0, s45
	v_lshl_add_u64 v[208:209], v[208:209], 0, s[76:77]
	s_add_u32 s12, s12, 0x20080
	ds_read_b128 v[164:167], v224 offset:49152
	s_nop 0
	ds_read_b128 v[168:171], v224 offset:50176
	s_nop 0
	ds_read_b128 v[172:175], v224 offset:51200
	s_nop 0
	ds_read_b128 v[176:179], v224 offset:52224
	s_nop 0
	ds_read_b128 v[180:183], v224 offset:53248
	s_nop 0
	ds_read_b128 v[184:187], v224 offset:54272
	s_nop 0
	ds_read_b128 v[188:191], v224 offset:55296
	s_nop 0
	ds_read_b128 v[204:207], v224 offset:56320
	global_load_lds_dwordx4 v[208:209], off
	v_lshl_add_u64 v[208:209], v[210:211], 0, s[76:77]
	s_mov_b32 m0, s46
	s_addc_u32 s13, s13, 0
	global_load_lds_dwordx4 v[208:209], off
	v_lshl_add_u64 v[208:209], s[12:13], 0, v[196:197]
	s_mov_b32 m0, s49
	s_nop 0
	global_load_lds_dwordx4 v[208:209], off
	v_lshl_add_u64 v[208:209], s[12:13], 0, v[192:193]
	s_mov_b32 m0, s50
	s_nop 0
	global_load_lds_dwordx4 v[208:209], off
	v_lshl_add_u64 v[208:209], v[212:213], 0, s[76:77]
	s_mov_b32 m0, s47
	s_nop 0
	global_load_lds_dwordx4 v[208:209], off
	v_lshl_add_u64 v[208:209], v[214:215], 0, s[76:77]
	s_mov_b32 m0, s48
	s_nop 0
	global_load_lds_dwordx4 v[208:209], off
	s_waitcnt vmcnt(8)
	s_waitcnt lgkmcnt(0)
	s_barrier
	v_mfma_f32_16x16x32_bf16 v[64:67], v[116:119], v[164:167], v[64:67]
	v_mfma_f32_16x16x32_bf16 v[64:67], v[128:131], v[168:171], v[64:67]
	v_mfma_f32_16x16x32_bf16 v[60:63], v[132:135], v[164:167], v[60:63]
	v_mfma_f32_16x16x32_bf16 v[60:63], v[136:139], v[168:171], v[60:63]
	v_mfma_f32_16x16x32_bf16 v[56:59], v[140:143], v[164:167], v[56:59]
	v_mfma_f32_16x16x32_bf16 v[56:59], v[144:147], v[168:171], v[56:59]
	v_mfma_f32_16x16x32_bf16 v[52:55], v[148:151], v[164:167], v[52:55]
	v_mfma_f32_16x16x32_bf16 v[52:55], v[152:155], v[168:171], v[52:55]
	v_mfma_f32_16x16x32_bf16 v[36:39], v[148:151], v[172:175], v[36:39]
	v_mfma_f32_16x16x32_bf16 v[36:39], v[152:155], v[176:179], v[36:39]
	v_mfma_f32_16x16x32_bf16 v[40:43], v[140:143], v[172:175], v[40:43]
	v_mfma_f32_16x16x32_bf16 v[40:43], v[144:147], v[176:179], v[40:43]
	v_mfma_f32_16x16x32_bf16 v[44:47], v[132:135], v[172:175], v[44:47]
	v_mfma_f32_16x16x32_bf16 v[44:47], v[136:139], v[176:179], v[44:47]
	v_mfma_f32_16x16x32_bf16 v[48:51], v[116:119], v[172:175], v[48:51]
	v_mfma_f32_16x16x32_bf16 v[48:51], v[128:131], v[176:179], v[48:51]
	v_mfma_f32_16x16x32_bf16 v[32:35], v[116:119], v[180:183], v[32:35]
	v_mfma_f32_16x16x32_bf16 v[32:35], v[128:131], v[184:187], v[32:35]
	v_mfma_f32_16x16x32_bf16 v[28:31], v[132:135], v[180:183], v[28:31]
	v_mfma_f32_16x16x32_bf16 v[28:31], v[136:139], v[184:187], v[28:31]
	v_mfma_f32_16x16x32_bf16 v[24:27], v[140:143], v[180:183], v[24:27]
	v_mfma_f32_16x16x32_bf16 v[24:27], v[144:147], v[184:187], v[24:27]
	v_mfma_f32_16x16x32_bf16 v[20:23], v[148:151], v[180:183], v[20:23]
	v_mfma_f32_16x16x32_bf16 v[20:23], v[152:155], v[184:187], v[20:23]
	v_mfma_f32_16x16x32_bf16 v[4:7], v[148:151], v[188:191], v[4:7]
	v_mfma_f32_16x16x32_bf16 v[4:7], v[152:155], v[204:207], v[4:7]
	v_mfma_f32_16x16x32_bf16 v[8:11], v[140:143], v[188:191], v[8:11]
	v_mfma_f32_16x16x32_bf16 v[8:11], v[144:147], v[204:207], v[8:11]
	v_mfma_f32_16x16x32_bf16 v[12:15], v[132:135], v[188:191], v[12:15]
	v_mfma_f32_16x16x32_bf16 v[12:15], v[136:139], v[204:207], v[12:15]
	v_mfma_f32_16x16x32_bf16 v[16:19], v[116:119], v[188:191], v[16:19]
	v_mfma_f32_16x16x32_bf16 v[16:19], v[128:131], v[204:207], v[16:19]
	s_barrier
	s_add_i32 s52, s52, 2
	s_add_u32 s0, s0, 0x100
	s_addc_u32 s1, s1, 0
	s_add_u32 s27, s27, 0x100
	s_addc_u32 s33, s33, 0
	s_cmp_gt_u32 s52, 5
	s_cbranch_scc0 .LBB0_1479
	s_and_b64 vcc, exec, s[8:9]
	s_cbranch_vccz .LBB0_1482
	s_barrier

;     __device__ __forceinline__ int nt(const Unit& u) const { return (u.pn >> 1) < 2 ? 22 : 20; }
; #define PG8_STAGE(bufoff, gbase, voff) do { _Pragma("unroll") for (int _i = 0; _i < 2; ++_i) \
;         __builtin_amdgcn_global_load_lds((const unsigned*)((const char*)(gbase) + (voff)[_i]), (LAS unsigned*)(lds + (bufoff) + ldsw + _i * 8192), 16, 0, 0); } while (0)
; #define PG8_LDA(dst, b, h) do { _Pragma("unroll") for (int m = 0; m < 4; ++m) _Pragma("unroll") for (int k = 0; k < 2; ++k) dst[m][k] = *(const LAS bf16x8*)(pA + PG8_SA(b, h) + m * 2048 + k * 1024); } while (0)
; #define PG8_LDB(dst, b, h) do { _Pragma("unroll") for (int n = 0; n < 2; ++n) _Pragma("unroll") for (int k = 0; k < 2; ++k) dst[n][k] = *(const LAS bf16x8*)(pB + (PG8_SB(b, h) - 4 * HTB) + n * 2048 + k * 1024); } while (0)
; #define PG8_MMA(ai, bj, At, Bt) do { __builtin_amdgcn_s_setprio(1); _Pragma("unroll") for (int m = 0; m < 4; ++m) _Pragma("unroll") for (int n = 0; n < 2; ++n) _Pragma("unroll") for (int k = 0; k < 2; ++k) \
;         acc[ai][bj][m][n] = __builtin_amdgcn_mfma_f32_16x16x32_bf16(Bt[n][k], At[m][k], acc[ai][bj][m][n], 0, 0, 0); __builtin_amdgcn_s_setprio(0); } while (0)
; #define PG8_WAIT_V(n) asm volatile("s_waitcnt vmcnt(" #n ")" ::: "memory")
; #define PG8_BAR __builtin_amdgcn_s_barrier()
; template <class Desc, class Epi, bool ALIGN_EPI>
; __device__ __forceinline__ void gemm_phase(LAS unsigned char* lds, const Desc& D, const Epi& E, int G, int c) {
;     ...
;         for (int t = 0; t < nt; t += 2) {
;             const bool last = (t == nt - 2);
;             if (last && has_next) PG8_AWAIT(nxt);
;             const char* a1 = cA + (size_t)(t + 1) * kstep;
;             const char* a2 = last ? nA : cA + (size_t)(t + 2) * kstep; const char* b2 = last ? nB : cB + (size_t)(t + 2) * kstep;
;             const char* a3 = a2 + kstep; const char* b3 = b2 + kstep;
;             PG8_LDB(B0, 0, 0); PG8_LDB(B1, 0, 1); PG8_SCHED; PG8_LDA(At, 0, 0); PG8_STAGE(PG8_SA(1, 1), a1 + hstepA, voffA);
;             PG8_WAIT_V(8); PG8_WAIT_L(0); PG8_BAR; PG8_MMA(0, 0, At, B0); PG8_MMA(0, 1, At, B1); PG8_BAR; PG8_SCHED;
;             PG8_LDA(At, 0, 1); PG8_STAGE(PG8_SB(0, 0), b2, voffB); PG8_STAGE(PG8_SB(0, 1), b2 + hstepB, voffB); PG8_STAGE(PG8_SA(0, 0), a2, voffA);
;             PG8_WAIT_V(8); PG8_WAIT_L(0); PG8_BAR; PG8_MMA(1, 0, At, B0); PG8_MMA(1, 1, At, B1); PG8_BAR; PG8_SCHED;
.LBB0_1517:
	ds_read_b128 v[116:119], v225
	s_nop 0
	ds_read_b128 v[128:131], v225 offset:1024
	s_nop 0
	ds_read_b128 v[132:135], v225 offset:2048
	s_nop 0
	ds_read_b128 v[136:139], v225 offset:3072
	s_nop 0
	ds_read_b128 v[140:143], v225 offset:16384
	s_nop 0
	ds_read_b128 v[144:147], v225 offset:17408
	s_nop 0
	ds_read_b128 v[148:151], v225 offset:18432
	s_nop 0
	ds_read_b128 v[152:155], v225 offset:19456
	s_add_u32 s12, s0, 0xfffe0080
	s_addc_u32 s13, s1, -1
	s_cmp_eq_u32 s54, 4
	s_cselect_b32 s17, s37, s13
	s_cselect_b32 s16, s36, s12
	s_cselect_b32 s13, s21, s33
	s_cselect_b32 s12, s24, s27
	v_lshl_add_u64 v[208:209], s[0:1], 0, v[200:201]
	s_add_i32 m0, s31, 0xc000
	ds_read_b128 v[164:167], v224
	s_nop 0
	ds_read_b128 v[168:171], v224 offset:1024
	s_nop 0
	ds_read_b128 v[172:175], v224 offset:2048
	s_nop 0
	ds_read_b128 v[176:179], v224 offset:3072
	s_nop 0
	ds_read_b128 v[180:183], v224 offset:4096
	s_nop 0
	ds_read_b128 v[184:187], v224 offset:5120
	s_nop 0
	ds_read_b128 v[188:191], v224 offset:6144
	s_nop 0
	ds_read_b128 v[204:207], v224 offset:7168
	global_load_lds_dwordx4 v[208:209], off
	v_lshl_add_u64 v[208:209], s[0:1], 0, v[202:203]
	s_add_i32 m0, s31, 0xe000
	s_nop 0
	global_load_lds_dwordx4 v[208:209], off
	s_waitcnt vmcnt(8)
	s_waitcnt lgkmcnt(0)
	s_barrier
	v_mfma_f32_16x16x32_bf16 v[160:163], v[116:119], v[164:167], v[160:163]
	v_mfma_f32_16x16x32_bf16 v[160:163], v[128:131], v[168:171], v[160:163]
	v_mfma_f32_16x16x32_bf16 v[156:159], v[132:135], v[164:167], v[156:159]
	v_mfma_f32_16x16x32_bf16 v[156:159], v[136:139], v[168:171], v[156:159]
	v_mfma_f32_16x16x32_bf16 v[124:127], v[140:143], v[164:167], v[124:127]
	v_mfma_f32_16x16x32_bf16 v[124:127], v[144:147], v[168:171], v[124:127]
	v_mfma_f32_16x16x32_bf16 v[120:123], v[148:151], v[164:167], v[120:123]
	v_mfma_f32_16x16x32_bf16 v[120:123], v[152:155], v[168:171], v[120:123]
	v_mfma_f32_16x16x32_bf16 v[100:103], v[148:151], v[172:175], v[100:103]
	v_mfma_f32_16x16x32_bf16 v[100:103], v[152:155], v[176:179], v[100:103]
	v_mfma_f32_16x16x32_bf16 v[104:107], v[140:143], v[172:175], v[104:107]
	v_mfma_f32_16x16x32_bf16 v[104:107], v[144:147], v[176:179], v[104:107]
	v_mfma_f32_16x16x32_bf16 v[108:111], v[132:135], v[172:175], v[108:111]
	v_mfma_f32_16x16x32_bf16 v[108:111], v[136:139], v[176:179], v[108:111]
	v_mfma_f32_16x16x32_bf16 v[112:115], v[116:119], v[172:175], v[112:115]
	v_mfma_f32_16x16x32_bf16 v[112:115], v[128:131], v[176:179], v[112:115]
	v_mfma_f32_16x16x32_bf16 v[96:99], v[116:119], v[180:183], v[96:99]
	v_mfma_f32_16x16x32_bf16 v[96:99], v[128:131], v[184:187], v[96:99]
	v_mfma_f32_16x16x32_bf16 v[92:95], v[132:135], v[180:183], v[92:95]
	v_mfma_f32_16x16x32_bf16 v[92:95], v[136:139], v[184:187], v[92:95]
	v_mfma_f32_16x16x32_bf16 v[88:91], v[140:143], v[180:183], v[88:91]
	v_mfma_f32_16x16x32_bf16 v[88:91], v[144:147], v[184:187], v[88:91]
	v_mfma_f32_16x16x32_bf16 v[84:87], v[148:151], v[180:183], v[84:87]
	v_mfma_f32_16x16x32_bf16 v[84:87], v[152:155], v[184:187], v[84:87]
	v_mfma_f32_16x16x32_bf16 v[68:71], v[148:151], v[188:191], v[68:71]
	v_mfma_f32_16x16x32_bf16 v[68:71], v[152:155], v[204:207], v[68:71]
	v_mfma_f32_16x16x32_bf16 v[72:75], v[140:143], v[188:191], v[72:75]
	v_mfma_f32_16x16x32_bf16 v[72:75], v[144:147], v[204:207], v[72:75]
	v_mfma_f32_16x16x32_bf16 v[76:79], v[132:135], v[188:191], v[76:79]
	v_mfma_f32_16x16x32_bf16 v[76:79], v[136:139], v[204:207], v[76:79]
	v_mfma_f32_16x16x32_bf16 v[80:83], v[116:119], v[188:191], v[80:83]
	v_mfma_f32_16x16x32_bf16 v[80:83], v[128:131], v[204:207], v[80:83]
	s_barrier
	s_mov_b32 m0, s34
	v_lshl_add_u64 v[208:209], s[12:13], 0, v[196:197]
	s_add_u32 s56, s12, 0x20000
	ds_read_b128 v[164:167], v224 offset:16384
	s_nop 0
	ds_read_b128 v[168:171], v224 offset:17408
	s_nop 0
	ds_read_b128 v[172:175], v224 offset:18432
	s_nop 0
	ds_read_b128 v[176:179], v224 offset:19456
	s_nop 0
	ds_read_b128 v[180:183], v224 offset:20480
	s_nop 0
	ds_read_b128 v[184:187], v224 offset:21504
	s_nop 0
	ds_read_b128 v[188:191], v224 offset:22528
	s_nop 0
	ds_read_b128 v[204:207], v224 offset:23552
	global_load_lds_dwordx4 v[208:209], off
	v_lshl_add_u64 v[210:211], s[12:13], 0, v[192:193]
	s_mov_b32 m0, s35
	s_addc_u32 s57, s13, 0
	global_load_lds_dwordx4 v[210:211], off
	v_lshl_add_u64 v[212:213], s[56:57], 0, v[196:197]
	s_mov_b32 m0, s42
	v_lshl_add_u64 v[214:215], s[16:17], 0, v[194:195]
	global_load_lds_dwordx4 v[212:213], off
	v_lshl_add_u64 v[212:213], s[56:57], 0, v[192:193]
	s_mov_b32 m0, s43
	s_nop 0
	global_load_lds_dwordx4 v[212:213], off
	v_lshl_add_u64 v[212:213], s[16:17], 0, v[198:199]
	s_mov_b32 m0, s31
	s_nop 0
	global_load_lds_dwordx4 v[212:213], off
	s_mov_b32 m0, s44
	s_nop 0
	global_load_lds_dwordx4 v[214:215], off
	s_waitcnt vmcnt(8)
	s_waitcnt lgkmcnt(0)
	s_barrier
; #define PG8_STAGE(bufoff, gbase, voff) do { _Pragma("unroll") for (int _i = 0; _i < 2; ++_i) \
;         __builtin_amdgcn_global_load_lds((const unsigned*)((const char*)(gbase) + (voff)[_i]), (LAS unsigned*)(lds + (bufoff) + ldsw + _i * 8192), 16, 0, 0); } while (0)
; #define PG8_LDA(dst, b, h) do { _Pragma("unroll") for (int m = 0; m < 4; ++m) _Pragma("unroll") for (int k = 0; k < 2; ++k) dst[m][k] = *(const LAS bf16x8*)(pA + PG8_SA(b, h) + m * 2048 + k * 1024); } while (0)
; #define PG8_LDB(dst, b, h) do { _Pragma("unroll") for (int n = 0; n < 2; ++n) _Pragma("unroll") for (int k = 0; k < 2; ++k) dst[n][k] = *(const LAS bf16x8*)(pB + (PG8_SB(b, h) - 4 * HTB) + n * 2048 + k * 1024); } while (0)
; #define PG8_MMA(ai, bj, At, Bt) do { __builtin_amdgcn_s_setprio(1); _Pragma("unroll") for (int m = 0; m < 4; ++m) _Pragma("unroll") for (int n = 0; n < 2; ++n) _Pragma("unroll") for (int k = 0; k < 2; ++k) \
;         acc[ai][bj][m][n] = __builtin_amdgcn_mfma_f32_16x16x32_bf16(Bt[n][k], At[m][k], acc[ai][bj][m][n], 0, 0, 0); __builtin_amdgcn_s_setprio(0); } while (0)
; #define PG8_WAIT_V(n) asm volatile("s_waitcnt vmcnt(" #n ")" ::: "memory")
; #define PG8_WAIT_L(n) asm volatile("s_waitcnt lgkmcnt(" #n ")" ::: "memory")
; #define PG8_BAR __builtin_amdgcn_s_barrier()
; #define PG8_SCHED __builtin_amdgcn_sched_barrier(0)
; template <class Desc, class Epi, bool ALIGN_EPI>
; __device__ __forceinline__ void gemm_phase(LAS unsigned char* lds, const Desc& D, const Epi& E, int G, int c) {
;     ...
;             PG8_WAIT_V(8); PG8_WAIT_L(0); PG8_BAR; PG8_MMA(1, 0, At, B0); PG8_MMA(1, 1, At, B1); PG8_BAR; PG8_SCHED;
;             PG8_LDB(B0, 1, 0); PG8_LDB(B1, 1, 1); PG8_SCHED; PG8_LDA(At, 1, 0); PG8_STAGE(PG8_SA(0, 1), a2 + hstepA, voffA);
;             PG8_WAIT_V(8); PG8_WAIT_L(0); PG8_BAR; PG8_MMA(0, 0, At, B0); PG8_MMA(0, 1, At, B1); PG8_BAR; PG8_SCHED;
	v_mfma_f32_16x16x32_bf16 v[64:67], v[116:119], v[164:167], v[64:67]
	v_mfma_f32_16x16x32_bf16 v[64:67], v[128:131], v[168:171], v[64:67]
	v_mfma_f32_16x16x32_bf16 v[60:63], v[132:135], v[164:167], v[60:63]
	v_mfma_f32_16x16x32_bf16 v[60:63], v[136:139], v[168:171], v[60:63]
	v_mfma_f32_16x16x32_bf16 v[56:59], v[140:143], v[164:167], v[56:59]
	v_mfma_f32_16x16x32_bf16 v[56:59], v[144:147], v[168:171], v[56:59]
	v_mfma_f32_16x16x32_bf16 v[52:55], v[148:151], v[164:167], v[52:55]
	v_mfma_f32_16x16x32_bf16 v[52:55], v[152:155], v[168:171], v[52:55]
	v_mfma_f32_16x16x32_bf16 v[36:39], v[148:151], v[172:175], v[36:39]
	v_mfma_f32_16x16x32_bf16 v[36:39], v[152:155], v[176:179], v[36:39]
	v_mfma_f32_16x16x32_bf16 v[40:43], v[140:143], v[172:175], v[40:43]
	v_mfma_f32_16x16x32_bf16 v[40:43], v[144:147], v[176:179], v[40:43]
	v_mfma_f32_16x16x32_bf16 v[44:47], v[132:135], v[172:175], v[44:47]
	v_mfma_f32_16x16x32_bf16 v[44:47], v[136:139], v[176:179], v[44:47]
	v_mfma_f32_16x16x32_bf16 v[48:51], v[116:119], v[172:175], v[48:51]
	v_mfma_f32_16x16x32_bf16 v[48:51], v[128:131], v[176:179], v[48:51]
	v_mfma_f32_16x16x32_bf16 v[32:35], v[116:119], v[180:183], v[32:35]
	v_mfma_f32_16x16x32_bf16 v[32:35], v[128:131], v[184:187], v[32:35]
	v_mfma_f32_16x16x32_bf16 v[28:31], v[132:135], v[180:183], v[28:31]
	v_mfma_f32_16x16x32_bf16 v[28:31], v[136:139], v[184:187], v[28:31]
	v_mfma_f32_16x16x32_bf16 v[24:27], v[140:143], v[180:183], v[24:27]
	v_mfma_f32_16x16x32_bf16 v[24:27], v[144:147], v[184:187], v[24:27]
	v_mfma_f32_16x16x32_bf16 v[20:23], v[148:151], v[180:183], v[20:23]
	v_mfma_f32_16x16x32_bf16 v[20:23], v[152:155], v[184:187], v[20:23]
	v_mfma_f32_16x16x32_bf16 v[4:7], v[148:151], v[188:191], v[4:7]
	v_mfma_f32_16x16x32_bf16 v[4:7], v[152:155], v[204:207], v[4:7]
	v_mfma_f32_16x16x32_bf16 v[8:11], v[140:143], v[188:191], v[8:11]
	v_mfma_f32_16x16x32_bf16 v[8:11], v[144:147], v[204:207], v[8:11]
	v_mfma_f32_16x16x32_bf16 v[12:15], v[132:135], v[188:191], v[12:15]
	v_mfma_f32_16x16x32_bf16 v[12:15], v[136:139], v[204:207], v[12:15]
	v_mfma_f32_16x16x32_bf16 v[16:19], v[116:119], v[188:191], v[16:19]
	v_mfma_f32_16x16x32_bf16 v[16:19], v[128:131], v[204:207], v[16:19]
	s_barrier
	ds_read_b128 v[116:119], v225 offset:32768
	s_nop 0
	ds_read_b128 v[128:131], v225 offset:33792
	s_nop 0
	ds_read_b128 v[132:135], v225 offset:34816
	s_nop 0
	ds_read_b128 v[136:139], v225 offset:35840
	s_nop 0
	ds_read_b128 v[140:143], v225 offset:49152
	s_nop 0
	ds_read_b128 v[144:147], v225 offset:50176
	s_nop 0
	ds_read_b128 v[148:151], v225 offset:51200
	s_nop 0
	ds_read_b128 v[152:155], v225 offset:52224
	s_add_u32 s16, s16, 0x20000
	s_addc_u32 s17, s17, 0
	s_mov_b32 m0, s45
	v_lshl_add_u64 v[216:217], s[16:17], 0, v[198:199]
	ds_read_b128 v[164:167], v224 offset:32768
	s_nop 0
	ds_read_b128 v[168:171], v224 offset:33792
	s_nop 0
	ds_read_b128 v[172:175], v224 offset:34816
	s_nop 0
	ds_read_b128 v[176:179], v224 offset:35840
	s_nop 0
	ds_read_b128 v[180:183], v224 offset:36864
	s_nop 0
	ds_read_b128 v[184:187], v224 offset:37888
	s_nop 0
	ds_read_b128 v[188:191], v224 offset:38912
	s_nop 0
	ds_read_b128 v[204:207], v224 offset:39936
	global_load_lds_dwordx4 v[216:217], off
	v_lshl_add_u64 v[216:217], s[16:17], 0, v[194:195]
	s_mov_b32 m0, s46
	s_nop 0
	global_load_lds_dwordx4 v[216:217], off
	s_waitcnt vmcnt(8)
	s_waitcnt lgkmcnt(0)
	s_barrier
	v_mfma_f32_16x16x32_bf16 v[160:163], v[116:119], v[164:167], v[160:163]
	v_mfma_f32_16x16x32_bf16 v[160:163], v[128:131], v[168:171], v[160:163]
	v_mfma_f32_16x16x32_bf16 v[156:159], v[132:135], v[164:167], v[156:159]
	v_mfma_f32_16x16x32_bf16 v[156:159], v[136:139], v[168:171], v[156:159]
	v_mfma_f32_16x16x32_bf16 v[124:127], v[140:143], v[164:167], v[124:127]
	v_mfma_f32_16x16x32_bf16 v[124:127], v[144:147], v[168:171], v[124:127]
	v_mfma_f32_16x16x32_bf16 v[120:123], v[148:151], v[164:167], v[120:123]
	v_mfma_f32_16x16x32_bf16 v[120:123], v[152:155], v[168:171], v[120:123]
	v_mfma_f32_16x16x32_bf16 v[100:103], v[148:151], v[172:175], v[100:103]
	v_mfma_f32_16x16x32_bf16 v[100:103], v[152:155], v[176:179], v[100:103]
	v_mfma_f32_16x16x32_bf16 v[104:107], v[140:143], v[172:175], v[104:107]
	v_mfma_f32_16x16x32_bf16 v[104:107], v[144:147], v[176:179], v[104:107]
	v_mfma_f32_16x16x32_bf16 v[108:111], v[132:135], v[172:175], v[108:111]
	v_mfma_f32_16x16x32_bf16 v[108:111], v[136:139], v[176:179], v[108:111]
	v_mfma_f32_16x16x32_bf16 v[112:115], v[116:119], v[172:175], v[112:115]
	v_mfma_f32_16x16x32_bf16 v[112:115], v[128:131], v[176:179], v[112:115]
	v_mfma_f32_16x16x32_bf16 v[96:99], v[116:119], v[180:183], v[96:99]
	v_mfma_f32_16x16x32_bf16 v[96:99], v[128:131], v[184:187], v[96:99]
	v_mfma_f32_16x16x32_bf16 v[92:95], v[132:135], v[180:183], v[92:95]
	v_mfma_f32_16x16x32_bf16 v[92:95], v[136:139], v[184:187], v[92:95]
	v_mfma_f32_16x16x32_bf16 v[88:91], v[140:143], v[180:183], v[88:91]
	v_mfma_f32_16x16x32_bf16 v[88:91], v[144:147], v[184:187], v[88:91]
	v_mfma_f32_16x16x32_bf16 v[84:87], v[148:151], v[180:183], v[84:87]
	v_mfma_f32_16x16x32_bf16 v[84:87], v[152:155], v[184:187], v[84:87]
	v_mfma_f32_16x16x32_bf16 v[68:71], v[148:151], v[188:191], v[68:71]
	v_mfma_f32_16x16x32_bf16 v[68:71], v[152:155], v[204:207], v[68:71]
	v_mfma_f32_16x16x32_bf16 v[72:75], v[140:143], v[188:191], v[72:75]
	v_mfma_f32_16x16x32_bf16 v[72:75], v[144:147], v[204:207], v[72:75]
	v_mfma_f32_16x16x32_bf16 v[76:79], v[132:135], v[188:191], v[76:79]
	v_mfma_f32_16x16x32_bf16 v[76:79], v[136:139], v[204:207], v[76:79]
	v_mfma_f32_16x16x32_bf16 v[80:83], v[116:119], v[188:191], v[80:83]
	v_mfma_f32_16x16x32_bf16 v[80:83], v[128:131], v[204:207], v[80:83]
	s_barrier
; #define PG8_STAGE(bufoff, gbase, voff) do { _Pragma("unroll") for (int _i = 0; _i < 2; ++_i) \
;         __builtin_amdgcn_global_load_lds((const unsigned*)((const char*)(gbase) + (voff)[_i]), (LAS unsigned*)(lds + (bufoff) + ldsw + _i * 8192), 16, 0, 0); } while (0)
; #define PG8_LDA(dst, b, h) do { _Pragma("unroll") for (int m = 0; m < 4; ++m) _Pragma("unroll") for (int k = 0; k < 2; ++k) dst[m][k] = *(const LAS bf16x8*)(pA + PG8_SA(b, h) + m * 2048 + k * 1024); } while (0)
; #define PG8_MMA(ai, bj, At, Bt) do { __builtin_amdgcn_s_setprio(1); _Pragma("unroll") for (int m = 0; m < 4; ++m) _Pragma("unroll") for (int n = 0; n < 2; ++n) _Pragma("unroll") for (int k = 0; k < 2; ++k) \
;         acc[ai][bj][m][n] = __builtin_amdgcn_mfma_f32_16x16x32_bf16(Bt[n][k], At[m][k], acc[ai][bj][m][n], 0, 0, 0); __builtin_amdgcn_s_setprio(0); } while (0)
; #define PG8_WAIT_V(n) asm volatile("s_waitcnt vmcnt(" #n ")" ::: "memory")
; #define PG8_WAIT_L(n) asm volatile("s_waitcnt lgkmcnt(" #n ")" ::: "memory")
; #define PG8_BAR __builtin_amdgcn_s_barrier()
; #define PG8_SCHED __builtin_amdgcn_sched_barrier(0)
; template <class Desc, class Epi, bool ALIGN_EPI>
; __device__ __forceinline__ void gemm_phase(LAS unsigned char* lds, const Desc& D, const Epi& E, int G, int c) {
;     ...
;             PG8_LDA(At, 1, 1); PG8_STAGE(PG8_SB(1, 0), b3, voffB); PG8_STAGE(PG8_SB(1, 1), b3 + hstepB, voffB); PG8_STAGE(PG8_SA(1, 0), a3, voffA);
;             PG8_WAIT_V(8); PG8_WAIT_L(0); PG8_BAR; PG8_MMA(1, 0, At, B0); PG8_MMA(1, 1, At, B1); PG8_BAR; PG8_SCHED;
;         }
;         if constexpr (ALIGN_EPI) { if (wr == 0) PG8_BAR; }
	s_mov_b32 m0, s47
	v_lshl_add_u64 v[208:209], v[208:209], 0, s[76:77]
	s_add_u32 s12, s12, 0x20080
	ds_read_b128 v[164:167], v224 offset:49152
	s_nop 0
	ds_read_b128 v[168:171], v224 offset:50176
	s_nop 0
	ds_read_b128 v[172:175], v224 offset:51200
	s_nop 0
	ds_read_b128 v[176:179], v224 offset:52224
	s_nop 0
	ds_read_b128 v[180:183], v224 offset:53248
	s_nop 0
	ds_read_b128 v[184:187], v224 offset:54272
	s_nop 0
	ds_read_b128 v[188:191], v224 offset:55296
	s_nop 0
	ds_read_b128 v[204:207], v224 offset:56320
	global_load_lds_dwordx4 v[208:209], off
	v_lshl_add_u64 v[208:209], v[210:211], 0, s[76:77]
	s_mov_b32 m0, s48
	s_addc_u32 s13, s13, 0
	global_load_lds_dwordx4 v[208:209], off
	v_lshl_add_u64 v[208:209], s[12:13], 0, v[196:197]
	s_mov_b32 m0, s51
	s_nop 0
	global_load_lds_dwordx4 v[208:209], off
	v_lshl_add_u64 v[208:209], s[12:13], 0, v[192:193]
	s_mov_b32 m0, s52
	s_nop 0
	global_load_lds_dwordx4 v[208:209], off
	v_lshl_add_u64 v[208:209], v[212:213], 0, s[76:77]
	s_mov_b32 m0, s49
	s_nop 0
	global_load_lds_dwordx4 v[208:209], off
	v_lshl_add_u64 v[208:209], v[214:215], 0, s[76:77]
	s_mov_b32 m0, s50
	s_nop 0
	global_load_lds_dwordx4 v[208:209], off
	s_waitcnt vmcnt(8)
	s_waitcnt lgkmcnt(0)
	s_barrier
	v_mfma_f32_16x16x32_bf16 v[64:67], v[116:119], v[164:167], v[64:67]
	v_mfma_f32_16x16x32_bf16 v[64:67], v[128:131], v[168:171], v[64:67]
	v_mfma_f32_16x16x32_bf16 v[60:63], v[132:135], v[164:167], v[60:63]
	v_mfma_f32_16x16x32_bf16 v[60:63], v[136:139], v[168:171], v[60:63]
	v_mfma_f32_16x16x32_bf16 v[56:59], v[140:143], v[164:167], v[56:59]
	v_mfma_f32_16x16x32_bf16 v[56:59], v[144:147], v[168:171], v[56:59]
	v_mfma_f32_16x16x32_bf16 v[52:55], v[148:151], v[164:167], v[52:55]
	v_mfma_f32_16x16x32_bf16 v[52:55], v[152:155], v[168:171], v[52:55]
	v_mfma_f32_16x16x32_bf16 v[36:39], v[148:151], v[172:175], v[36:39]
	v_mfma_f32_16x16x32_bf16 v[36:39], v[152:155], v[176:179], v[36:39]
	v_mfma_f32_16x16x32_bf16 v[40:43], v[140:143], v[172:175], v[40:43]
	v_mfma_f32_16x16x32_bf16 v[40:43], v[144:147], v[176:179], v[40:43]
	v_mfma_f32_16x16x32_bf16 v[44:47], v[132:135], v[172:175], v[44:47]
	v_mfma_f32_16x16x32_bf16 v[44:47], v[136:139], v[176:179], v[44:47]
	v_mfma_f32_16x16x32_bf16 v[48:51], v[116:119], v[172:175], v[48:51]
	v_mfma_f32_16x16x32_bf16 v[48:51], v[128:131], v[176:179], v[48:51]
	v_mfma_f32_16x16x32_bf16 v[32:35], v[116:119], v[180:183], v[32:35]
	v_mfma_f32_16x16x32_bf16 v[32:35], v[128:131], v[184:187], v[32:35]
	v_mfma_f32_16x16x32_bf16 v[28:31], v[132:135], v[180:183], v[28:31]
	v_mfma_f32_16x16x32_bf16 v[28:31], v[136:139], v[184:187], v[28:31]
	v_mfma_f32_16x16x32_bf16 v[24:27], v[140:143], v[180:183], v[24:27]
	v_mfma_f32_16x16x32_bf16 v[24:27], v[144:147], v[184:187], v[24:27]
	v_mfma_f32_16x16x32_bf16 v[20:23], v[148:151], v[180:183], v[20:23]
	v_mfma_f32_16x16x32_bf16 v[20:23], v[152:155], v[184:187], v[20:23]
	v_mfma_f32_16x16x32_bf16 v[4:7], v[148:151], v[188:191], v[4:7]
	v_mfma_f32_16x16x32_bf16 v[4:7], v[152:155], v[204:207], v[4:7]
	v_mfma_f32_16x16x32_bf16 v[8:11], v[140:143], v[188:191], v[8:11]
	v_mfma_f32_16x16x32_bf16 v[8:11], v[144:147], v[204:207], v[8:11]
	v_mfma_f32_16x16x32_bf16 v[12:15], v[132:135], v[188:191], v[12:15]
	v_mfma_f32_16x16x32_bf16 v[12:15], v[136:139], v[204:207], v[12:15]
	v_mfma_f32_16x16x32_bf16 v[16:19], v[116:119], v[188:191], v[16:19]
	v_mfma_f32_16x16x32_bf16 v[16:19], v[128:131], v[204:207], v[16:19]
	s_barrier
	s_add_i32 s54, s54, 2
	s_add_u32 s0, s0, 0x100
	s_addc_u32 s1, s1, 0
	s_add_u32 s27, s27, 0x100
	s_addc_u32 s33, s33, 0
	s_cmp_gt_u32 s54, 5
	s_cbranch_scc0 .LBB0_1517
	s_and_b64 vcc, exec, s[10:11]
	s_cbranch_vccz .LBB0_1520
	s_barrier

;     __device__ __forceinline__ int nt(const Unit& u) const { return (u.pn >> 1) < 2 ? 22 : 20; }
; #define PG8_STAGE(bufoff, gbase, voff) do { _Pragma("unroll") for (int _i = 0; _i < 2; ++_i) \
;         __builtin_amdgcn_global_load_lds((const unsigned*)((const char*)(gbase) + (voff)[_i]), (LAS unsigned*)(lds + (bufoff) + ldsw + _i * 8192), 16, 0, 0); } while (0)
; #define PG8_LDA(dst, b, h) do { _Pragma("unroll") for (int m = 0; m < 4; ++m) _Pragma("unroll") for (int k = 0; k < 2; ++k) dst[m][k] = *(const LAS bf16x8*)(pA + PG8_SA(b, h) + m * 2048 + k * 1024); } while (0)
; #define PG8_LDB(dst, b, h) do { _Pragma("unroll") for (int n = 0; n < 2; ++n) _Pragma("unroll") for (int k = 0; k < 2; ++k) dst[n][k] = *(const LAS bf16x8*)(pB + (PG8_SB(b, h) - 4 * HTB) + n * 2048 + k * 1024); } while (0)
; #define PG8_MMA(ai, bj, At, Bt) do { __builtin_amdgcn_s_setprio(1); _Pragma("unroll") for (int m = 0; m < 4; ++m) _Pragma("unroll") for (int n = 0; n < 2; ++n) _Pragma("unroll") for (int k = 0; k < 2; ++k) \
;         acc[ai][bj][m][n] = __builtin_amdgcn_mfma_f32_16x16x32_bf16(Bt[n][k], At[m][k], acc[ai][bj][m][n], 0, 0, 0); __builtin_amdgcn_s_setprio(0); } while (0)
; #define PG8_WAIT_V(n) asm volatile("s_waitcnt vmcnt(" #n ")" ::: "memory")
; #define PG8_BAR __builtin_amdgcn_s_barrier()
; template <class Desc, class Epi, bool ALIGN_EPI>
; __device__ __forceinline__ void gemm_phase(LAS unsigned char* lds, const Desc& D, const Epi& E, int G, int c) {
;     ...
;         for (int t = 0; t < nt; t += 2) {
;             const bool last = (t == nt - 2);
;             if (last && has_next) PG8_AWAIT(nxt);
;             const char* a1 = cA + (size_t)(t + 1) * kstep;
;             const char* a2 = last ? nA : cA + (size_t)(t + 2) * kstep; const char* b2 = last ? nB : cB + (size_t)(t + 2) * kstep;
;             const char* a3 = a2 + kstep; const char* b3 = b2 + kstep;
;             PG8_LDB(B0, 0, 0); PG8_LDB(B1, 0, 1); PG8_SCHED; PG8_LDA(At, 0, 0); PG8_STAGE(PG8_SA(1, 1), a1 + hstepA, voffA);
;             PG8_WAIT_V(8); PG8_WAIT_L(0); PG8_BAR; PG8_MMA(0, 0, At, B0); PG8_MMA(0, 1, At, B1); PG8_BAR; PG8_SCHED;
;             PG8_LDA(At, 0, 1); PG8_STAGE(PG8_SB(0, 0), b2, voffB); PG8_STAGE(PG8_SB(0, 1), b2 + hstepB, voffB); PG8_STAGE(PG8_SA(0, 0), a2, voffA);
;             PG8_WAIT_V(8); PG8_WAIT_L(0); PG8_BAR; PG8_MMA(1, 0, At, B0); PG8_MMA(1, 1, At, B1); PG8_BAR; PG8_SCHED;
.LBB0_1580:
	s_or_b32 s14, s30, 1
	s_add_i32 s30, s30, 2
	s_mov_b32 s31, s15
	s_lshl_b64 s[72:73], s[14:15], 7
	s_lshl_b64 s[74:75], s[30:31], 7
	s_add_u32 s14, s18, s74
	ds_read_b128 v[140:143], v163
	s_nop 0
	ds_read_b128 v[144:147], v163 offset:1024
	s_nop 0
	ds_read_b128 v[148:151], v163 offset:2048
	s_nop 0
	ds_read_b128 v[152:155], v163 offset:3072
	s_nop 0
	ds_read_b128 v[156:159], v163 offset:16384
	s_nop 0
	ds_read_b128 v[166:169], v163 offset:17408
	s_nop 0
	ds_read_b128 v[170:173], v163 offset:18432
	s_nop 0
	ds_read_b128 v[174:177], v163 offset:19456
	s_addc_u32 s31, s19, s75
	s_and_b64 s[46:47], s[34:35], exec
	s_cselect_b32 s47, s43, s31
	s_cselect_b32 s46, s42, s14
	s_add_u32 s14, s20, s74
	s_addc_u32 s31, s21, s75
	s_and_b64 s[34:35], s[34:35], exec
	s_cselect_b32 s35, s3, s31
	s_cselect_b32 s34, s13, s14
	s_add_u32 s14, s18, s72
	s_addc_u32 s31, s19, s73
	s_add_u32 s72, s14, 0x100000
	s_addc_u32 s73, s31, 0
	s_add_i32 m0, s52, 0xc000
	ds_read_b128 v[178:181], v162
	s_nop 0
	ds_read_b128 v[182:185], v162 offset:1024
	s_nop 0
	ds_read_b128 v[186:189], v162 offset:2048
	s_nop 0
	ds_read_b128 v[190:193], v162 offset:3072
	s_nop 0
	ds_read_b128 v[194:197], v162 offset:4096
	s_nop 0
	ds_read_b128 v[198:201], v162 offset:5120
	s_nop 0
	ds_read_b128 v[202:205], v162 offset:6144
	s_nop 0
	ds_read_b128 v[206:209], v162 offset:7168
	global_load_lds_dwordx4 v132, s[72:73]
	s_add_i32 m0, s52, 0xe000
	s_nop 0
	global_load_lds_dwordx4 v136, s[72:73]
	s_waitcnt vmcnt(8)
	s_waitcnt lgkmcnt(0)
	s_barrier
	v_mfma_f32_16x16x32_bf16 v[128:131], v[140:143], v[178:181], v[128:131]
	v_mfma_f32_16x16x32_bf16 v[128:131], v[144:147], v[182:185], v[128:131]
	v_mfma_f32_16x16x32_bf16 v[124:127], v[148:151], v[178:181], v[124:127]
	v_mfma_f32_16x16x32_bf16 v[124:127], v[152:155], v[182:185], v[124:127]
	v_mfma_f32_16x16x32_bf16 v[96:99], v[156:159], v[178:181], v[96:99]
	v_mfma_f32_16x16x32_bf16 v[96:99], v[166:169], v[182:185], v[96:99]
	v_mfma_f32_16x16x32_bf16 v[92:95], v[170:173], v[178:181], v[92:95]
	v_mfma_f32_16x16x32_bf16 v[92:95], v[174:177], v[182:185], v[92:95]
	v_mfma_f32_16x16x32_bf16 v[84:87], v[170:173], v[186:189], v[84:87]
	v_mfma_f32_16x16x32_bf16 v[84:87], v[174:177], v[190:193], v[84:87]
	v_mfma_f32_16x16x32_bf16 v[88:91], v[156:159], v[186:189], v[88:91]
	v_mfma_f32_16x16x32_bf16 v[88:91], v[166:169], v[190:193], v[88:91]
	v_mfma_f32_16x16x32_bf16 v[116:119], v[148:151], v[186:189], v[116:119]
	v_mfma_f32_16x16x32_bf16 v[116:119], v[152:155], v[190:193], v[116:119]
	v_mfma_f32_16x16x32_bf16 v[120:123], v[140:143], v[186:189], v[120:123]
	v_mfma_f32_16x16x32_bf16 v[120:123], v[144:147], v[190:193], v[120:123]
	v_mfma_f32_16x16x32_bf16 v[112:115], v[140:143], v[194:197], v[112:115]
	v_mfma_f32_16x16x32_bf16 v[112:115], v[144:147], v[198:201], v[112:115]
	v_mfma_f32_16x16x32_bf16 v[108:111], v[148:151], v[194:197], v[108:111]
	v_mfma_f32_16x16x32_bf16 v[108:111], v[152:155], v[198:201], v[108:111]
	v_mfma_f32_16x16x32_bf16 v[80:83], v[156:159], v[194:197], v[80:83]
	v_mfma_f32_16x16x32_bf16 v[80:83], v[166:169], v[198:201], v[80:83]
	v_mfma_f32_16x16x32_bf16 v[76:79], v[170:173], v[194:197], v[76:79]
	v_mfma_f32_16x16x32_bf16 v[76:79], v[174:177], v[198:201], v[76:79]
	v_mfma_f32_16x16x32_bf16 v[68:71], v[170:173], v[202:205], v[68:71]
	v_mfma_f32_16x16x32_bf16 v[68:71], v[174:177], v[206:209], v[68:71]
	v_mfma_f32_16x16x32_bf16 v[72:75], v[156:159], v[202:205], v[72:75]
	v_mfma_f32_16x16x32_bf16 v[72:75], v[166:169], v[206:209], v[72:75]
	v_mfma_f32_16x16x32_bf16 v[100:103], v[148:151], v[202:205], v[100:103]
	v_mfma_f32_16x16x32_bf16 v[100:103], v[152:155], v[206:209], v[100:103]
	v_mfma_f32_16x16x32_bf16 v[104:107], v[140:143], v[202:205], v[104:107]
	v_mfma_f32_16x16x32_bf16 v[104:107], v[144:147], v[206:209], v[104:107]
	s_barrier
	s_mov_b32 m0, s53
	s_add_u32 s72, s34, 0x100000
	s_addc_u32 s73, s35, 0
	ds_read_b128 v[178:181], v162 offset:16384
	s_nop 0
	ds_read_b128 v[182:185], v162 offset:17408
	s_nop 0
	ds_read_b128 v[186:189], v162 offset:18432
	s_nop 0
	ds_read_b128 v[190:193], v162 offset:19456
	s_nop 0
	ds_read_b128 v[194:197], v162 offset:20480
	s_nop 0
	ds_read_b128 v[198:201], v162 offset:21504
	s_nop 0
	ds_read_b128 v[202:205], v162 offset:22528
	s_nop 0
	ds_read_b128 v[206:209], v162 offset:23552
	global_load_lds_dwordx4 v134, s[34:35]
	s_mov_b32 m0, s54
	s_nop 0
	global_load_lds_dwordx4 v138, s[34:35]
	s_mov_b32 m0, s55
	s_nop 0
	global_load_lds_dwordx4 v134, s[72:73]
	s_mov_b32 m0, s56
	s_nop 0
	global_load_lds_dwordx4 v138, s[72:73]
	s_mov_b32 m0, s52
	s_nop 0
	global_load_lds_dwordx4 v132, s[46:47]
	s_mov_b32 m0, s57
	s_nop 0
	global_load_lds_dwordx4 v136, s[46:47]
	s_waitcnt vmcnt(8)
	s_waitcnt lgkmcnt(0)
	s_barrier
; #define PG8_STAGE(bufoff, gbase, voff) do { _Pragma("unroll") for (int _i = 0; _i < 2; ++_i) \
;         __builtin_amdgcn_global_load_lds((const unsigned*)((const char*)(gbase) + (voff)[_i]), (LAS unsigned*)(lds + (bufoff) + ldsw + _i * 8192), 16, 0, 0); } while (0)
; #define PG8_LDA(dst, b, h) do { _Pragma("unroll") for (int m = 0; m < 4; ++m) _Pragma("unroll") for (int k = 0; k < 2; ++k) dst[m][k] = *(const LAS bf16x8*)(pA + PG8_SA(b, h) + m * 2048 + k * 1024); } while (0)
; #define PG8_LDB(dst, b, h) do { _Pragma("unroll") for (int n = 0; n < 2; ++n) _Pragma("unroll") for (int k = 0; k < 2; ++k) dst[n][k] = *(const LAS bf16x8*)(pB + (PG8_SB(b, h) - 4 * HTB) + n * 2048 + k * 1024); } while (0)
; #define PG8_MMA(ai, bj, At, Bt) do { __builtin_amdgcn_s_setprio(1); _Pragma("unroll") for (int m = 0; m < 4; ++m) _Pragma("unroll") for (int n = 0; n < 2; ++n) _Pragma("unroll") for (int k = 0; k < 2; ++k) \
;         acc[ai][bj][m][n] = __builtin_amdgcn_mfma_f32_16x16x32_bf16(Bt[n][k], At[m][k], acc[ai][bj][m][n], 0, 0, 0); __builtin_amdgcn_s_setprio(0); } while (0)
; #define PG8_WAIT_V(n) asm volatile("s_waitcnt vmcnt(" #n ")" ::: "memory")
; #define PG8_WAIT_L(n) asm volatile("s_waitcnt lgkmcnt(" #n ")" ::: "memory")
; #define PG8_BAR __builtin_amdgcn_s_barrier()
; #define PG8_SCHED __builtin_amdgcn_sched_barrier(0)
; template <class Desc, class Epi, bool ALIGN_EPI>
; __device__ __forceinline__ void gemm_phase(LAS unsigned char* lds, const Desc& D, const Epi& E, int G, int c) {
;     ...
;             PG8_WAIT_V(8); PG8_WAIT_L(0); PG8_BAR; PG8_MMA(0, 0, At, B0); PG8_MMA(0, 1, At, B1); PG8_BAR; PG8_SCHED;
;             PG8_LDA(At, 0, 1); PG8_STAGE(PG8_SB(0, 0), b2, voffB); PG8_STAGE(PG8_SB(0, 1), b2 + hstepB, voffB); PG8_STAGE(PG8_SA(0, 0), a2, voffA);
;             PG8_WAIT_V(8); PG8_WAIT_L(0); PG8_BAR; PG8_MMA(1, 0, At, B0); PG8_MMA(1, 1, At, B1); PG8_BAR; PG8_SCHED;
;             PG8_LDB(B0, 1, 0); PG8_LDB(B1, 1, 1); PG8_SCHED; PG8_LDA(At, 1, 0); PG8_STAGE(PG8_SA(0, 1), a2 + hstepA, voffA);
;             PG8_WAIT_V(8); PG8_WAIT_L(0); PG8_BAR; PG8_MMA(0, 0, At, B0); PG8_MMA(0, 1, At, B1); PG8_BAR; PG8_SCHED;
	v_mfma_f32_16x16x32_bf16 v[64:67], v[140:143], v[178:181], v[64:67]
	v_mfma_f32_16x16x32_bf16 v[64:67], v[144:147], v[182:185], v[64:67]
	v_mfma_f32_16x16x32_bf16 v[52:55], v[148:151], v[178:181], v[52:55]
	v_mfma_f32_16x16x32_bf16 v[52:55], v[152:155], v[182:185], v[52:55]
	v_mfma_f32_16x16x32_bf16 v[60:63], v[156:159], v[178:181], v[60:63]
	v_mfma_f32_16x16x32_bf16 v[60:63], v[166:169], v[182:185], v[60:63]
	v_mfma_f32_16x16x32_bf16 v[56:59], v[170:173], v[178:181], v[56:59]
	v_mfma_f32_16x16x32_bf16 v[56:59], v[174:177], v[182:185], v[56:59]
	v_mfma_f32_16x16x32_bf16 v[44:47], v[170:173], v[186:189], v[44:47]
	v_mfma_f32_16x16x32_bf16 v[44:47], v[174:177], v[190:193], v[44:47]
	v_mfma_f32_16x16x32_bf16 v[48:51], v[156:159], v[186:189], v[48:51]
	v_mfma_f32_16x16x32_bf16 v[48:51], v[166:169], v[190:193], v[48:51]
	v_mfma_f32_16x16x32_bf16 v[20:23], v[148:151], v[186:189], v[20:23]
	v_mfma_f32_16x16x32_bf16 v[20:23], v[152:155], v[190:193], v[20:23]
	v_mfma_f32_16x16x32_bf16 v[32:35], v[140:143], v[186:189], v[32:35]
	v_mfma_f32_16x16x32_bf16 v[32:35], v[144:147], v[190:193], v[32:35]
	v_mfma_f32_16x16x32_bf16 v[16:19], v[140:143], v[194:197], v[16:19]
	v_mfma_f32_16x16x32_bf16 v[16:19], v[144:147], v[198:201], v[16:19]
	v_mfma_f32_16x16x32_bf16 v[12:15], v[148:151], v[194:197], v[12:15]
	v_mfma_f32_16x16x32_bf16 v[12:15], v[152:155], v[198:201], v[12:15]
	v_mfma_f32_16x16x32_bf16 v[40:43], v[156:159], v[194:197], v[40:43]
	v_mfma_f32_16x16x32_bf16 v[40:43], v[166:169], v[198:201], v[40:43]
	v_mfma_f32_16x16x32_bf16 v[36:39], v[170:173], v[194:197], v[36:39]
	v_mfma_f32_16x16x32_bf16 v[36:39], v[174:177], v[198:201], v[36:39]
	v_mfma_f32_16x16x32_bf16 v[24:27], v[170:173], v[202:205], v[24:27]
	v_mfma_f32_16x16x32_bf16 v[24:27], v[174:177], v[206:209], v[24:27]
	v_mfma_f32_16x16x32_bf16 v[28:31], v[156:159], v[202:205], v[28:31]
	v_mfma_f32_16x16x32_bf16 v[28:31], v[166:169], v[206:209], v[28:31]
	v_mfma_f32_16x16x32_bf16 v[4:7], v[148:151], v[202:205], v[4:7]
	v_mfma_f32_16x16x32_bf16 v[4:7], v[152:155], v[206:209], v[4:7]
	v_mfma_f32_16x16x32_bf16 v[8:11], v[140:143], v[202:205], v[8:11]
	v_mfma_f32_16x16x32_bf16 v[8:11], v[144:147], v[206:209], v[8:11]
	s_barrier
	ds_read_b128 v[140:143], v163 offset:32768
	s_nop 0
	ds_read_b128 v[144:147], v163 offset:33792
	s_nop 0
	ds_read_b128 v[148:151], v163 offset:34816
	s_nop 0
	ds_read_b128 v[152:155], v163 offset:35840
	s_nop 0
	ds_read_b128 v[156:159], v163 offset:49152
	s_nop 0
	ds_read_b128 v[166:169], v163 offset:50176
	s_nop 0
	ds_read_b128 v[170:173], v163 offset:51200
	s_nop 0
	ds_read_b128 v[174:177], v163 offset:52224
	s_add_u32 s46, s46, 0x100000
	s_addc_u32 s47, s47, 0
	s_mov_b32 m0, s58
	ds_read_b128 v[178:181], v162 offset:32768
	s_nop 0
	ds_read_b128 v[182:185], v162 offset:33792
	s_nop 0
	ds_read_b128 v[186:189], v162 offset:34816
	s_nop 0
	ds_read_b128 v[190:193], v162 offset:35840
	s_nop 0
	ds_read_b128 v[194:197], v162 offset:36864
	s_nop 0
	ds_read_b128 v[198:201], v162 offset:37888
	s_nop 0
	ds_read_b128 v[202:205], v162 offset:38912
	s_nop 0
	ds_read_b128 v[206:209], v162 offset:39936
	global_load_lds_dwordx4 v132, s[46:47]
	s_mov_b32 m0, s59
	s_nop 0
	global_load_lds_dwordx4 v136, s[46:47]
	s_waitcnt vmcnt(8)
	s_waitcnt lgkmcnt(0)
	s_barrier
	v_mfma_f32_16x16x32_bf16 v[128:131], v[140:143], v[178:181], v[128:131]
	v_mfma_f32_16x16x32_bf16 v[128:131], v[144:147], v[182:185], v[128:131]
	v_mfma_f32_16x16x32_bf16 v[124:127], v[148:151], v[178:181], v[124:127]
	v_mfma_f32_16x16x32_bf16 v[124:127], v[152:155], v[182:185], v[124:127]
	v_mfma_f32_16x16x32_bf16 v[96:99], v[156:159], v[178:181], v[96:99]
	v_mfma_f32_16x16x32_bf16 v[96:99], v[166:169], v[182:185], v[96:99]
	v_mfma_f32_16x16x32_bf16 v[92:95], v[170:173], v[178:181], v[92:95]
	v_mfma_f32_16x16x32_bf16 v[92:95], v[174:177], v[182:185], v[92:95]
	v_mfma_f32_16x16x32_bf16 v[84:87], v[170:173], v[186:189], v[84:87]
	v_mfma_f32_16x16x32_bf16 v[84:87], v[174:177], v[190:193], v[84:87]
	v_mfma_f32_16x16x32_bf16 v[88:91], v[156:159], v[186:189], v[88:91]
	v_mfma_f32_16x16x32_bf16 v[88:91], v[166:169], v[190:193], v[88:91]
	v_mfma_f32_16x16x32_bf16 v[116:119], v[148:151], v[186:189], v[116:119]
	v_mfma_f32_16x16x32_bf16 v[116:119], v[152:155], v[190:193], v[116:119]
	v_mfma_f32_16x16x32_bf16 v[120:123], v[140:143], v[186:189], v[120:123]
	v_mfma_f32_16x16x32_bf16 v[120:123], v[144:147], v[190:193], v[120:123]
	v_mfma_f32_16x16x32_bf16 v[112:115], v[140:143], v[194:197], v[112:115]
	v_mfma_f32_16x16x32_bf16 v[112:115], v[144:147], v[198:201], v[112:115]
	v_mfma_f32_16x16x32_bf16 v[108:111], v[148:151], v[194:197], v[108:111]
	v_mfma_f32_16x16x32_bf16 v[108:111], v[152:155], v[198:201], v[108:111]
	v_mfma_f32_16x16x32_bf16 v[80:83], v[156:159], v[194:197], v[80:83]
	v_mfma_f32_16x16x32_bf16 v[80:83], v[166:169], v[198:201], v[80:83]
	v_mfma_f32_16x16x32_bf16 v[76:79], v[170:173], v[194:197], v[76:79]
	v_mfma_f32_16x16x32_bf16 v[76:79], v[174:177], v[198:201], v[76:79]
	v_mfma_f32_16x16x32_bf16 v[68:71], v[170:173], v[202:205], v[68:71]
	v_mfma_f32_16x16x32_bf16 v[68:71], v[174:177], v[206:209], v[68:71]
	v_mfma_f32_16x16x32_bf16 v[72:75], v[156:159], v[202:205], v[72:75]
	v_mfma_f32_16x16x32_bf16 v[72:75], v[166:169], v[206:209], v[72:75]
	v_mfma_f32_16x16x32_bf16 v[100:103], v[148:151], v[202:205], v[100:103]
	v_mfma_f32_16x16x32_bf16 v[100:103], v[152:155], v[206:209], v[100:103]
	v_mfma_f32_16x16x32_bf16 v[104:107], v[140:143], v[202:205], v[104:107]
	v_mfma_f32_16x16x32_bf16 v[104:107], v[144:147], v[206:209], v[104:107]
	s_barrier
; #define PG8_STAGE(bufoff, gbase, voff) do { _Pragma("unroll") for (int _i = 0; _i < 2; ++_i) \
;         __builtin_amdgcn_global_load_lds((const unsigned*)((const char*)(gbase) + (voff)[_i]), (LAS unsigned*)(lds + (bufoff) + ldsw + _i * 8192), 16, 0, 0); } while (0)
; #define PG8_LDA(dst, b, h) do { _Pragma("unroll") for (int m = 0; m < 4; ++m) _Pragma("unroll") for (int k = 0; k < 2; ++k) dst[m][k] = *(const LAS bf16x8*)(pA + PG8_SA(b, h) + m * 2048 + k * 1024); } while (0)
; #define PG8_MMA(ai, bj, At, Bt) do { __builtin_amdgcn_s_setprio(1); _Pragma("unroll") for (int m = 0; m < 4; ++m) _Pragma("unroll") for (int n = 0; n < 2; ++n) _Pragma("unroll") for (int k = 0; k < 2; ++k) \
;         acc[ai][bj][m][n] = __builtin_amdgcn_mfma_f32_16x16x32_bf16(Bt[n][k], At[m][k], acc[ai][bj][m][n], 0, 0, 0); __builtin_amdgcn_s_setprio(0); } while (0)
; #define PG8_WAIT_V(n) asm volatile("s_waitcnt vmcnt(" #n ")" ::: "memory")
; #define PG8_WAIT_L(n) asm volatile("s_waitcnt lgkmcnt(" #n ")" ::: "memory")
; #define PG8_BAR __builtin_amdgcn_s_barrier()
; #define PG8_SCHED __builtin_amdgcn_sched_barrier(0)
; template <class Desc, class Epi, bool ALIGN_EPI>
; __device__ __forceinline__ void gemm_phase(LAS unsigned char* lds, const Desc& D, const Epi& E, int G, int c) {
;     ...
;             PG8_LDA(At, 1, 1); PG8_STAGE(PG8_SB(1, 0), b3, voffB); PG8_STAGE(PG8_SB(1, 1), b3 + hstepB, voffB); PG8_STAGE(PG8_SA(1, 0), a3, voffA);
;             PG8_WAIT_V(8); PG8_WAIT_L(0); PG8_BAR; PG8_MMA(1, 0, At, B0); PG8_MMA(1, 1, At, B1); PG8_BAR; PG8_SCHED;
;         }
	s_mov_b32 m0, s61
	s_add_u32 s74, s34, 0x80
	s_addc_u32 s75, s35, 0
	s_add_u32 s34, s34, 0x100080
	s_addc_u32 s35, s35, 0
	ds_read_b128 v[178:181], v162 offset:49152
	s_nop 0
	ds_read_b128 v[182:185], v162 offset:50176
	s_nop 0
	ds_read_b128 v[186:189], v162 offset:51200
	s_nop 0
	ds_read_b128 v[190:193], v162 offset:52224
	s_nop 0
	ds_read_b128 v[194:197], v162 offset:53248
	s_nop 0
	ds_read_b128 v[198:201], v162 offset:54272
	s_nop 0
	ds_read_b128 v[202:205], v162 offset:55296
	s_nop 0
	ds_read_b128 v[206:209], v162 offset:56320
	global_load_lds_dwordx4 v134, s[74:75]
	s_mov_b32 m0, s62
	s_nop 0
	global_load_lds_dwordx4 v138, s[74:75]
	s_mov_b32 m0, s65
	s_nop 0
	global_load_lds_dwordx4 v134, s[34:35]
	s_mov_b32 m0, s67
	s_nop 0
	global_load_lds_dwordx4 v138, s[34:35]
	s_sub_u32 s74, s46, 0xfff80
	s_subb_u32 s75, s47, 0
	s_mov_b32 m0, s63
	s_nop 0
	global_load_lds_dwordx4 v132, s[74:75]
	s_mov_b32 m0, s64
	s_nop 0
	global_load_lds_dwordx4 v136, s[74:75]
	s_waitcnt vmcnt(8)
	s_waitcnt lgkmcnt(0)
	s_barrier
	v_mfma_f32_16x16x32_bf16 v[64:67], v[140:143], v[178:181], v[64:67]
	v_mfma_f32_16x16x32_bf16 v[64:67], v[144:147], v[182:185], v[64:67]
	v_mfma_f32_16x16x32_bf16 v[52:55], v[148:151], v[178:181], v[52:55]
	v_mfma_f32_16x16x32_bf16 v[52:55], v[152:155], v[182:185], v[52:55]
	v_mfma_f32_16x16x32_bf16 v[60:63], v[156:159], v[178:181], v[60:63]
	v_mfma_f32_16x16x32_bf16 v[60:63], v[166:169], v[182:185], v[60:63]
	v_mfma_f32_16x16x32_bf16 v[56:59], v[170:173], v[178:181], v[56:59]
	v_mfma_f32_16x16x32_bf16 v[56:59], v[174:177], v[182:185], v[56:59]
	v_mfma_f32_16x16x32_bf16 v[44:47], v[170:173], v[186:189], v[44:47]
	v_mfma_f32_16x16x32_bf16 v[44:47], v[174:177], v[190:193], v[44:47]
	v_mfma_f32_16x16x32_bf16 v[48:51], v[156:159], v[186:189], v[48:51]
	v_mfma_f32_16x16x32_bf16 v[48:51], v[166:169], v[190:193], v[48:51]
	v_mfma_f32_16x16x32_bf16 v[20:23], v[148:151], v[186:189], v[20:23]
	v_mfma_f32_16x16x32_bf16 v[20:23], v[152:155], v[190:193], v[20:23]
	v_mfma_f32_16x16x32_bf16 v[32:35], v[140:143], v[186:189], v[32:35]
	v_mfma_f32_16x16x32_bf16 v[32:35], v[144:147], v[190:193], v[32:35]
	v_mfma_f32_16x16x32_bf16 v[16:19], v[140:143], v[194:197], v[16:19]
	v_mfma_f32_16x16x32_bf16 v[16:19], v[144:147], v[198:201], v[16:19]
	v_mfma_f32_16x16x32_bf16 v[12:15], v[148:151], v[194:197], v[12:15]
	v_mfma_f32_16x16x32_bf16 v[12:15], v[152:155], v[198:201], v[12:15]
	v_mfma_f32_16x16x32_bf16 v[40:43], v[156:159], v[194:197], v[40:43]
	v_mfma_f32_16x16x32_bf16 v[40:43], v[166:169], v[198:201], v[40:43]
	v_mfma_f32_16x16x32_bf16 v[36:39], v[170:173], v[194:197], v[36:39]
	v_mfma_f32_16x16x32_bf16 v[36:39], v[174:177], v[198:201], v[36:39]
	v_mfma_f32_16x16x32_bf16 v[24:27], v[170:173], v[202:205], v[24:27]
	v_mfma_f32_16x16x32_bf16 v[24:27], v[174:177], v[206:209], v[24:27]
	v_mfma_f32_16x16x32_bf16 v[28:31], v[156:159], v[202:205], v[28:31]
	v_mfma_f32_16x16x32_bf16 v[28:31], v[166:169], v[206:209], v[28:31]
	v_mfma_f32_16x16x32_bf16 v[4:7], v[148:151], v[202:205], v[4:7]
	v_mfma_f32_16x16x32_bf16 v[4:7], v[152:155], v[206:209], v[4:7]
	v_mfma_f32_16x16x32_bf16 v[8:11], v[140:143], v[202:205], v[8:11]
	v_mfma_f32_16x16x32_bf16 v[8:11], v[144:147], v[206:209], v[8:11]
	s_barrier
	s_cmp_ge_u32 s30, s2
	s_cbranch_scc1 .LBB0_1591

;     __device__ __forceinline__ int nt(const Unit& u) const { return (u.pn >> 1) < 2 ? 22 : 20; }
; #define PG8_STAGE(bufoff, gbase, voff) do { _Pragma("unroll") for (int _i = 0; _i < 2; ++_i) \
;         __builtin_amdgcn_global_load_lds((const unsigned*)((const char*)(gbase) + (voff)[_i]), (LAS unsigned*)(lds + (bufoff) + ldsw + _i * 8192), 16, 0, 0); } while (0)
; #define PG8_LDA(dst, b, h) do { _Pragma("unroll") for (int m = 0; m < 4; ++m) _Pragma("unroll") for (int k = 0; k < 2; ++k) dst[m][k] = *(const LAS bf16x8*)(pA + PG8_SA(b, h) + m * 2048 + k * 1024); } while (0)
; #define PG8_LDB(dst, b, h) do { _Pragma("unroll") for (int n = 0; n < 2; ++n) _Pragma("unroll") for (int k = 0; k < 2; ++k) dst[n][k] = *(const LAS bf16x8*)(pB + (PG8_SB(b, h) - 4 * HTB) + n * 2048 + k * 1024); } while (0)
; #define PG8_MMA(ai, bj, At, Bt) do { __builtin_amdgcn_s_setprio(1); _Pragma("unroll") for (int m = 0; m < 4; ++m) _Pragma("unroll") for (int n = 0; n < 2; ++n) _Pragma("unroll") for (int k = 0; k < 2; ++k) \
;         acc[ai][bj][m][n] = __builtin_amdgcn_mfma_f32_16x16x32_bf16(Bt[n][k], At[m][k], acc[ai][bj][m][n], 0, 0, 0); __builtin_amdgcn_s_setprio(0); } while (0)
; #define PG8_WAIT_V(n) asm volatile("s_waitcnt vmcnt(" #n ")" ::: "memory")
; #define PG8_BAR __builtin_amdgcn_s_barrier()
; template <class Desc, class Epi, bool ALIGN_EPI>
; __device__ __forceinline__ void gemm_phase(LAS unsigned char* lds, const Desc& D, const Epi& E, int G, int c) {
;     ...
;         for (int t = 0; t < nt; t += 2) {
;             const bool last = (t == nt - 2);
;             if (last && has_next) PG8_AWAIT(nxt);
;             const char* a1 = cA + (size_t)(t + 1) * kstep;
;             const char* a2 = last ? nA : cA + (size_t)(t + 2) * kstep; const char* b2 = last ? nB : cB + (size_t)(t + 2) * kstep;
;             const char* a3 = a2 + kstep; const char* b3 = b2 + kstep;
;             PG8_LDB(B0, 0, 0); PG8_LDB(B1, 0, 1); PG8_SCHED; PG8_LDA(At, 0, 0); PG8_STAGE(PG8_SA(1, 1), a1 + hstepA, voffA);
;             PG8_WAIT_V(8); PG8_WAIT_L(0); PG8_BAR; PG8_MMA(0, 0, At, B0); PG8_MMA(0, 1, At, B1); PG8_BAR; PG8_SCHED;
;             PG8_LDA(At, 0, 1); PG8_STAGE(PG8_SB(0, 0), b2, voffB); PG8_STAGE(PG8_SB(0, 1), b2 + hstepB, voffB); PG8_STAGE(PG8_SA(0, 0), a2, voffA);
;             PG8_WAIT_V(8); PG8_WAIT_L(0); PG8_BAR; PG8_MMA(1, 0, At, B0); PG8_MMA(1, 1, At, B1); PG8_BAR; PG8_SCHED;
.LBB0_1765:
	s_or_b32 s14, s39, 1
	s_lshl_b64 s[40:41], s[14:15], 7
	s_add_i32 s14, s39, 2
	s_lshl_b64 s[42:43], s[14:15], 7
	s_add_u32 s39, s12, s42
	s_waitcnt lgkmcnt(0)
	ds_read_b128 v[132:135], v248
	s_nop 0
	ds_read_b128 v[136:139], v248 offset:1024
	s_nop 0
	ds_read_b128 v[140:143], v248 offset:2048
	s_nop 0
	ds_read_b128 v[144:147], v248 offset:3072
	s_nop 0
	ds_read_b128 v[148:151], v248 offset:16384
	s_nop 0
	ds_read_b128 v[152:155], v248 offset:17408
	s_nop 0
	ds_read_b128 v[156:159], v248 offset:18432
	s_nop 0
	ds_read_b128 v[160:163], v248 offset:19456
	s_addc_u32 s78, s13, s43
	s_and_b64 s[30:31], s[20:21], exec
	s_cselect_b32 s31, s49, s78
	s_cselect_b32 s30, s48, s39
	s_add_u32 s39, s16, s42
	s_addc_u32 s42, s17, s43
	s_and_b64 s[20:21], s[20:21], exec
	s_cselect_b32 s21, s51, s42
	s_cselect_b32 s20, s50, s39
	s_add_u32 s39, s12, s40
	s_addc_u32 s41, s13, s41
	s_add_u32 s40, s39, 0x2b0000
	s_addc_u32 s41, s41, 0
	v_lshl_add_u64 v[196:197], s[40:41], 0, v[200:201]
	s_add_i32 m0, s56, 0xc000
	ds_read_b128 v[164:167], v247
	s_nop 0
	ds_read_b128 v[168:171], v247 offset:1024
	s_nop 0
	ds_read_b128 v[172:175], v247 offset:2048
	s_nop 0
	ds_read_b128 v[176:179], v247 offset:3072
	s_nop 0
	ds_read_b128 v[180:183], v247 offset:4096
	s_nop 0
	ds_read_b128 v[184:187], v247 offset:5120
	s_nop 0
	ds_read_b128 v[188:191], v247 offset:6144
	s_nop 0
	ds_read_b128 v[192:195], v247 offset:7168
	global_load_lds_dwordx4 v[196:197], off
	v_lshl_add_u64 v[196:197], s[40:41], 0, v[204:205]
	s_add_i32 m0, s56, 0xe000
	s_nop 0
	global_load_lds_dwordx4 v[196:197], off
	s_waitcnt vmcnt(8)
	s_waitcnt lgkmcnt(0)
	s_barrier
	v_mfma_f32_16x16x32_bf16 v[128:131], v[132:135], v[164:167], v[128:131]
	v_mfma_f32_16x16x32_bf16 v[128:131], v[136:139], v[168:171], v[128:131]
	v_mfma_f32_16x16x32_bf16 v[124:127], v[140:143], v[164:167], v[124:127]
	v_mfma_f32_16x16x32_bf16 v[124:127], v[144:147], v[168:171], v[124:127]
	v_mfma_f32_16x16x32_bf16 v[96:99], v[148:151], v[164:167], v[96:99]
	v_mfma_f32_16x16x32_bf16 v[96:99], v[152:155], v[168:171], v[96:99]
	v_mfma_f32_16x16x32_bf16 v[92:95], v[156:159], v[164:167], v[92:95]
	v_mfma_f32_16x16x32_bf16 v[92:95], v[160:163], v[168:171], v[92:95]
	v_mfma_f32_16x16x32_bf16 v[80:83], v[156:159], v[172:175], v[80:83]
	v_mfma_f32_16x16x32_bf16 v[80:83], v[160:163], v[176:179], v[80:83]
	v_mfma_f32_16x16x32_bf16 v[88:91], v[148:151], v[172:175], v[88:91]
	v_mfma_f32_16x16x32_bf16 v[88:91], v[152:155], v[176:179], v[88:91]
	v_mfma_f32_16x16x32_bf16 v[116:119], v[140:143], v[172:175], v[116:119]
	v_mfma_f32_16x16x32_bf16 v[116:119], v[144:147], v[176:179], v[116:119]
	v_mfma_f32_16x16x32_bf16 v[120:123], v[132:135], v[172:175], v[120:123]
	v_mfma_f32_16x16x32_bf16 v[120:123], v[136:139], v[176:179], v[120:123]
	v_mfma_f32_16x16x32_bf16 v[112:115], v[132:135], v[180:183], v[112:115]
	v_mfma_f32_16x16x32_bf16 v[112:115], v[136:139], v[184:187], v[112:115]
	v_mfma_f32_16x16x32_bf16 v[108:111], v[140:143], v[180:183], v[108:111]
	v_mfma_f32_16x16x32_bf16 v[108:111], v[144:147], v[184:187], v[108:111]
	v_mfma_f32_16x16x32_bf16 v[64:67], v[148:151], v[180:183], v[64:67]
	v_mfma_f32_16x16x32_bf16 v[64:67], v[152:155], v[184:187], v[64:67]
	v_mfma_f32_16x16x32_bf16 v[52:55], v[156:159], v[180:183], v[52:55]
	v_mfma_f32_16x16x32_bf16 v[52:55], v[160:163], v[184:187], v[52:55]
	v_mfma_f32_16x16x32_bf16 v[20:23], v[156:159], v[188:191], v[20:23]
	v_mfma_f32_16x16x32_bf16 v[20:23], v[160:163], v[192:195], v[20:23]
	v_mfma_f32_16x16x32_bf16 v[32:35], v[148:151], v[188:191], v[32:35]
	v_mfma_f32_16x16x32_bf16 v[32:35], v[152:155], v[192:195], v[32:35]
	v_mfma_f32_16x16x32_bf16 v[100:103], v[140:143], v[188:191], v[100:103]
	v_mfma_f32_16x16x32_bf16 v[100:103], v[144:147], v[192:195], v[100:103]
	v_mfma_f32_16x16x32_bf16 v[104:107], v[132:135], v[188:191], v[104:107]
	v_mfma_f32_16x16x32_bf16 v[104:107], v[136:139], v[192:195], v[104:107]
	s_barrier
	s_mov_b32 m0, s57
	v_lshl_add_u64 v[196:197], s[20:21], 0, v[202:203]
	s_add_u32 s40, s20, 0x2b0000
	ds_read_b128 v[164:167], v247 offset:16384
	s_nop 0
	ds_read_b128 v[168:171], v247 offset:17408
	s_nop 0
	ds_read_b128 v[172:175], v247 offset:18432
	s_nop 0
	ds_read_b128 v[176:179], v247 offset:19456
	s_nop 0
	ds_read_b128 v[180:183], v247 offset:20480
	s_nop 0
	ds_read_b128 v[184:187], v247 offset:21504
	s_nop 0
	ds_read_b128 v[188:191], v247 offset:22528
	s_nop 0
	ds_read_b128 v[192:195], v247 offset:23552
	global_load_lds_dwordx4 v[196:197], off
	v_lshl_add_u64 v[198:199], s[20:21], 0, v[206:207]
	s_mov_b32 m0, s58
	s_addc_u32 s41, s21, 0
	global_load_lds_dwordx4 v[198:199], off
	v_lshl_add_u64 v[208:209], s[40:41], 0, v[202:203]
	s_mov_b32 m0, s59
	v_lshl_add_u64 v[210:211], s[30:31], 0, v[204:205]
	global_load_lds_dwordx4 v[208:209], off
	v_lshl_add_u64 v[208:209], s[40:41], 0, v[206:207]
	s_mov_b32 m0, s60
	s_nop 0
	global_load_lds_dwordx4 v[208:209], off
	v_lshl_add_u64 v[208:209], s[30:31], 0, v[200:201]
	s_mov_b32 m0, s56
	s_nop 0
	global_load_lds_dwordx4 v[208:209], off
	s_mov_b32 m0, s61
	s_nop 0
	global_load_lds_dwordx4 v[210:211], off
	s_waitcnt vmcnt(8)
	s_waitcnt lgkmcnt(0)
	s_barrier
; #define PG8_STAGE(bufoff, gbase, voff) do { _Pragma("unroll") for (int _i = 0; _i < 2; ++_i) \
;         __builtin_amdgcn_global_load_lds((const unsigned*)((const char*)(gbase) + (voff)[_i]), (LAS unsigned*)(lds + (bufoff) + ldsw + _i * 8192), 16, 0, 0); } while (0)
; #define PG8_LDA(dst, b, h) do { _Pragma("unroll") for (int m = 0; m < 4; ++m) _Pragma("unroll") for (int k = 0; k < 2; ++k) dst[m][k] = *(const LAS bf16x8*)(pA + PG8_SA(b, h) + m * 2048 + k * 1024); } while (0)
; #define PG8_LDB(dst, b, h) do { _Pragma("unroll") for (int n = 0; n < 2; ++n) _Pragma("unroll") for (int k = 0; k < 2; ++k) dst[n][k] = *(const LAS bf16x8*)(pB + (PG8_SB(b, h) - 4 * HTB) + n * 2048 + k * 1024); } while (0)
; #define PG8_MMA(ai, bj, At, Bt) do { __builtin_amdgcn_s_setprio(1); _Pragma("unroll") for (int m = 0; m < 4; ++m) _Pragma("unroll") for (int n = 0; n < 2; ++n) _Pragma("unroll") for (int k = 0; k < 2; ++k) \
;         acc[ai][bj][m][n] = __builtin_amdgcn_mfma_f32_16x16x32_bf16(Bt[n][k], At[m][k], acc[ai][bj][m][n], 0, 0, 0); __builtin_amdgcn_s_setprio(0); } while (0)
; #define PG8_WAIT_V(n) asm volatile("s_waitcnt vmcnt(" #n ")" ::: "memory")
; #define PG8_WAIT_L(n) asm volatile("s_waitcnt lgkmcnt(" #n ")" ::: "memory")
; #define PG8_BAR __builtin_amdgcn_s_barrier()
; #define PG8_SCHED __builtin_amdgcn_sched_barrier(0)
; template <class Desc, class Epi, bool ALIGN_EPI>
; __device__ __forceinline__ void gemm_phase(LAS unsigned char* lds, const Desc& D, const Epi& E, int G, int c) {
;     ...
;             PG8_WAIT_V(8); PG8_WAIT_L(0); PG8_BAR; PG8_MMA(1, 0, At, B0); PG8_MMA(1, 1, At, B1); PG8_BAR; PG8_SCHED;
;             PG8_LDB(B0, 1, 0); PG8_LDB(B1, 1, 1); PG8_SCHED; PG8_LDA(At, 1, 0); PG8_STAGE(PG8_SA(0, 1), a2 + hstepA, voffA);
;             PG8_WAIT_V(8); PG8_WAIT_L(0); PG8_BAR; PG8_MMA(0, 0, At, B0); PG8_MMA(0, 1, At, B1); PG8_BAR; PG8_SCHED;
	v_mfma_f32_16x16x32_bf16 v[84:87], v[132:135], v[164:167], v[84:87]
	v_mfma_f32_16x16x32_bf16 v[84:87], v[136:139], v[168:171], v[84:87]
	v_mfma_f32_16x16x32_bf16 v[76:79], v[140:143], v[164:167], v[76:79]
	v_mfma_f32_16x16x32_bf16 v[76:79], v[144:147], v[168:171], v[76:79]
	v_mfma_f32_16x16x32_bf16 v[40:43], v[148:151], v[164:167], v[40:43]
	v_mfma_f32_16x16x32_bf16 v[40:43], v[152:155], v[168:171], v[40:43]
	v_mfma_f32_16x16x32_bf16 v[36:39], v[156:159], v[164:167], v[36:39]
	v_mfma_f32_16x16x32_bf16 v[36:39], v[160:163], v[168:171], v[36:39]
	v_mfma_f32_16x16x32_bf16 v[24:27], v[156:159], v[172:175], v[24:27]
	v_mfma_f32_16x16x32_bf16 v[24:27], v[160:163], v[176:179], v[24:27]
	v_mfma_f32_16x16x32_bf16 v[28:31], v[148:151], v[172:175], v[28:31]
	v_mfma_f32_16x16x32_bf16 v[28:31], v[152:155], v[176:179], v[28:31]
	v_mfma_f32_16x16x32_bf16 v[68:71], v[140:143], v[172:175], v[68:71]
	v_mfma_f32_16x16x32_bf16 v[68:71], v[144:147], v[176:179], v[68:71]
	v_mfma_f32_16x16x32_bf16 v[72:75], v[132:135], v[172:175], v[72:75]
	v_mfma_f32_16x16x32_bf16 v[72:75], v[136:139], v[176:179], v[72:75]
	v_mfma_f32_16x16x32_bf16 v[60:63], v[132:135], v[180:183], v[60:63]
	v_mfma_f32_16x16x32_bf16 v[60:63], v[136:139], v[184:187], v[60:63]
	v_mfma_f32_16x16x32_bf16 v[56:59], v[140:143], v[180:183], v[56:59]
	v_mfma_f32_16x16x32_bf16 v[56:59], v[144:147], v[184:187], v[56:59]
	v_mfma_f32_16x16x32_bf16 v[16:19], v[148:151], v[180:183], v[16:19]
	v_mfma_f32_16x16x32_bf16 v[16:19], v[152:155], v[184:187], v[16:19]
	v_mfma_f32_16x16x32_bf16 v[12:15], v[156:159], v[180:183], v[12:15]
	v_mfma_f32_16x16x32_bf16 v[12:15], v[160:163], v[184:187], v[12:15]
	v_mfma_f32_16x16x32_bf16 v[4:7], v[156:159], v[188:191], v[4:7]
	v_mfma_f32_16x16x32_bf16 v[4:7], v[160:163], v[192:195], v[4:7]
	v_mfma_f32_16x16x32_bf16 v[8:11], v[148:151], v[188:191], v[8:11]
	v_mfma_f32_16x16x32_bf16 v[8:11], v[152:155], v[192:195], v[8:11]
	v_mfma_f32_16x16x32_bf16 v[44:47], v[140:143], v[188:191], v[44:47]
	v_mfma_f32_16x16x32_bf16 v[44:47], v[144:147], v[192:195], v[44:47]
	v_mfma_f32_16x16x32_bf16 v[48:51], v[132:135], v[188:191], v[48:51]
	v_mfma_f32_16x16x32_bf16 v[48:51], v[136:139], v[192:195], v[48:51]
	s_barrier
	ds_read_b128 v[132:135], v248 offset:32768
	s_nop 0
	ds_read_b128 v[136:139], v248 offset:33792
	s_nop 0
	ds_read_b128 v[140:143], v248 offset:34816
	s_nop 0
	ds_read_b128 v[144:147], v248 offset:35840
	s_nop 0
	ds_read_b128 v[148:151], v248 offset:49152
	s_nop 0
	ds_read_b128 v[152:155], v248 offset:50176
	s_nop 0
	ds_read_b128 v[156:159], v248 offset:51200
	s_nop 0
	ds_read_b128 v[160:163], v248 offset:52224
	s_add_u32 s30, s30, 0x2b0000
	s_addc_u32 s31, s31, 0
	s_mov_b32 m0, s62
	v_lshl_add_u64 v[212:213], s[30:31], 0, v[200:201]
	ds_read_b128 v[164:167], v247 offset:32768
	s_nop 0
	ds_read_b128 v[168:171], v247 offset:33792
	s_nop 0
	ds_read_b128 v[172:175], v247 offset:34816
	s_nop 0
	ds_read_b128 v[176:179], v247 offset:35840
	s_nop 0
	ds_read_b128 v[180:183], v247 offset:36864
	s_nop 0
	ds_read_b128 v[184:187], v247 offset:37888
	s_nop 0
	ds_read_b128 v[188:191], v247 offset:38912
	s_nop 0
	ds_read_b128 v[192:195], v247 offset:39936
	global_load_lds_dwordx4 v[212:213], off
	v_lshl_add_u64 v[212:213], s[30:31], 0, v[204:205]
	s_mov_b32 m0, s63
	s_nop 0
	global_load_lds_dwordx4 v[212:213], off
	s_waitcnt vmcnt(8)
	s_waitcnt lgkmcnt(0)
	s_barrier
	v_mfma_f32_16x16x32_bf16 v[128:131], v[132:135], v[164:167], v[128:131]
	v_mfma_f32_16x16x32_bf16 v[128:131], v[136:139], v[168:171], v[128:131]
	v_mfma_f32_16x16x32_bf16 v[124:127], v[140:143], v[164:167], v[124:127]
	v_mfma_f32_16x16x32_bf16 v[124:127], v[144:147], v[168:171], v[124:127]
	v_mfma_f32_16x16x32_bf16 v[96:99], v[148:151], v[164:167], v[96:99]
	v_mfma_f32_16x16x32_bf16 v[96:99], v[152:155], v[168:171], v[96:99]
	v_mfma_f32_16x16x32_bf16 v[92:95], v[156:159], v[164:167], v[92:95]
	v_mfma_f32_16x16x32_bf16 v[92:95], v[160:163], v[168:171], v[92:95]
	v_mfma_f32_16x16x32_bf16 v[80:83], v[156:159], v[172:175], v[80:83]
	v_mfma_f32_16x16x32_bf16 v[80:83], v[160:163], v[176:179], v[80:83]
	v_mfma_f32_16x16x32_bf16 v[88:91], v[148:151], v[172:175], v[88:91]
	v_mfma_f32_16x16x32_bf16 v[88:91], v[152:155], v[176:179], v[88:91]
	v_mfma_f32_16x16x32_bf16 v[116:119], v[140:143], v[172:175], v[116:119]
	v_mfma_f32_16x16x32_bf16 v[116:119], v[144:147], v[176:179], v[116:119]
	v_mfma_f32_16x16x32_bf16 v[120:123], v[132:135], v[172:175], v[120:123]
	v_mfma_f32_16x16x32_bf16 v[120:123], v[136:139], v[176:179], v[120:123]
	v_mfma_f32_16x16x32_bf16 v[112:115], v[132:135], v[180:183], v[112:115]
	v_mfma_f32_16x16x32_bf16 v[112:115], v[136:139], v[184:187], v[112:115]
	v_mfma_f32_16x16x32_bf16 v[108:111], v[140:143], v[180:183], v[108:111]
	v_mfma_f32_16x16x32_bf16 v[108:111], v[144:147], v[184:187], v[108:111]
	v_mfma_f32_16x16x32_bf16 v[64:67], v[148:151], v[180:183], v[64:67]
	v_mfma_f32_16x16x32_bf16 v[64:67], v[152:155], v[184:187], v[64:67]
	v_mfma_f32_16x16x32_bf16 v[52:55], v[156:159], v[180:183], v[52:55]
	v_mfma_f32_16x16x32_bf16 v[52:55], v[160:163], v[184:187], v[52:55]
	v_mfma_f32_16x16x32_bf16 v[20:23], v[156:159], v[188:191], v[20:23]
	v_mfma_f32_16x16x32_bf16 v[20:23], v[160:163], v[192:195], v[20:23]
	v_mfma_f32_16x16x32_bf16 v[32:35], v[148:151], v[188:191], v[32:35]
	v_mfma_f32_16x16x32_bf16 v[32:35], v[152:155], v[192:195], v[32:35]
	v_mfma_f32_16x16x32_bf16 v[100:103], v[140:143], v[188:191], v[100:103]
	v_mfma_f32_16x16x32_bf16 v[100:103], v[144:147], v[192:195], v[100:103]
	v_mfma_f32_16x16x32_bf16 v[104:107], v[132:135], v[188:191], v[104:107]
	v_mfma_f32_16x16x32_bf16 v[104:107], v[136:139], v[192:195], v[104:107]
	s_barrier
; #define PG8_STAGE(bufoff, gbase, voff) do { _Pragma("unroll") for (int _i = 0; _i < 2; ++_i) \
;         __builtin_amdgcn_global_load_lds((const unsigned*)((const char*)(gbase) + (voff)[_i]), (LAS unsigned*)(lds + (bufoff) + ldsw + _i * 8192), 16, 0, 0); } while (0)
; #define PG8_LDA(dst, b, h) do { _Pragma("unroll") for (int m = 0; m < 4; ++m) _Pragma("unroll") for (int k = 0; k < 2; ++k) dst[m][k] = *(const LAS bf16x8*)(pA + PG8_SA(b, h) + m * 2048 + k * 1024); } while (0)
; #define PG8_MMA(ai, bj, At, Bt) do { __builtin_amdgcn_s_setprio(1); _Pragma("unroll") for (int m = 0; m < 4; ++m) _Pragma("unroll") for (int n = 0; n < 2; ++n) _Pragma("unroll") for (int k = 0; k < 2; ++k) \
;         acc[ai][bj][m][n] = __builtin_amdgcn_mfma_f32_16x16x32_bf16(Bt[n][k], At[m][k], acc[ai][bj][m][n], 0, 0, 0); __builtin_amdgcn_s_setprio(0); } while (0)
; #define PG8_WAIT_V(n) asm volatile("s_waitcnt vmcnt(" #n ")" ::: "memory")
; #define PG8_WAIT_L(n) asm volatile("s_waitcnt lgkmcnt(" #n ")" ::: "memory")
; #define PG8_BAR __builtin_amdgcn_s_barrier()
; #define PG8_SCHED __builtin_amdgcn_sched_barrier(0)
; template <class Desc, class Epi, bool ALIGN_EPI>
; __device__ __forceinline__ void gemm_phase(LAS unsigned char* lds, const Desc& D, const Epi& E, int G, int c) {
;     ...
;             PG8_LDA(At, 1, 1); PG8_STAGE(PG8_SB(1, 0), b3, voffB); PG8_STAGE(PG8_SB(1, 1), b3 + hstepB, voffB); PG8_STAGE(PG8_SA(1, 0), a3, voffA);
;             PG8_WAIT_V(8); PG8_WAIT_L(0); PG8_BAR; PG8_MMA(1, 0, At, B0); PG8_MMA(1, 1, At, B1); PG8_BAR; PG8_SCHED;
;         }
	s_mov_b32 m0, s64
	v_lshl_add_u64 v[196:197], v[196:197], 0, s[76:77]
	s_add_u32 s20, s20, 0x2b0080
	ds_read_b128 v[164:167], v247 offset:49152
	s_nop 0
	ds_read_b128 v[168:171], v247 offset:50176
	s_nop 0
	ds_read_b128 v[172:175], v247 offset:51200
	s_nop 0
	ds_read_b128 v[176:179], v247 offset:52224
	s_nop 0
	ds_read_b128 v[180:183], v247 offset:53248
	s_nop 0
	ds_read_b128 v[184:187], v247 offset:54272
	s_nop 0
	ds_read_b128 v[188:191], v247 offset:55296
	s_nop 0
	ds_read_b128 v[192:195], v247 offset:56320
	global_load_lds_dwordx4 v[196:197], off
	v_lshl_add_u64 v[196:197], v[198:199], 0, s[76:77]
	s_mov_b32 m0, s65
	s_addc_u32 s21, s21, 0
	global_load_lds_dwordx4 v[196:197], off
	v_lshl_add_u64 v[196:197], s[20:21], 0, v[202:203]
	s_mov_b32 m0, s69
	s_nop 0
	global_load_lds_dwordx4 v[196:197], off
	v_lshl_add_u64 v[196:197], s[20:21], 0, v[206:207]
	s_mov_b32 m0, s70
	s_nop 0
	global_load_lds_dwordx4 v[196:197], off
	v_lshl_add_u64 v[196:197], v[208:209], 0, s[76:77]
	s_mov_b32 m0, s66
	s_nop 0
	global_load_lds_dwordx4 v[196:197], off
	v_lshl_add_u64 v[196:197], v[210:211], 0, s[76:77]
	s_mov_b32 m0, s67
	s_nop 0
	global_load_lds_dwordx4 v[196:197], off
	s_waitcnt vmcnt(8)
	s_waitcnt lgkmcnt(0)
	s_barrier
	v_mfma_f32_16x16x32_bf16 v[84:87], v[132:135], v[164:167], v[84:87]
	v_mfma_f32_16x16x32_bf16 v[84:87], v[136:139], v[168:171], v[84:87]
	v_mfma_f32_16x16x32_bf16 v[76:79], v[140:143], v[164:167], v[76:79]
	v_mfma_f32_16x16x32_bf16 v[76:79], v[144:147], v[168:171], v[76:79]
	v_mfma_f32_16x16x32_bf16 v[40:43], v[148:151], v[164:167], v[40:43]
	v_mfma_f32_16x16x32_bf16 v[40:43], v[152:155], v[168:171], v[40:43]
	v_mfma_f32_16x16x32_bf16 v[36:39], v[156:159], v[164:167], v[36:39]
	v_mfma_f32_16x16x32_bf16 v[36:39], v[160:163], v[168:171], v[36:39]
	v_mfma_f32_16x16x32_bf16 v[24:27], v[156:159], v[172:175], v[24:27]
	v_mfma_f32_16x16x32_bf16 v[24:27], v[160:163], v[176:179], v[24:27]
	v_mfma_f32_16x16x32_bf16 v[28:31], v[148:151], v[172:175], v[28:31]
	v_mfma_f32_16x16x32_bf16 v[28:31], v[152:155], v[176:179], v[28:31]
	v_mfma_f32_16x16x32_bf16 v[68:71], v[140:143], v[172:175], v[68:71]
	v_mfma_f32_16x16x32_bf16 v[68:71], v[144:147], v[176:179], v[68:71]
	v_mfma_f32_16x16x32_bf16 v[72:75], v[132:135], v[172:175], v[72:75]
	v_mfma_f32_16x16x32_bf16 v[72:75], v[136:139], v[176:179], v[72:75]
	v_mfma_f32_16x16x32_bf16 v[60:63], v[132:135], v[180:183], v[60:63]
	v_mfma_f32_16x16x32_bf16 v[60:63], v[136:139], v[184:187], v[60:63]
	v_mfma_f32_16x16x32_bf16 v[56:59], v[140:143], v[180:183], v[56:59]
	v_mfma_f32_16x16x32_bf16 v[56:59], v[144:147], v[184:187], v[56:59]
	v_mfma_f32_16x16x32_bf16 v[16:19], v[148:151], v[180:183], v[16:19]
	v_mfma_f32_16x16x32_bf16 v[16:19], v[152:155], v[184:187], v[16:19]
	v_mfma_f32_16x16x32_bf16 v[12:15], v[156:159], v[180:183], v[12:15]
	v_mfma_f32_16x16x32_bf16 v[12:15], v[160:163], v[184:187], v[12:15]
	v_mfma_f32_16x16x32_bf16 v[4:7], v[156:159], v[188:191], v[4:7]
	v_mfma_f32_16x16x32_bf16 v[4:7], v[160:163], v[192:195], v[4:7]
	v_mfma_f32_16x16x32_bf16 v[8:11], v[148:151], v[188:191], v[8:11]
	v_mfma_f32_16x16x32_bf16 v[8:11], v[152:155], v[192:195], v[8:11]
	v_mfma_f32_16x16x32_bf16 v[44:47], v[140:143], v[188:191], v[44:47]
	v_mfma_f32_16x16x32_bf16 v[44:47], v[144:147], v[192:195], v[44:47]
	v_mfma_f32_16x16x32_bf16 v[48:51], v[132:135], v[188:191], v[48:51]
	v_mfma_f32_16x16x32_bf16 v[48:51], v[136:139], v[192:195], v[48:51]
	s_barrier
	s_cmp_ge_u32 s14, s24
	s_mov_b32 s39, s14
	s_cbranch_scc1 .LBB0_1776
